# v25 + K-loop SP1/SP3 LDS-DMA use scalar-base addressing (4 VALU 64-bit adds removed per iteration)
# speedup vs baseline: 1.0067x; 1.0015x over previous
; #define PG8_STAGE(bufoff, gbase, voff) do { _Pragma("unroll") for (int _i = 0; _i < 2; ++_i) \
;         __builtin_amdgcn_global_load_lds((const unsigned*)((const char*)(gbase) + (voff)[_i]), (PG8_LAS unsigned*)(lds + (bufoff) + ldsw + _i * 8192), 16, 0, 0); } while (0)
; #define PG8_LDA(dst, b, h) do { _Pragma("unroll") for (int m = 0; m < 4; ++m) _Pragma("unroll") for (int k = 0; k < 2; ++k) dst[m][k] = *(const PG8_LAS bf16x8*)(lds + PG8_SA(b, h) + aoff + m * 2048 + k * 1024); } while (0)
; #define PG8_LDB(dst, b, h) do { _Pragma("unroll") for (int n = 0; n < 2; ++n) _Pragma("unroll") for (int k = 0; k < 2; ++k) dst[n][k] = *(const PG8_LAS bf16x8*)(lds + PG8_SB(b, h) + boff + n * 2048 + k * 1024); } while (0)
; #define PG8_WAIT_V(n) asm volatile("s_waitcnt vmcnt(" #n ")" ::: "memory")
; #define PG8_WAIT_L(n) asm volatile("s_waitcnt lgkmcnt(" #n ")" ::: "memory")
; #define PG8_BAR __builtin_amdgcn_s_barrier()
; #define PG8_SCHED __builtin_amdgcn_sched_barrier(0)
; template <class Epi, class Sched, bool ALIGN_EPI = false, bool SP2 = false, bool F16 = false>
; __device__ __forceinline__ void gemm_phase(PG8_LAS unsigned char* lds, const Gemm g, const Sched& S, const Epi& E) {
;     ...
;             if constexpr (SP2) {
;             PG8_LDB(B0, 0, 0); PG8_LDB(B1, 0, 1); PG8_SCHED; PG8_LDA(At, 0, 0); PG8_STAGE(PG8_SA(1, 1), a1 + hstepA, voffA);
;             PG8_WAIT_V(8); PG8_WAIT_L(0); PG8_BAR; PG8_MMA(0, 0, At, B0); PG8_MMA(0, 1, At, B1); PG8_BAR; PG8_SCHED;
;             PG8_LDA(At, 0, 1); PG8_STAGE(PG8_SB(0, 0), b2, voffB); PG8_STAGE(PG8_SB(0, 1), b2 + hstepB, voffB); PG8_STAGE(PG8_SA(0, 0), a2, voffA);
;             PG8_WAIT_V(8); PG8_WAIT_L(0); PG8_BAR; PG8_MMA(1, 0, At, B0); PG8_MMA(1, 1, At, B1); PG8_BAR; PG8_SCHED;
;             PG8_LDB(B0, 1, 0); PG8_LDB(B1, 1, 1); PG8_SCHED; PG8_LDA(At, 1, 0); PG8_STAGE(PG8_SA(0, 1), a2 + hstepA, voffA);
;             PG8_WAIT_V(8); PG8_WAIT_L(0); PG8_BAR; PG8_MMA(0, 0, At, B0); PG8_MMA(0, 1, At, B1); PG8_BAR; PG8_SCHED;
;             PG8_LDA(At, 1, 1); PG8_STAGE(PG8_SB(1, 0), b3, voffB); PG8_STAGE(PG8_SB(1, 1), b3 + hstepB, voffB); PG8_STAGE(PG8_SA(1, 0), a3, voffA);
;             PG8_WAIT_V(8); PG8_WAIT_L(0); PG8_BAR; PG8_MMA(1, 0, At, B0); PG8_MMA(1, 1, At, B1); PG8_BAR; PG8_SCHED;
.Lpk_gu:
	s_add_i32 s82, s54, 2
	s_add_u32 s83, s52, 0x80
	s_addc_u32 s55, s53, 0
	s_add_i32 vcc_lo, 0, 0x10000
	s_cmp_eq_u32 s74, s54
	s_cselect_b32 s55, s39, s55
	s_cselect_b32 s54, s38, s83
	s_cselect_b32 s95, s47, s81
	s_cselect_b32 s94, s46, s80
	s_add_i32 s83, 0, 0x14000
	v_add_u32_e32 v156, vcc_lo, v165
	v_add_u32_e32 v164, s83, v165
	ds_read_b128 v[130:133], v156
	ds_read_b128 v[134:137], v156 offset:1024
	ds_read_b128 v[152:155], v156 offset:2048
	ds_read_b128 v[156:159], v156 offset:3072
	ds_read_b128 v[160:163], v164
	ds_read_b128 v[166:169], v164 offset:1024
	ds_read_b128 v[184:187], v164 offset:2048
	ds_read_b128 v[188:191], v164 offset:3072
	s_add_i32 m0, s22, 0xc000
	ds_read_b128 v[192:195], v183
	ds_read_b128 v[204:207], v183 offset:1024
	ds_read_b128 v[208:211], v183 offset:2048
	ds_read_b128 v[212:215], v183 offset:3072
	ds_read_b128 v[216:219], v183 offset:4096
	ds_read_b128 v[220:223], v183 offset:5120
	ds_read_b128 v[224:227], v183 offset:6144
	ds_read_b128 v[228:231], v183 offset:7168
	global_load_lds_dwordx4 v148, s[52:53]
	s_add_i32 m0, s22, 0xe000
	s_nop 0
	global_load_lds_dwordx4 v150, s[52:53]
	s_waitcnt vmcnt(8)
	s_waitcnt lgkmcnt(0)
	s_setprio 1
	s_barrier
	v_mfma_f32_16x16x32_f16 v[122:125], v[130:133], v[192:195], 0
	v_mfma_f32_16x16x32_f16 v[114:117], v[152:155], v[192:195], 0
	v_mfma_f32_16x16x32_f16 v[106:109], v[130:133], v[208:211], 0
	v_mfma_f32_16x16x32_f16 v[98:101], v[152:155], v[208:211], 0
	v_mfma_f32_16x16x32_f16 v[90:93], v[130:133], v[216:219], 0
	v_mfma_f32_16x16x32_f16 v[82:85], v[152:155], v[216:219], 0
	v_mfma_f32_16x16x32_f16 v[74:77], v[130:133], v[224:227], 0
	v_mfma_f32_16x16x32_f16 v[66:69], v[152:155], v[224:227], 0
	v_mfma_f32_16x16x32_f16 v[122:125], v[134:137], v[204:207], v[122:125]
	v_mfma_f32_16x16x32_f16 v[114:117], v[156:159], v[204:207], v[114:117]
	v_mfma_f32_16x16x32_f16 v[106:109], v[134:137], v[212:215], v[106:109]
	v_mfma_f32_16x16x32_f16 v[98:101], v[156:159], v[212:215], v[98:101]
	v_mfma_f32_16x16x32_f16 v[90:93], v[134:137], v[220:223], v[90:93]
	v_mfma_f32_16x16x32_f16 v[82:85], v[156:159], v[220:223], v[82:85]
	v_mfma_f32_16x16x32_f16 v[74:77], v[134:137], v[228:231], v[74:77]
	v_mfma_f32_16x16x32_f16 v[66:69], v[156:159], v[228:231], v[66:69]
	v_mfma_f32_16x16x32_f16 v[126:129], v[160:163], v[192:195], 0
	v_mfma_f32_16x16x32_f16 v[118:121], v[184:187], v[192:195], 0
	v_mfma_f32_16x16x32_f16 v[110:113], v[160:163], v[208:211], 0
	v_mfma_f32_16x16x32_f16 v[102:105], v[184:187], v[208:211], 0
	v_mfma_f32_16x16x32_f16 v[94:97], v[160:163], v[216:219], 0
	v_mfma_f32_16x16x32_f16 v[86:89], v[184:187], v[216:219], 0
	v_mfma_f32_16x16x32_f16 v[78:81], v[160:163], v[224:227], 0
	v_mfma_f32_16x16x32_f16 v[70:73], v[184:187], v[224:227], 0
	v_mfma_f32_16x16x32_f16 v[126:129], v[166:169], v[204:207], v[126:129]
	v_mfma_f32_16x16x32_f16 v[118:121], v[188:191], v[204:207], v[118:121]
	v_mfma_f32_16x16x32_f16 v[110:113], v[166:169], v[212:215], v[110:113]
	v_mfma_f32_16x16x32_f16 v[102:105], v[188:191], v[212:215], v[102:105]
	v_mfma_f32_16x16x32_f16 v[94:97], v[166:169], v[220:223], v[94:97]
	v_mfma_f32_16x16x32_f16 v[86:89], v[188:191], v[220:223], v[86:89]
	v_mfma_f32_16x16x32_f16 v[78:81], v[166:169], v[228:231], v[78:81]
	v_mfma_f32_16x16x32_f16 v[70:73], v[188:191], v[228:231], v[70:73]
	s_barrier
	s_setprio 0
	s_add_i32 vcc_lo, vcc_lo, s2
	v_lshl_add_u64 v[172:173], s[94:95], 0, v[142:143]
	s_mov_b32 m0, vcc_lo
	ds_read_b128 v[192:195], v183 offset:16384
	ds_read_b128 v[204:207], v183 offset:17408
	ds_read_b128 v[208:211], v183 offset:18432
	ds_read_b128 v[212:215], v183 offset:19456
	ds_read_b128 v[216:219], v183 offset:20480
	ds_read_b128 v[220:223], v183 offset:21504
	ds_read_b128 v[224:227], v183 offset:22528
	ds_read_b128 v[228:231], v183 offset:23552
	global_load_lds_dwordx4 v[172:173], off
	s_add_i32 m0, vcc_lo, 0x2000
	v_lshl_add_u64 v[176:177], s[94:95], 0, v[138:139]
	s_add_u32 s94, s94, s48
	s_addc_u32 s95, s95, 0
	s_add_i32 s83, s83, s2
	global_load_lds_dwordx4 v[176:177], off
	v_lshl_add_u64 v[196:197], s[94:95], 0, v[142:143]
	s_mov_b32 m0, s83
	v_lshl_add_u64 v[232:233], s[94:95], 0, v[138:139]
	global_load_lds_dwordx4 v[196:197], off
	s_add_i32 m0, s83, 0x2000
	v_lshl_add_u64 v[234:235], s[54:55], 0, v[144:145]
	global_load_lds_dwordx4 v[232:233], off
	s_mov_b32 m0, s22
	v_lshl_add_u64 v[236:237], s[54:55], 0, v[140:141]
	global_load_lds_dwordx4 v[234:235], off
	s_mov_b32 m0, s33
	s_nop 0
	global_load_lds_dwordx4 v[236:237], off
	s_waitcnt vmcnt(8)
	s_waitcnt lgkmcnt(0)
	s_setprio 1
	s_barrier
	v_mfma_f32_16x16x32_f16 v[58:61], v[130:133], v[192:195], 0
	v_mfma_f32_16x16x32_f16 v[50:53], v[152:155], v[192:195], 0
	v_mfma_f32_16x16x32_f16 v[42:45], v[130:133], v[208:211], 0
	v_mfma_f32_16x16x32_f16 v[34:37], v[152:155], v[208:211], 0
	v_mfma_f32_16x16x32_f16 v[26:29], v[130:133], v[216:219], 0
	v_mfma_f32_16x16x32_f16 v[18:21], v[152:155], v[216:219], 0
	v_mfma_f32_16x16x32_f16 v[10:13], v[130:133], v[224:227], 0
	v_mfma_f32_16x16x32_f16 v[6:9], v[152:155], v[224:227], 0
	v_mfma_f32_16x16x32_f16 v[58:61], v[134:137], v[204:207], v[58:61]
	v_mfma_f32_16x16x32_f16 v[50:53], v[156:159], v[204:207], v[50:53]
	v_mfma_f32_16x16x32_f16 v[42:45], v[134:137], v[212:215], v[42:45]
	v_mfma_f32_16x16x32_f16 v[34:37], v[156:159], v[212:215], v[34:37]
	v_mfma_f32_16x16x32_f16 v[26:29], v[134:137], v[220:223], v[26:29]
	v_mfma_f32_16x16x32_f16 v[18:21], v[156:159], v[220:223], v[18:21]
	v_mfma_f32_16x16x32_f16 v[10:13], v[134:137], v[228:231], v[10:13]
	v_mfma_f32_16x16x32_f16 v[6:9], v[156:159], v[228:231], v[6:9]
	v_mfma_f32_16x16x32_f16 v[62:65], v[160:163], v[192:195], 0
	v_mfma_f32_16x16x32_f16 v[54:57], v[184:187], v[192:195], 0
	v_mfma_f32_16x16x32_f16 v[46:49], v[160:163], v[208:211], 0
	v_mfma_f32_16x16x32_f16 v[38:41], v[184:187], v[208:211], 0
	v_mfma_f32_16x16x32_f16 v[30:33], v[160:163], v[216:219], 0
	v_mfma_f32_16x16x32_f16 v[22:25], v[184:187], v[216:219], 0
	v_mfma_f32_16x16x32_f16 v[14:17], v[160:163], v[224:227], 0
	v_mfma_f32_16x16x32_f16 v[2:5], v[184:187], v[224:227], 0
	v_mfma_f32_16x16x32_f16 v[62:65], v[166:169], v[204:207], v[62:65]
	v_mfma_f32_16x16x32_f16 v[54:57], v[188:191], v[204:207], v[54:57]
	v_mfma_f32_16x16x32_f16 v[46:49], v[166:169], v[212:215], v[46:49]
	v_mfma_f32_16x16x32_f16 v[38:41], v[188:191], v[212:215], v[38:41]
	v_mfma_f32_16x16x32_f16 v[30:33], v[166:169], v[220:223], v[30:33]
	v_mfma_f32_16x16x32_f16 v[22:25], v[188:191], v[220:223], v[22:25]
	v_mfma_f32_16x16x32_f16 v[14:17], v[166:169], v[228:231], v[14:17]
	v_mfma_f32_16x16x32_f16 v[2:5], v[188:191], v[228:231], v[2:5]
	s_barrier
; #define PG8_STAGE(bufoff, gbase, voff) do { _Pragma("unroll") for (int _i = 0; _i < 2; ++_i) \
;         __builtin_amdgcn_global_load_lds((const unsigned*)((const char*)(gbase) + (voff)[_i]), (PG8_LAS unsigned*)(lds + (bufoff) + ldsw + _i * 8192), 16, 0, 0); } while (0)
; #define PG8_LDA(dst, b, h) do { _Pragma("unroll") for (int m = 0; m < 4; ++m) _Pragma("unroll") for (int k = 0; k < 2; ++k) dst[m][k] = *(const PG8_LAS bf16x8*)(lds + PG8_SA(b, h) + aoff + m * 2048 + k * 1024); } while (0)
; #define PG8_LDB(dst, b, h) do { _Pragma("unroll") for (int n = 0; n < 2; ++n) _Pragma("unroll") for (int k = 0; k < 2; ++k) dst[n][k] = *(const PG8_LAS bf16x8*)(lds + PG8_SB(b, h) + boff + n * 2048 + k * 1024); } while (0)
; #define PG8_WAIT_V(n) asm volatile("s_waitcnt vmcnt(" #n ")" ::: "memory")
; #define PG8_WAIT_L(n) asm volatile("s_waitcnt lgkmcnt(" #n ")" ::: "memory")
; #define PG8_BAR __builtin_amdgcn_s_barrier()
; #define PG8_SCHED __builtin_amdgcn_sched_barrier(0)
; template <class Epi, class Sched, bool ALIGN_EPI = false, bool SP2 = false, bool F16 = false>
; __device__ __forceinline__ void gemm_phase(PG8_LAS unsigned char* lds, const Gemm g, const Sched& S, const Epi& E) {
;     ...
;             if constexpr (SP2) {
;             PG8_LDB(B0, 0, 0); PG8_LDB(B1, 0, 1); PG8_SCHED; PG8_LDA(At, 0, 0); PG8_STAGE(PG8_SA(1, 1), a1 + hstepA, voffA);
;             PG8_WAIT_V(8); PG8_WAIT_L(0); PG8_BAR; PG8_MMA(0, 0, At, B0); PG8_MMA(0, 1, At, B1); PG8_BAR; PG8_SCHED;
;             PG8_LDA(At, 0, 1); PG8_STAGE(PG8_SB(0, 0), b2, voffB); PG8_STAGE(PG8_SB(0, 1), b2 + hstepB, voffB); PG8_STAGE(PG8_SA(0, 0), a2, voffA);
;             PG8_WAIT_V(8); PG8_WAIT_L(0); PG8_BAR; PG8_MMA(1, 0, At, B0); PG8_MMA(1, 1, At, B1); PG8_BAR; PG8_SCHED;
;             PG8_LDB(B0, 1, 0); PG8_LDB(B1, 1, 1); PG8_SCHED; PG8_LDA(At, 1, 0); PG8_STAGE(PG8_SA(0, 1), a2 + hstepA, voffA);
;             PG8_WAIT_V(8); PG8_WAIT_L(0); PG8_BAR; PG8_MMA(0, 0, At, B0); PG8_MMA(0, 1, At, B1); PG8_BAR; PG8_SCHED;
;             PG8_LDA(At, 1, 1); PG8_STAGE(PG8_SB(1, 0), b3, voffB); PG8_STAGE(PG8_SB(1, 1), b3 + hstepB, voffB); PG8_STAGE(PG8_SA(1, 0), a3, voffA);
;             PG8_WAIT_V(8); PG8_WAIT_L(0); PG8_BAR; PG8_MMA(1, 0, At, B0); PG8_MMA(1, 1, At, B1); PG8_BAR; PG8_SCHED;
	s_setprio 0
	s_add_i32 s83, 0, 0x18000
	s_add_i32 s94, 0, 0x1c000
	v_add_u32_e32 v156, s83, v165
	v_add_u32_e32 v164, s94, v165
	ds_read_b128 v[130:133], v156
	ds_read_b128 v[134:137], v156 offset:1024
	ds_read_b128 v[152:155], v156 offset:2048
	ds_read_b128 v[156:159], v156 offset:3072
	ds_read_b128 v[160:163], v164
	ds_read_b128 v[166:169], v164 offset:1024
	ds_read_b128 v[184:187], v164 offset:2048
	ds_read_b128 v[188:191], v164 offset:3072
	s_add_u32 s54, s54, s8
	s_addc_u32 s55, s55, 0
	s_mov_b32 m0, s12
	ds_read_b128 v[192:195], v183 offset:32768
	ds_read_b128 v[204:207], v183 offset:33792
	ds_read_b128 v[208:211], v183 offset:34816
	ds_read_b128 v[212:215], v183 offset:35840
	ds_read_b128 v[216:219], v183 offset:36864
	ds_read_b128 v[220:223], v183 offset:37888
	ds_read_b128 v[224:227], v183 offset:38912
	ds_read_b128 v[228:231], v183 offset:39936
	global_load_lds_dwordx4 v144, s[54:55]
	s_mov_b32 m0, s13
	s_nop 0
	global_load_lds_dwordx4 v140, s[54:55]
	s_waitcnt vmcnt(8)
	s_waitcnt lgkmcnt(0)
	s_setprio 1
	s_barrier
	v_mfma_f32_16x16x32_f16 v[122:125], v[130:133], v[192:195], v[122:125]
	v_mfma_f32_16x16x32_f16 v[114:117], v[152:155], v[192:195], v[114:117]
	v_mfma_f32_16x16x32_f16 v[106:109], v[130:133], v[208:211], v[106:109]
	v_mfma_f32_16x16x32_f16 v[98:101], v[152:155], v[208:211], v[98:101]
	v_mfma_f32_16x16x32_f16 v[90:93], v[130:133], v[216:219], v[90:93]
	v_mfma_f32_16x16x32_f16 v[82:85], v[152:155], v[216:219], v[82:85]
	v_mfma_f32_16x16x32_f16 v[74:77], v[130:133], v[224:227], v[74:77]
	v_mfma_f32_16x16x32_f16 v[66:69], v[152:155], v[224:227], v[66:69]
	v_mfma_f32_16x16x32_f16 v[122:125], v[134:137], v[204:207], v[122:125]
	v_mfma_f32_16x16x32_f16 v[114:117], v[156:159], v[204:207], v[114:117]
	v_mfma_f32_16x16x32_f16 v[106:109], v[134:137], v[212:215], v[106:109]
	v_mfma_f32_16x16x32_f16 v[98:101], v[156:159], v[212:215], v[98:101]
	v_mfma_f32_16x16x32_f16 v[90:93], v[134:137], v[220:223], v[90:93]
	v_mfma_f32_16x16x32_f16 v[82:85], v[156:159], v[220:223], v[82:85]
	v_mfma_f32_16x16x32_f16 v[74:77], v[134:137], v[228:231], v[74:77]
	v_mfma_f32_16x16x32_f16 v[66:69], v[156:159], v[228:231], v[66:69]
	v_mfma_f32_16x16x32_f16 v[126:129], v[160:163], v[192:195], v[126:129]
	v_mfma_f32_16x16x32_f16 v[118:121], v[184:187], v[192:195], v[118:121]
	v_mfma_f32_16x16x32_f16 v[110:113], v[160:163], v[208:211], v[110:113]
	v_mfma_f32_16x16x32_f16 v[102:105], v[184:187], v[208:211], v[102:105]
	v_mfma_f32_16x16x32_f16 v[94:97], v[160:163], v[216:219], v[94:97]
	v_mfma_f32_16x16x32_f16 v[86:89], v[184:187], v[216:219], v[86:89]
	v_mfma_f32_16x16x32_f16 v[78:81], v[160:163], v[224:227], v[78:81]
	v_mfma_f32_16x16x32_f16 v[70:73], v[184:187], v[224:227], v[70:73]
	v_mfma_f32_16x16x32_f16 v[126:129], v[166:169], v[204:207], v[126:129]
	v_mfma_f32_16x16x32_f16 v[118:121], v[188:191], v[204:207], v[118:121]
	v_mfma_f32_16x16x32_f16 v[110:113], v[166:169], v[212:215], v[110:113]
	v_mfma_f32_16x16x32_f16 v[102:105], v[188:191], v[212:215], v[102:105]
	v_mfma_f32_16x16x32_f16 v[94:97], v[166:169], v[220:223], v[94:97]
	v_mfma_f32_16x16x32_f16 v[86:89], v[188:191], v[220:223], v[86:89]
	v_mfma_f32_16x16x32_f16 v[78:81], v[166:169], v[228:231], v[78:81]
	v_mfma_f32_16x16x32_f16 v[70:73], v[188:191], v[228:231], v[70:73]
	s_barrier
	s_setprio 0
	s_add_i32 s54, s83, s2
	v_lshl_add_u64 v[172:173], v[172:173], 0, s[92:93]
	s_mov_b32 m0, s54
	ds_read_b128 v[192:195], v183 offset:49152
	ds_read_b128 v[204:207], v183 offset:50176
	ds_read_b128 v[208:211], v183 offset:51200
	ds_read_b128 v[212:215], v183 offset:52224
	ds_read_b128 v[216:219], v183 offset:53248
	ds_read_b128 v[220:223], v183 offset:54272
	ds_read_b128 v[224:227], v183 offset:55296
	ds_read_b128 v[228:231], v183 offset:56320
	global_load_lds_dwordx4 v[172:173], off
	v_lshl_add_u64 v[172:173], v[176:177], 0, s[92:93]
	s_add_i32 m0, s54, 0x2000
	s_add_i32 s54, s94, s2
	global_load_lds_dwordx4 v[172:173], off
	v_lshl_add_u64 v[172:173], v[196:197], 0, s[92:93]
	s_mov_b32 m0, s54
	s_nop 0
	global_load_lds_dwordx4 v[172:173], off
	v_lshl_add_u64 v[172:173], v[232:233], 0, s[92:93]
	s_add_i32 m0, s54, 0x2000
	s_nop 0
	global_load_lds_dwordx4 v[172:173], off
	v_lshl_add_u64 v[172:173], v[234:235], 0, s[92:93]
	s_mov_b32 m0, s35
	s_nop 0
	global_load_lds_dwordx4 v[172:173], off
	v_lshl_add_u64 v[172:173], v[236:237], 0, s[92:93]
	s_mov_b32 m0, s59
	s_nop 0
	global_load_lds_dwordx4 v[172:173], off
	s_waitcnt vmcnt(8)
	s_waitcnt lgkmcnt(0)
	s_setprio 1
	s_barrier
	v_mfma_f32_16x16x32_f16 v[58:61], v[130:133], v[192:195], v[58:61]
	v_mfma_f32_16x16x32_f16 v[50:53], v[152:155], v[192:195], v[50:53]
	v_mfma_f32_16x16x32_f16 v[42:45], v[130:133], v[208:211], v[42:45]
	v_mfma_f32_16x16x32_f16 v[34:37], v[152:155], v[208:211], v[34:37]
	v_mfma_f32_16x16x32_f16 v[26:29], v[130:133], v[216:219], v[26:29]
	v_mfma_f32_16x16x32_f16 v[18:21], v[152:155], v[216:219], v[18:21]
	v_mfma_f32_16x16x32_f16 v[10:13], v[130:133], v[224:227], v[10:13]
	v_mfma_f32_16x16x32_f16 v[6:9], v[152:155], v[224:227], v[6:9]
	v_mfma_f32_16x16x32_f16 v[58:61], v[134:137], v[204:207], v[58:61]
	v_mfma_f32_16x16x32_f16 v[50:53], v[156:159], v[204:207], v[50:53]
	v_mfma_f32_16x16x32_f16 v[42:45], v[134:137], v[212:215], v[42:45]
	v_mfma_f32_16x16x32_f16 v[34:37], v[156:159], v[212:215], v[34:37]
	v_mfma_f32_16x16x32_f16 v[26:29], v[134:137], v[220:223], v[26:29]
	v_mfma_f32_16x16x32_f16 v[18:21], v[156:159], v[220:223], v[18:21]
	v_mfma_f32_16x16x32_f16 v[10:13], v[134:137], v[228:231], v[10:13]
	v_mfma_f32_16x16x32_f16 v[6:9], v[156:159], v[228:231], v[6:9]
	v_mfma_f32_16x16x32_f16 v[62:65], v[160:163], v[192:195], v[62:65]
	v_mfma_f32_16x16x32_f16 v[54:57], v[184:187], v[192:195], v[54:57]
	v_mfma_f32_16x16x32_f16 v[46:49], v[160:163], v[208:211], v[46:49]
	v_mfma_f32_16x16x32_f16 v[38:41], v[184:187], v[208:211], v[38:41]
	v_mfma_f32_16x16x32_f16 v[30:33], v[160:163], v[216:219], v[30:33]
	v_mfma_f32_16x16x32_f16 v[22:25], v[184:187], v[216:219], v[22:25]
	v_mfma_f32_16x16x32_f16 v[14:17], v[160:163], v[224:227], v[14:17]
	v_mfma_f32_16x16x32_f16 v[2:5], v[184:187], v[224:227], v[2:5]
	v_mfma_f32_16x16x32_f16 v[62:65], v[166:169], v[204:207], v[62:65]
	v_mfma_f32_16x16x32_f16 v[54:57], v[188:191], v[204:207], v[54:57]
	v_mfma_f32_16x16x32_f16 v[46:49], v[166:169], v[212:215], v[46:49]
	v_mfma_f32_16x16x32_f16 v[38:41], v[188:191], v[212:215], v[38:41]
	v_mfma_f32_16x16x32_f16 v[30:33], v[166:169], v[220:223], v[30:33]
	v_mfma_f32_16x16x32_f16 v[22:25], v[188:191], v[220:223], v[22:25]
	v_mfma_f32_16x16x32_f16 v[14:17], v[166:169], v[228:231], v[14:17]
	v_mfma_f32_16x16x32_f16 v[2:5], v[188:191], v[228:231], v[2:5]
	s_barrier
	s_setprio 0
	s_add_u32 s52, s52, 0x100
	s_addc_u32 s53, s53, 0
	s_add_u32 s80, s80, 0x100
	s_addc_u32 s81, s81, 0
	s_cmp_ge_u32 s82, s65
	s_mov_b32 s54, s82
	s_cbranch_scc1 .LBB0_311
; #define PG8_STAGE(bufoff, gbase, voff) do { _Pragma("unroll") for (int _i = 0; _i < 2; ++_i) \
;         __builtin_amdgcn_global_load_lds((const unsigned*)((const char*)(gbase) + (voff)[_i]), (PG8_LAS unsigned*)(lds + (bufoff) + ldsw + _i * 8192), 16, 0, 0); } while (0)
; #define PG8_LDA(dst, b, h) do { _Pragma("unroll") for (int m = 0; m < 4; ++m) _Pragma("unroll") for (int k = 0; k < 2; ++k) dst[m][k] = *(const PG8_LAS bf16x8*)(lds + PG8_SA(b, h) + aoff + m * 2048 + k * 1024); } while (0)
; #define PG8_LDB(dst, b, h) do { _Pragma("unroll") for (int n = 0; n < 2; ++n) _Pragma("unroll") for (int k = 0; k < 2; ++k) dst[n][k] = *(const PG8_LAS bf16x8*)(lds + PG8_SB(b, h) + boff + n * 2048 + k * 1024); } while (0)
; #define PG8_WAIT_V(n) asm volatile("s_waitcnt vmcnt(" #n ")" ::: "memory")
; #define PG8_WAIT_L(n) asm volatile("s_waitcnt lgkmcnt(" #n ")" ::: "memory")
; #define PG8_BAR __builtin_amdgcn_s_barrier()
; #define PG8_SCHED __builtin_amdgcn_sched_barrier(0)
; template <class Epi, class Sched, bool ALIGN_EPI = false, bool SP2 = false, bool F16 = false>
; __device__ __forceinline__ void gemm_phase(PG8_LAS unsigned char* lds, const Gemm g, const Sched& S, const Epi& E) {
;     ...
;             if constexpr (SP2) {
;             PG8_LDB(B0, 0, 0); PG8_LDB(B1, 0, 1); PG8_SCHED; PG8_LDA(At, 0, 0); PG8_STAGE(PG8_SA(1, 1), a1 + hstepA, voffA);
;             PG8_WAIT_V(8); PG8_WAIT_L(0); PG8_BAR; PG8_MMA(0, 0, At, B0); PG8_MMA(0, 1, At, B1); PG8_BAR; PG8_SCHED;
;             PG8_LDA(At, 0, 1); PG8_STAGE(PG8_SB(0, 0), b2, voffB); PG8_STAGE(PG8_SB(0, 1), b2 + hstepB, voffB); PG8_STAGE(PG8_SA(0, 0), a2, voffA);
;             PG8_WAIT_V(8); PG8_WAIT_L(0); PG8_BAR; PG8_MMA(1, 0, At, B0); PG8_MMA(1, 1, At, B1); PG8_BAR; PG8_SCHED;
;             PG8_LDB(B0, 1, 0); PG8_LDB(B1, 1, 1); PG8_SCHED; PG8_LDA(At, 1, 0); PG8_STAGE(PG8_SA(0, 1), a2 + hstepA, voffA);
;             PG8_WAIT_V(8); PG8_WAIT_L(0); PG8_BAR; PG8_MMA(0, 0, At, B0); PG8_MMA(0, 1, At, B1); PG8_BAR; PG8_SCHED;
;             PG8_LDA(At, 1, 1); PG8_STAGE(PG8_SB(1, 0), b3, voffB); PG8_STAGE(PG8_SB(1, 1), b3 + hstepB, voffB); PG8_STAGE(PG8_SA(1, 0), a3, voffA);
;             PG8_WAIT_V(8); PG8_WAIT_L(0); PG8_BAR; PG8_MMA(1, 0, At, B0); PG8_MMA(1, 1, At, B1); PG8_BAR; PG8_SCHED;
.LBB0_310:
	s_add_i32 s82, s54, 2
	s_add_u32 s83, s52, 0x80
	s_addc_u32 s55, s53, 0
	s_add_i32 vcc_lo, 0, 0x10000
	s_cmp_eq_u32 s74, s54
	s_cselect_b32 s55, s39, s55
	s_cselect_b32 s54, s38, s83
	s_cselect_b32 s95, s47, s81
	s_cselect_b32 s94, s46, s80
	s_add_i32 s83, 0, 0x14000
	v_add_u32_e32 v156, vcc_lo, v165
	v_add_u32_e32 v164, s83, v165
	ds_read_b128 v[130:133], v156
	ds_read_b128 v[134:137], v156 offset:1024
	ds_read_b128 v[152:155], v156 offset:2048
	ds_read_b128 v[156:159], v156 offset:3072
	ds_read_b128 v[160:163], v164
	ds_read_b128 v[166:169], v164 offset:1024
	ds_read_b128 v[184:187], v164 offset:2048
	ds_read_b128 v[188:191], v164 offset:3072
	s_add_i32 m0, s22, 0xc000
	ds_read_b128 v[192:195], v183
	ds_read_b128 v[204:207], v183 offset:1024
	ds_read_b128 v[208:211], v183 offset:2048
	ds_read_b128 v[212:215], v183 offset:3072
	ds_read_b128 v[216:219], v183 offset:4096
	ds_read_b128 v[220:223], v183 offset:5120
	ds_read_b128 v[224:227], v183 offset:6144
	ds_read_b128 v[228:231], v183 offset:7168
	global_load_lds_dwordx4 v148, s[52:53]
	s_add_i32 m0, s22, 0xe000
	s_nop 0
	global_load_lds_dwordx4 v150, s[52:53]
	s_waitcnt vmcnt(8)
	s_waitcnt lgkmcnt(0)
	s_setprio 1
	s_barrier
	v_mfma_f32_16x16x32_f16 v[122:125], v[130:133], v[192:195], v[122:125]
	v_mfma_f32_16x16x32_f16 v[114:117], v[152:155], v[192:195], v[114:117]
	v_mfma_f32_16x16x32_f16 v[106:109], v[130:133], v[208:211], v[106:109]
	v_mfma_f32_16x16x32_f16 v[98:101], v[152:155], v[208:211], v[98:101]
	v_mfma_f32_16x16x32_f16 v[90:93], v[130:133], v[216:219], v[90:93]
	v_mfma_f32_16x16x32_f16 v[82:85], v[152:155], v[216:219], v[82:85]
	v_mfma_f32_16x16x32_f16 v[74:77], v[130:133], v[224:227], v[74:77]
	v_mfma_f32_16x16x32_f16 v[66:69], v[152:155], v[224:227], v[66:69]
	v_mfma_f32_16x16x32_f16 v[122:125], v[134:137], v[204:207], v[122:125]
	v_mfma_f32_16x16x32_f16 v[114:117], v[156:159], v[204:207], v[114:117]
	v_mfma_f32_16x16x32_f16 v[106:109], v[134:137], v[212:215], v[106:109]
	v_mfma_f32_16x16x32_f16 v[98:101], v[156:159], v[212:215], v[98:101]
	v_mfma_f32_16x16x32_f16 v[90:93], v[134:137], v[220:223], v[90:93]
	v_mfma_f32_16x16x32_f16 v[82:85], v[156:159], v[220:223], v[82:85]
	v_mfma_f32_16x16x32_f16 v[74:77], v[134:137], v[228:231], v[74:77]
	v_mfma_f32_16x16x32_f16 v[66:69], v[156:159], v[228:231], v[66:69]
	v_mfma_f32_16x16x32_f16 v[126:129], v[160:163], v[192:195], v[126:129]
	v_mfma_f32_16x16x32_f16 v[118:121], v[184:187], v[192:195], v[118:121]
	v_mfma_f32_16x16x32_f16 v[110:113], v[160:163], v[208:211], v[110:113]
	v_mfma_f32_16x16x32_f16 v[102:105], v[184:187], v[208:211], v[102:105]
	v_mfma_f32_16x16x32_f16 v[94:97], v[160:163], v[216:219], v[94:97]
	v_mfma_f32_16x16x32_f16 v[86:89], v[184:187], v[216:219], v[86:89]
	v_mfma_f32_16x16x32_f16 v[78:81], v[160:163], v[224:227], v[78:81]
	v_mfma_f32_16x16x32_f16 v[70:73], v[184:187], v[224:227], v[70:73]
	v_mfma_f32_16x16x32_f16 v[126:129], v[166:169], v[204:207], v[126:129]
	v_mfma_f32_16x16x32_f16 v[118:121], v[188:191], v[204:207], v[118:121]
	v_mfma_f32_16x16x32_f16 v[110:113], v[166:169], v[212:215], v[110:113]
	v_mfma_f32_16x16x32_f16 v[102:105], v[188:191], v[212:215], v[102:105]
	v_mfma_f32_16x16x32_f16 v[94:97], v[166:169], v[220:223], v[94:97]
	v_mfma_f32_16x16x32_f16 v[86:89], v[188:191], v[220:223], v[86:89]
	v_mfma_f32_16x16x32_f16 v[78:81], v[166:169], v[228:231], v[78:81]
	v_mfma_f32_16x16x32_f16 v[70:73], v[188:191], v[228:231], v[70:73]
	s_barrier
	s_setprio 0
	s_add_i32 vcc_lo, vcc_lo, s2
	v_lshl_add_u64 v[172:173], s[94:95], 0, v[142:143]
	s_mov_b32 m0, vcc_lo
	ds_read_b128 v[192:195], v183 offset:16384
	ds_read_b128 v[204:207], v183 offset:17408
	ds_read_b128 v[208:211], v183 offset:18432
	ds_read_b128 v[212:215], v183 offset:19456
	ds_read_b128 v[216:219], v183 offset:20480
	ds_read_b128 v[220:223], v183 offset:21504
	ds_read_b128 v[224:227], v183 offset:22528
	ds_read_b128 v[228:231], v183 offset:23552
	global_load_lds_dwordx4 v[172:173], off
	s_add_i32 m0, vcc_lo, 0x2000
	v_lshl_add_u64 v[176:177], s[94:95], 0, v[138:139]
	s_add_u32 s94, s94, s48
	s_addc_u32 s95, s95, 0
	s_add_i32 s83, s83, s2
	global_load_lds_dwordx4 v[176:177], off
	v_lshl_add_u64 v[196:197], s[94:95], 0, v[142:143]
	s_mov_b32 m0, s83
	v_lshl_add_u64 v[232:233], s[94:95], 0, v[138:139]
	global_load_lds_dwordx4 v[196:197], off
	s_add_i32 m0, s83, 0x2000
	v_lshl_add_u64 v[234:235], s[54:55], 0, v[144:145]
	global_load_lds_dwordx4 v[232:233], off
	s_mov_b32 m0, s22
	v_lshl_add_u64 v[236:237], s[54:55], 0, v[140:141]
	global_load_lds_dwordx4 v[234:235], off
	s_mov_b32 m0, s33
	s_nop 0
	global_load_lds_dwordx4 v[236:237], off
	s_waitcnt vmcnt(8)
	s_waitcnt lgkmcnt(0)
	s_setprio 1
	s_barrier
; #define PG8_STAGE(bufoff, gbase, voff) do { _Pragma("unroll") for (int _i = 0; _i < 2; ++_i) \
;         __builtin_amdgcn_global_load_lds((const unsigned*)((const char*)(gbase) + (voff)[_i]), (PG8_LAS unsigned*)(lds + (bufoff) + ldsw + _i * 8192), 16, 0, 0); } while (0)
; #define PG8_LDA(dst, b, h) do { _Pragma("unroll") for (int m = 0; m < 4; ++m) _Pragma("unroll") for (int k = 0; k < 2; ++k) dst[m][k] = *(const PG8_LAS bf16x8*)(lds + PG8_SA(b, h) + aoff + m * 2048 + k * 1024); } while (0)
; #define PG8_LDB(dst, b, h) do { _Pragma("unroll") for (int n = 0; n < 2; ++n) _Pragma("unroll") for (int k = 0; k < 2; ++k) dst[n][k] = *(const PG8_LAS bf16x8*)(lds + PG8_SB(b, h) + boff + n * 2048 + k * 1024); } while (0)
; #define PG8_WAIT_V(n) asm volatile("s_waitcnt vmcnt(" #n ")" ::: "memory")
; #define PG8_WAIT_L(n) asm volatile("s_waitcnt lgkmcnt(" #n ")" ::: "memory")
; #define PG8_BAR __builtin_amdgcn_s_barrier()
; #define PG8_SCHED __builtin_amdgcn_sched_barrier(0)
; template <class Epi, class Sched, bool ALIGN_EPI = false, bool SP2 = false, bool F16 = false>
; __device__ __forceinline__ void gemm_phase(PG8_LAS unsigned char* lds, const Gemm g, const Sched& S, const Epi& E) {
;     ...
;             PG8_WAIT_V(8); PG8_WAIT_L(0); PG8_BAR; PG8_MMA(1, 0, At, B0); PG8_MMA(1, 1, At, B1); PG8_BAR; PG8_SCHED;
;             PG8_LDB(B0, 1, 0); PG8_LDB(B1, 1, 1); PG8_SCHED; PG8_LDA(At, 1, 0); PG8_STAGE(PG8_SA(0, 1), a2 + hstepA, voffA);
;             PG8_WAIT_V(8); PG8_WAIT_L(0); PG8_BAR; PG8_MMA(0, 0, At, B0); PG8_MMA(0, 1, At, B1); PG8_BAR; PG8_SCHED;
	v_mfma_f32_16x16x32_f16 v[58:61], v[130:133], v[192:195], v[58:61]
	v_mfma_f32_16x16x32_f16 v[50:53], v[152:155], v[192:195], v[50:53]
	v_mfma_f32_16x16x32_f16 v[42:45], v[130:133], v[208:211], v[42:45]
	v_mfma_f32_16x16x32_f16 v[34:37], v[152:155], v[208:211], v[34:37]
	v_mfma_f32_16x16x32_f16 v[26:29], v[130:133], v[216:219], v[26:29]
	v_mfma_f32_16x16x32_f16 v[18:21], v[152:155], v[216:219], v[18:21]
	v_mfma_f32_16x16x32_f16 v[10:13], v[130:133], v[224:227], v[10:13]
	v_mfma_f32_16x16x32_f16 v[6:9], v[152:155], v[224:227], v[6:9]
	v_mfma_f32_16x16x32_f16 v[58:61], v[134:137], v[204:207], v[58:61]
	v_mfma_f32_16x16x32_f16 v[50:53], v[156:159], v[204:207], v[50:53]
	v_mfma_f32_16x16x32_f16 v[42:45], v[134:137], v[212:215], v[42:45]
	v_mfma_f32_16x16x32_f16 v[34:37], v[156:159], v[212:215], v[34:37]
	v_mfma_f32_16x16x32_f16 v[26:29], v[134:137], v[220:223], v[26:29]
	v_mfma_f32_16x16x32_f16 v[18:21], v[156:159], v[220:223], v[18:21]
	v_mfma_f32_16x16x32_f16 v[10:13], v[134:137], v[228:231], v[10:13]
	v_mfma_f32_16x16x32_f16 v[6:9], v[156:159], v[228:231], v[6:9]
	v_mfma_f32_16x16x32_f16 v[62:65], v[160:163], v[192:195], v[62:65]
	v_mfma_f32_16x16x32_f16 v[54:57], v[184:187], v[192:195], v[54:57]
	v_mfma_f32_16x16x32_f16 v[46:49], v[160:163], v[208:211], v[46:49]
	v_mfma_f32_16x16x32_f16 v[38:41], v[184:187], v[208:211], v[38:41]
	v_mfma_f32_16x16x32_f16 v[30:33], v[160:163], v[216:219], v[30:33]
	v_mfma_f32_16x16x32_f16 v[22:25], v[184:187], v[216:219], v[22:25]
	v_mfma_f32_16x16x32_f16 v[14:17], v[160:163], v[224:227], v[14:17]
	v_mfma_f32_16x16x32_f16 v[2:5], v[184:187], v[224:227], v[2:5]
	v_mfma_f32_16x16x32_f16 v[62:65], v[166:169], v[204:207], v[62:65]
	v_mfma_f32_16x16x32_f16 v[54:57], v[188:191], v[204:207], v[54:57]
	v_mfma_f32_16x16x32_f16 v[46:49], v[166:169], v[212:215], v[46:49]
	v_mfma_f32_16x16x32_f16 v[38:41], v[188:191], v[212:215], v[38:41]
	v_mfma_f32_16x16x32_f16 v[30:33], v[166:169], v[220:223], v[30:33]
	v_mfma_f32_16x16x32_f16 v[22:25], v[188:191], v[220:223], v[22:25]
	v_mfma_f32_16x16x32_f16 v[14:17], v[166:169], v[228:231], v[14:17]
	v_mfma_f32_16x16x32_f16 v[2:5], v[188:191], v[228:231], v[2:5]
	s_barrier
	s_setprio 0
	s_add_i32 s83, 0, 0x18000
	s_add_i32 s94, 0, 0x1c000
	v_add_u32_e32 v156, s83, v165
	v_add_u32_e32 v164, s94, v165
	ds_read_b128 v[130:133], v156
	ds_read_b128 v[134:137], v156 offset:1024
	ds_read_b128 v[152:155], v156 offset:2048
	ds_read_b128 v[156:159], v156 offset:3072
	ds_read_b128 v[160:163], v164
	ds_read_b128 v[166:169], v164 offset:1024
	ds_read_b128 v[184:187], v164 offset:2048
	ds_read_b128 v[188:191], v164 offset:3072
	s_add_u32 s54, s54, s8
	s_addc_u32 s55, s55, 0
	s_mov_b32 m0, s12
	ds_read_b128 v[192:195], v183 offset:32768
	ds_read_b128 v[204:207], v183 offset:33792
	ds_read_b128 v[208:211], v183 offset:34816
	ds_read_b128 v[212:215], v183 offset:35840
	ds_read_b128 v[216:219], v183 offset:36864
	ds_read_b128 v[220:223], v183 offset:37888
	ds_read_b128 v[224:227], v183 offset:38912
	ds_read_b128 v[228:231], v183 offset:39936
	global_load_lds_dwordx4 v144, s[54:55]
	s_mov_b32 m0, s13
	s_nop 0
	global_load_lds_dwordx4 v140, s[54:55]
	s_waitcnt vmcnt(8)
	s_waitcnt lgkmcnt(0)
	s_setprio 1
	s_barrier
	v_mfma_f32_16x16x32_f16 v[122:125], v[130:133], v[192:195], v[122:125]
	v_mfma_f32_16x16x32_f16 v[114:117], v[152:155], v[192:195], v[114:117]
	v_mfma_f32_16x16x32_f16 v[106:109], v[130:133], v[208:211], v[106:109]
	v_mfma_f32_16x16x32_f16 v[98:101], v[152:155], v[208:211], v[98:101]
	v_mfma_f32_16x16x32_f16 v[90:93], v[130:133], v[216:219], v[90:93]
	v_mfma_f32_16x16x32_f16 v[82:85], v[152:155], v[216:219], v[82:85]
	v_mfma_f32_16x16x32_f16 v[74:77], v[130:133], v[224:227], v[74:77]
	v_mfma_f32_16x16x32_f16 v[66:69], v[152:155], v[224:227], v[66:69]
	v_mfma_f32_16x16x32_f16 v[122:125], v[134:137], v[204:207], v[122:125]
	v_mfma_f32_16x16x32_f16 v[114:117], v[156:159], v[204:207], v[114:117]
	v_mfma_f32_16x16x32_f16 v[106:109], v[134:137], v[212:215], v[106:109]
	v_mfma_f32_16x16x32_f16 v[98:101], v[156:159], v[212:215], v[98:101]
	v_mfma_f32_16x16x32_f16 v[90:93], v[134:137], v[220:223], v[90:93]
	v_mfma_f32_16x16x32_f16 v[82:85], v[156:159], v[220:223], v[82:85]
	v_mfma_f32_16x16x32_f16 v[74:77], v[134:137], v[228:231], v[74:77]
	v_mfma_f32_16x16x32_f16 v[66:69], v[156:159], v[228:231], v[66:69]
	v_mfma_f32_16x16x32_f16 v[126:129], v[160:163], v[192:195], v[126:129]
	v_mfma_f32_16x16x32_f16 v[118:121], v[184:187], v[192:195], v[118:121]
	v_mfma_f32_16x16x32_f16 v[110:113], v[160:163], v[208:211], v[110:113]
	v_mfma_f32_16x16x32_f16 v[102:105], v[184:187], v[208:211], v[102:105]
	v_mfma_f32_16x16x32_f16 v[94:97], v[160:163], v[216:219], v[94:97]
	v_mfma_f32_16x16x32_f16 v[86:89], v[184:187], v[216:219], v[86:89]
	v_mfma_f32_16x16x32_f16 v[78:81], v[160:163], v[224:227], v[78:81]
	v_mfma_f32_16x16x32_f16 v[70:73], v[184:187], v[224:227], v[70:73]
	v_mfma_f32_16x16x32_f16 v[126:129], v[166:169], v[204:207], v[126:129]
	v_mfma_f32_16x16x32_f16 v[118:121], v[188:191], v[204:207], v[118:121]
	v_mfma_f32_16x16x32_f16 v[110:113], v[166:169], v[212:215], v[110:113]
	v_mfma_f32_16x16x32_f16 v[102:105], v[188:191], v[212:215], v[102:105]
	v_mfma_f32_16x16x32_f16 v[94:97], v[166:169], v[220:223], v[94:97]
	v_mfma_f32_16x16x32_f16 v[86:89], v[188:191], v[220:223], v[86:89]
	v_mfma_f32_16x16x32_f16 v[78:81], v[166:169], v[228:231], v[78:81]
	v_mfma_f32_16x16x32_f16 v[70:73], v[188:191], v[228:231], v[70:73]
	s_barrier
; #define PG8_STAGE(bufoff, gbase, voff) do { _Pragma("unroll") for (int _i = 0; _i < 2; ++_i) \
;         __builtin_amdgcn_global_load_lds((const unsigned*)((const char*)(gbase) + (voff)[_i]), (PG8_LAS unsigned*)(lds + (bufoff) + ldsw + _i * 8192), 16, 0, 0); } while (0)
; #define PG8_LDA(dst, b, h) do { _Pragma("unroll") for (int m = 0; m < 4; ++m) _Pragma("unroll") for (int k = 0; k < 2; ++k) dst[m][k] = *(const PG8_LAS bf16x8*)(lds + PG8_SA(b, h) + aoff + m * 2048 + k * 1024); } while (0)
; #define PG8_WAIT_V(n) asm volatile("s_waitcnt vmcnt(" #n ")" ::: "memory")
; #define PG8_WAIT_L(n) asm volatile("s_waitcnt lgkmcnt(" #n ")" ::: "memory")
; #define PG8_BAR __builtin_amdgcn_s_barrier()
; #define PG8_SCHED __builtin_amdgcn_sched_barrier(0)
; template <class Epi, class Sched, bool ALIGN_EPI = false, bool SP2 = false, bool F16 = false>
; __device__ __forceinline__ void gemm_phase(PG8_LAS unsigned char* lds, const Gemm g, const Sched& S, const Epi& E) {
;     ...
;         for (int t = 0; t < nt; t += 2) {
;     ...
;             PG8_LDA(At, 1, 1); PG8_STAGE(PG8_SB(1, 0), b3, voffB); PG8_STAGE(PG8_SB(1, 1), b3 + hstepB, voffB); PG8_STAGE(PG8_SA(1, 0), a3, voffA);
;             PG8_WAIT_V(8); PG8_WAIT_L(0); PG8_BAR; PG8_MMA(1, 0, At, B0); PG8_MMA(1, 1, At, B1); PG8_BAR; PG8_SCHED;
	s_setprio 0
	s_add_i32 s54, s83, s2
	v_lshl_add_u64 v[172:173], v[172:173], 0, s[92:93]
	s_mov_b32 m0, s54
	ds_read_b128 v[192:195], v183 offset:49152
	ds_read_b128 v[204:207], v183 offset:50176
	ds_read_b128 v[208:211], v183 offset:51200
	ds_read_b128 v[212:215], v183 offset:52224
	ds_read_b128 v[216:219], v183 offset:53248
	ds_read_b128 v[220:223], v183 offset:54272
	ds_read_b128 v[224:227], v183 offset:55296
	ds_read_b128 v[228:231], v183 offset:56320
	global_load_lds_dwordx4 v[172:173], off
	v_lshl_add_u64 v[172:173], v[176:177], 0, s[92:93]
	s_add_i32 m0, s54, 0x2000
	s_add_i32 s54, s94, s2
	global_load_lds_dwordx4 v[172:173], off
	v_lshl_add_u64 v[172:173], v[196:197], 0, s[92:93]
	s_mov_b32 m0, s54
	s_nop 0
	global_load_lds_dwordx4 v[172:173], off
	v_lshl_add_u64 v[172:173], v[232:233], 0, s[92:93]
	s_add_i32 m0, s54, 0x2000
	s_nop 0
	global_load_lds_dwordx4 v[172:173], off
	v_lshl_add_u64 v[172:173], v[234:235], 0, s[92:93]
	s_mov_b32 m0, s35
	s_nop 0
	global_load_lds_dwordx4 v[172:173], off
	v_lshl_add_u64 v[172:173], v[236:237], 0, s[92:93]
	s_mov_b32 m0, s59
	s_nop 0
	global_load_lds_dwordx4 v[172:173], off
	s_waitcnt vmcnt(8)
	s_waitcnt lgkmcnt(0)
	s_setprio 1
	s_barrier
	v_mfma_f32_16x16x32_f16 v[58:61], v[130:133], v[192:195], v[58:61]
	v_mfma_f32_16x16x32_f16 v[50:53], v[152:155], v[192:195], v[50:53]
	v_mfma_f32_16x16x32_f16 v[42:45], v[130:133], v[208:211], v[42:45]
	v_mfma_f32_16x16x32_f16 v[34:37], v[152:155], v[208:211], v[34:37]
	v_mfma_f32_16x16x32_f16 v[26:29], v[130:133], v[216:219], v[26:29]
	v_mfma_f32_16x16x32_f16 v[18:21], v[152:155], v[216:219], v[18:21]
	v_mfma_f32_16x16x32_f16 v[10:13], v[130:133], v[224:227], v[10:13]
	v_mfma_f32_16x16x32_f16 v[6:9], v[152:155], v[224:227], v[6:9]
	v_mfma_f32_16x16x32_f16 v[58:61], v[134:137], v[204:207], v[58:61]
	v_mfma_f32_16x16x32_f16 v[50:53], v[156:159], v[204:207], v[50:53]
	v_mfma_f32_16x16x32_f16 v[42:45], v[134:137], v[212:215], v[42:45]
	v_mfma_f32_16x16x32_f16 v[34:37], v[156:159], v[212:215], v[34:37]
	v_mfma_f32_16x16x32_f16 v[26:29], v[134:137], v[220:223], v[26:29]
	v_mfma_f32_16x16x32_f16 v[18:21], v[156:159], v[220:223], v[18:21]
	v_mfma_f32_16x16x32_f16 v[10:13], v[134:137], v[228:231], v[10:13]
	v_mfma_f32_16x16x32_f16 v[6:9], v[156:159], v[228:231], v[6:9]
	v_mfma_f32_16x16x32_f16 v[62:65], v[160:163], v[192:195], v[62:65]
	v_mfma_f32_16x16x32_f16 v[54:57], v[184:187], v[192:195], v[54:57]
	v_mfma_f32_16x16x32_f16 v[46:49], v[160:163], v[208:211], v[46:49]
	v_mfma_f32_16x16x32_f16 v[38:41], v[184:187], v[208:211], v[38:41]
	v_mfma_f32_16x16x32_f16 v[30:33], v[160:163], v[216:219], v[30:33]
	v_mfma_f32_16x16x32_f16 v[22:25], v[184:187], v[216:219], v[22:25]
	v_mfma_f32_16x16x32_f16 v[14:17], v[160:163], v[224:227], v[14:17]
	v_mfma_f32_16x16x32_f16 v[2:5], v[184:187], v[224:227], v[2:5]
	v_mfma_f32_16x16x32_f16 v[62:65], v[166:169], v[204:207], v[62:65]
	v_mfma_f32_16x16x32_f16 v[54:57], v[188:191], v[204:207], v[54:57]
	v_mfma_f32_16x16x32_f16 v[46:49], v[166:169], v[212:215], v[46:49]
	v_mfma_f32_16x16x32_f16 v[38:41], v[188:191], v[212:215], v[38:41]
	v_mfma_f32_16x16x32_f16 v[30:33], v[166:169], v[220:223], v[30:33]
	v_mfma_f32_16x16x32_f16 v[22:25], v[188:191], v[220:223], v[22:25]
	v_mfma_f32_16x16x32_f16 v[14:17], v[166:169], v[228:231], v[14:17]
	v_mfma_f32_16x16x32_f16 v[2:5], v[188:191], v[228:231], v[2:5]
	s_barrier
	s_setprio 0
	s_add_u32 s52, s52, 0x100
	s_addc_u32 s53, s53, 0
	s_add_u32 s80, s80, 0x100
	s_addc_u32 s81, s81, 0
	s_cmp_ge_u32 s82, s65
	s_mov_b32 s54, s82
	s_cbranch_scc0 .LBB0_310

; #define PG8_STAGE(bufoff, gbase, voff) do { _Pragma("unroll") for (int _i = 0; _i < 2; ++_i) \
;         __builtin_amdgcn_global_load_lds((const unsigned*)((const char*)(gbase) + (voff)[_i]), (PG8_LAS unsigned*)(lds + (bufoff) + ldsw + _i * 8192), 16, 0, 0); } while (0)
; #define PG8_LDA(dst, b, h) do { _Pragma("unroll") for (int m = 0; m < 4; ++m) _Pragma("unroll") for (int k = 0; k < 2; ++k) dst[m][k] = *(const PG8_LAS bf16x8*)(lds + PG8_SA(b, h) + aoff + m * 2048 + k * 1024); } while (0)
; #define PG8_LDB(dst, b, h) do { _Pragma("unroll") for (int n = 0; n < 2; ++n) _Pragma("unroll") for (int k = 0; k < 2; ++k) dst[n][k] = *(const PG8_LAS bf16x8*)(lds + PG8_SB(b, h) + boff + n * 2048 + k * 1024); } while (0)
; #define PG8_WAIT_V(n) asm volatile("s_waitcnt vmcnt(" #n ")" ::: "memory")
; #define PG8_WAIT_L(n) asm volatile("s_waitcnt lgkmcnt(" #n ")" ::: "memory")
; #define PG8_BAR __builtin_amdgcn_s_barrier()
; #define PG8_SCHED __builtin_amdgcn_sched_barrier(0)
; template <class Epi, class Sched, bool ALIGN_EPI = false, bool SP2 = false, bool F16 = false>
; __device__ __forceinline__ void gemm_phase(PG8_LAS unsigned char* lds, const Gemm g, const Sched& S, const Epi& E) {
;     ...
;             const bool last = (t == nt - 2);
;             const char* a1 = cA + (size_t)(t + 1) * kstep;
;             const char* a2 = last ? nA : cA + (size_t)(t + 2) * kstep; const char* b2 = last ? nB : cB + (size_t)(t + 2) * kstep;
;             const char* a3 = a2 + kstep; const char* b3 = b2 + kstep;
;             if (last && has_next) S.a_ready(nxt);
;             if constexpr (SP2) {
;             PG8_LDB(B0, 0, 0); PG8_LDB(B1, 0, 1); PG8_SCHED; PG8_LDA(At, 0, 0); PG8_STAGE(PG8_SA(1, 1), a1 + hstepA, voffA);
;             PG8_WAIT_V(8); PG8_WAIT_L(0); PG8_BAR; PG8_MMA(0, 0, At, B0); PG8_MMA(0, 1, At, B1); PG8_BAR; PG8_SCHED;
;             PG8_LDA(At, 0, 1); PG8_STAGE(PG8_SB(0, 0), b2, voffB); PG8_STAGE(PG8_SB(0, 1), b2 + hstepB, voffB); PG8_STAGE(PG8_SA(0, 0), a2, voffA);
;             PG8_WAIT_V(8); PG8_WAIT_L(0); PG8_BAR; PG8_MMA(1, 0, At, B0); PG8_MMA(1, 1, At, B1); PG8_BAR; PG8_SCHED;
.Lpk_rs:
	s_add_i32 s81, s54, 2
	s_add_u32 s82, s52, 0x80
	s_addc_u32 s55, s53, 0
	s_add_i32 s94, 0, 0x10000
	s_cmp_eq_u32 s74, s54
	s_cselect_b32 s55, s41, s55
	s_cselect_b32 s54, s40, s82
	s_cselect_b32 s83, s47, s80
	s_cselect_b32 s82, s46, s79
	s_add_i32 s95, 0, 0x14000
	v_add_u32_e32 v152, s94, v158
	v_add_u32_e32 v156, s95, v158
	ds_read_b128 v[130:133], v152
	ds_read_b128 v[134:137], v152 offset:1024
	ds_read_b128 v[148:151], v152 offset:2048
	ds_read_b128 v[152:155], v152 offset:3072
	ds_read_b128 v[162:165], v156
	ds_read_b128 v[166:169], v156 offset:1024
	ds_read_b128 v[170:173], v156 offset:2048
	ds_read_b128 v[182:185], v156 offset:3072
	s_add_i32 m0, s3, 0xc000
	ds_read_b128 v[186:189], v160
	ds_read_b128 v[190:193], v160 offset:1024
	ds_read_b128 v[194:197], v160 offset:2048
	ds_read_b128 v[204:207], v160 offset:3072
	ds_read_b128 v[208:211], v160 offset:4096
	ds_read_b128 v[212:215], v160 offset:5120
	ds_read_b128 v[216:219], v160 offset:6144
	ds_read_b128 v[220:223], v160 offset:7168
	global_load_lds_dwordx4 v144, s[52:53]
	s_add_i32 m0, s3, 0xe000
	s_nop 0
	global_load_lds_dwordx4 v146, s[52:53]
	s_waitcnt vmcnt(8)
	s_waitcnt lgkmcnt(0)
	s_setprio 1
	s_barrier
	v_mfma_f32_16x16x32_bf16 v[122:125], v[130:133], v[186:189], 0
	v_mfma_f32_16x16x32_bf16 v[126:129], v[148:151], v[186:189], 0
	v_mfma_f32_16x16x32_bf16 v[110:113], v[130:133], v[194:197], 0
	v_mfma_f32_16x16x32_bf16 v[106:109], v[148:151], v[194:197], 0
	v_mfma_f32_16x16x32_bf16 v[94:97], v[130:133], v[208:211], 0
	v_mfma_f32_16x16x32_bf16 v[90:93], v[148:151], v[208:211], 0
	v_mfma_f32_16x16x32_bf16 v[78:81], v[130:133], v[216:219], 0
	v_mfma_f32_16x16x32_bf16 v[74:77], v[148:151], v[216:219], 0
	v_mfma_f32_16x16x32_bf16 v[122:125], v[134:137], v[190:193], v[122:125]
	v_mfma_f32_16x16x32_bf16 v[126:129], v[152:155], v[190:193], v[126:129]
	v_mfma_f32_16x16x32_bf16 v[110:113], v[134:137], v[204:207], v[110:113]
	v_mfma_f32_16x16x32_bf16 v[106:109], v[152:155], v[204:207], v[106:109]
	v_mfma_f32_16x16x32_bf16 v[94:97], v[134:137], v[212:215], v[94:97]
	v_mfma_f32_16x16x32_bf16 v[90:93], v[152:155], v[212:215], v[90:93]
	v_mfma_f32_16x16x32_bf16 v[78:81], v[134:137], v[220:223], v[78:81]
	v_mfma_f32_16x16x32_bf16 v[74:77], v[152:155], v[220:223], v[74:77]
	v_mfma_f32_16x16x32_bf16 v[118:121], v[162:165], v[186:189], 0
	v_mfma_f32_16x16x32_bf16 v[114:117], v[170:173], v[186:189], 0
	v_mfma_f32_16x16x32_bf16 v[102:105], v[162:165], v[194:197], 0
	v_mfma_f32_16x16x32_bf16 v[98:101], v[170:173], v[194:197], 0
	v_mfma_f32_16x16x32_bf16 v[86:89], v[162:165], v[208:211], 0
	v_mfma_f32_16x16x32_bf16 v[82:85], v[170:173], v[208:211], 0
	v_mfma_f32_16x16x32_bf16 v[70:73], v[162:165], v[216:219], 0
	v_mfma_f32_16x16x32_bf16 v[66:69], v[170:173], v[216:219], 0
	v_mfma_f32_16x16x32_bf16 v[118:121], v[166:169], v[190:193], v[118:121]
	v_mfma_f32_16x16x32_bf16 v[114:117], v[182:185], v[190:193], v[114:117]
	v_mfma_f32_16x16x32_bf16 v[102:105], v[166:169], v[204:207], v[102:105]
	v_mfma_f32_16x16x32_bf16 v[98:101], v[182:185], v[204:207], v[98:101]
	v_mfma_f32_16x16x32_bf16 v[86:89], v[166:169], v[212:215], v[86:89]
	v_mfma_f32_16x16x32_bf16 v[82:85], v[182:185], v[212:215], v[82:85]
	v_mfma_f32_16x16x32_bf16 v[70:73], v[166:169], v[220:223], v[70:73]
	v_mfma_f32_16x16x32_bf16 v[66:69], v[182:185], v[220:223], v[66:69]
	s_barrier
	s_setprio 0
	s_add_i32 s94, s94, s2
	v_lshl_add_u64 v[156:157], s[82:83], 0, v[174:175]
	s_mov_b32 m0, s94
	ds_read_b128 v[186:189], v160 offset:16384
	ds_read_b128 v[190:193], v160 offset:17408
	ds_read_b128 v[194:197], v160 offset:18432
	ds_read_b128 v[204:207], v160 offset:19456
	ds_read_b128 v[208:211], v160 offset:20480
	ds_read_b128 v[212:215], v160 offset:21504
	ds_read_b128 v[216:219], v160 offset:22528
	ds_read_b128 v[220:223], v160 offset:23552
	global_load_lds_dwordx4 v[156:157], off
	s_add_i32 m0, s94, 0x2000
	v_lshl_add_u64 v[176:177], s[82:83], 0, v[142:143]
	s_add_u32 s82, s82, s48
	s_addc_u32 s83, s83, 0
	s_add_i32 s94, s95, s2
	global_load_lds_dwordx4 v[176:177], off
	v_lshl_add_u64 v[224:225], s[82:83], 0, v[174:175]
	s_mov_b32 m0, s94
	v_lshl_add_u64 v[226:227], s[82:83], 0, v[142:143]
	global_load_lds_dwordx4 v[224:225], off
	s_add_i32 m0, s94, 0x2000
	v_lshl_add_u64 v[228:229], s[54:55], 0, v[138:139]
	global_load_lds_dwordx4 v[226:227], off
	s_mov_b32 m0, s3
	v_lshl_add_u64 v[230:231], s[54:55], 0, v[140:141]
	global_load_lds_dwordx4 v[228:229], off
	s_mov_b32 m0, s12
	s_nop 0
	global_load_lds_dwordx4 v[230:231], off
	s_waitcnt vmcnt(8)
	s_waitcnt lgkmcnt(0)
	s_setprio 1
	s_barrier
	v_mfma_f32_16x16x32_bf16 v[62:65], v[130:133], v[186:189], 0
	v_mfma_f32_16x16x32_bf16 v[58:61], v[148:151], v[186:189], 0
	v_mfma_f32_16x16x32_bf16 v[46:49], v[130:133], v[194:197], 0
	v_mfma_f32_16x16x32_bf16 v[42:45], v[148:151], v[194:197], 0
	v_mfma_f32_16x16x32_bf16 v[30:33], v[130:133], v[208:211], 0
	v_mfma_f32_16x16x32_bf16 v[26:29], v[148:151], v[208:211], 0
	v_mfma_f32_16x16x32_bf16 v[14:17], v[130:133], v[216:219], 0
	v_mfma_f32_16x16x32_bf16 v[10:13], v[148:151], v[216:219], 0
	v_mfma_f32_16x16x32_bf16 v[62:65], v[134:137], v[190:193], v[62:65]
	v_mfma_f32_16x16x32_bf16 v[58:61], v[152:155], v[190:193], v[58:61]
	v_mfma_f32_16x16x32_bf16 v[46:49], v[134:137], v[204:207], v[46:49]
	v_mfma_f32_16x16x32_bf16 v[42:45], v[152:155], v[204:207], v[42:45]
	v_mfma_f32_16x16x32_bf16 v[30:33], v[134:137], v[212:215], v[30:33]
	v_mfma_f32_16x16x32_bf16 v[26:29], v[152:155], v[212:215], v[26:29]
	v_mfma_f32_16x16x32_bf16 v[14:17], v[134:137], v[220:223], v[14:17]
	v_mfma_f32_16x16x32_bf16 v[10:13], v[152:155], v[220:223], v[10:13]
	v_mfma_f32_16x16x32_bf16 v[54:57], v[162:165], v[186:189], 0
	v_mfma_f32_16x16x32_bf16 v[50:53], v[170:173], v[186:189], 0
	v_mfma_f32_16x16x32_bf16 v[38:41], v[162:165], v[194:197], 0
	v_mfma_f32_16x16x32_bf16 v[34:37], v[170:173], v[194:197], 0
	v_mfma_f32_16x16x32_bf16 v[22:25], v[162:165], v[208:211], 0
	v_mfma_f32_16x16x32_bf16 v[18:21], v[170:173], v[208:211], 0
	v_mfma_f32_16x16x32_bf16 v[6:9], v[162:165], v[216:219], 0
	v_mfma_f32_16x16x32_bf16 v[2:5], v[170:173], v[216:219], 0
	v_mfma_f32_16x16x32_bf16 v[54:57], v[166:169], v[190:193], v[54:57]
	v_mfma_f32_16x16x32_bf16 v[50:53], v[182:185], v[190:193], v[50:53]
	v_mfma_f32_16x16x32_bf16 v[38:41], v[166:169], v[204:207], v[38:41]
	v_mfma_f32_16x16x32_bf16 v[34:37], v[182:185], v[204:207], v[34:37]
	v_mfma_f32_16x16x32_bf16 v[22:25], v[166:169], v[212:215], v[22:25]
	v_mfma_f32_16x16x32_bf16 v[18:21], v[182:185], v[212:215], v[18:21]
	v_mfma_f32_16x16x32_bf16 v[6:9], v[166:169], v[220:223], v[6:9]
	v_mfma_f32_16x16x32_bf16 v[2:5], v[182:185], v[220:223], v[2:5]
	s_barrier
; #define PG8_STAGE(bufoff, gbase, voff) do { _Pragma("unroll") for (int _i = 0; _i < 2; ++_i) \
;         __builtin_amdgcn_global_load_lds((const unsigned*)((const char*)(gbase) + (voff)[_i]), (PG8_LAS unsigned*)(lds + (bufoff) + ldsw + _i * 8192), 16, 0, 0); } while (0)
; #define PG8_LDA(dst, b, h) do { _Pragma("unroll") for (int m = 0; m < 4; ++m) _Pragma("unroll") for (int k = 0; k < 2; ++k) dst[m][k] = *(const PG8_LAS bf16x8*)(lds + PG8_SA(b, h) + aoff + m * 2048 + k * 1024); } while (0)
; #define PG8_LDB(dst, b, h) do { _Pragma("unroll") for (int n = 0; n < 2; ++n) _Pragma("unroll") for (int k = 0; k < 2; ++k) dst[n][k] = *(const PG8_LAS bf16x8*)(lds + PG8_SB(b, h) + boff + n * 2048 + k * 1024); } while (0)
; #define PG8_WAIT_V(n) asm volatile("s_waitcnt vmcnt(" #n ")" ::: "memory")
; #define PG8_WAIT_L(n) asm volatile("s_waitcnt lgkmcnt(" #n ")" ::: "memory")
; #define PG8_BAR __builtin_amdgcn_s_barrier()
; #define PG8_SCHED __builtin_amdgcn_sched_barrier(0)
; template <class Epi, class Sched, bool ALIGN_EPI = false, bool SP2 = false, bool F16 = false>
; __device__ __forceinline__ void gemm_phase(PG8_LAS unsigned char* lds, const Gemm g, const Sched& S, const Epi& E) {
;     ...
;             PG8_LDB(B0, 1, 0); PG8_LDB(B1, 1, 1); PG8_SCHED; PG8_LDA(At, 1, 0); PG8_STAGE(PG8_SA(0, 1), a2 + hstepA, voffA);
;             PG8_WAIT_V(8); PG8_WAIT_L(0); PG8_BAR; PG8_MMA(0, 0, At, B0); PG8_MMA(0, 1, At, B1); PG8_BAR; PG8_SCHED;
;             PG8_LDA(At, 1, 1); PG8_STAGE(PG8_SB(1, 0), b3, voffB); PG8_STAGE(PG8_SB(1, 1), b3 + hstepB, voffB); PG8_STAGE(PG8_SA(1, 0), a3, voffA);
;             PG8_WAIT_V(8); PG8_WAIT_L(0); PG8_BAR; PG8_MMA(1, 0, At, B0); PG8_MMA(1, 1, At, B1); PG8_BAR; PG8_SCHED;
	s_setprio 0
	s_add_i32 s82, 0, 0x18000
	s_add_i32 s83, 0, 0x1c000
	v_add_u32_e32 v152, s82, v158
	v_add_u32_e32 v161, s83, v158
	ds_read_b128 v[130:133], v152
	ds_read_b128 v[134:137], v152 offset:1024
	ds_read_b128 v[148:151], v152 offset:2048
	ds_read_b128 v[152:155], v152 offset:3072
	ds_read_b128 v[162:165], v161
	ds_read_b128 v[166:169], v161 offset:1024
	ds_read_b128 v[170:173], v161 offset:2048
	ds_read_b128 v[182:185], v161 offset:3072
	s_add_u32 s54, s54, s8
	s_addc_u32 s55, s55, 0
	s_mov_b32 m0, s13
	ds_read_b128 v[186:189], v160 offset:32768
	ds_read_b128 v[190:193], v160 offset:33792
	ds_read_b128 v[194:197], v160 offset:34816
	ds_read_b128 v[204:207], v160 offset:35840
	ds_read_b128 v[208:211], v160 offset:36864
	ds_read_b128 v[212:215], v160 offset:37888
	ds_read_b128 v[216:219], v160 offset:38912
	ds_read_b128 v[220:223], v160 offset:39936
	global_load_lds_dwordx4 v138, s[54:55]
	s_mov_b32 m0, s22
	s_nop 0
	global_load_lds_dwordx4 v140, s[54:55]
	s_waitcnt vmcnt(8)
	s_waitcnt lgkmcnt(0)
	s_setprio 1
	s_barrier
	v_mfma_f32_16x16x32_bf16 v[122:125], v[130:133], v[186:189], v[122:125]
	v_mfma_f32_16x16x32_bf16 v[126:129], v[148:151], v[186:189], v[126:129]
	v_mfma_f32_16x16x32_bf16 v[110:113], v[130:133], v[194:197], v[110:113]
	v_mfma_f32_16x16x32_bf16 v[106:109], v[148:151], v[194:197], v[106:109]
	v_mfma_f32_16x16x32_bf16 v[94:97], v[130:133], v[208:211], v[94:97]
	v_mfma_f32_16x16x32_bf16 v[90:93], v[148:151], v[208:211], v[90:93]
	v_mfma_f32_16x16x32_bf16 v[78:81], v[130:133], v[216:219], v[78:81]
	v_mfma_f32_16x16x32_bf16 v[74:77], v[148:151], v[216:219], v[74:77]
	v_mfma_f32_16x16x32_bf16 v[122:125], v[134:137], v[190:193], v[122:125]
	v_mfma_f32_16x16x32_bf16 v[126:129], v[152:155], v[190:193], v[126:129]
	v_mfma_f32_16x16x32_bf16 v[110:113], v[134:137], v[204:207], v[110:113]
	v_mfma_f32_16x16x32_bf16 v[106:109], v[152:155], v[204:207], v[106:109]
	v_mfma_f32_16x16x32_bf16 v[94:97], v[134:137], v[212:215], v[94:97]
	v_mfma_f32_16x16x32_bf16 v[90:93], v[152:155], v[212:215], v[90:93]
	v_mfma_f32_16x16x32_bf16 v[78:81], v[134:137], v[220:223], v[78:81]
	v_mfma_f32_16x16x32_bf16 v[74:77], v[152:155], v[220:223], v[74:77]
	v_mfma_f32_16x16x32_bf16 v[118:121], v[162:165], v[186:189], v[118:121]
	v_mfma_f32_16x16x32_bf16 v[114:117], v[170:173], v[186:189], v[114:117]
	v_mfma_f32_16x16x32_bf16 v[102:105], v[162:165], v[194:197], v[102:105]
	v_mfma_f32_16x16x32_bf16 v[98:101], v[170:173], v[194:197], v[98:101]
	v_mfma_f32_16x16x32_bf16 v[86:89], v[162:165], v[208:211], v[86:89]
	v_mfma_f32_16x16x32_bf16 v[82:85], v[170:173], v[208:211], v[82:85]
	v_mfma_f32_16x16x32_bf16 v[70:73], v[162:165], v[216:219], v[70:73]
	v_mfma_f32_16x16x32_bf16 v[66:69], v[170:173], v[216:219], v[66:69]
	v_mfma_f32_16x16x32_bf16 v[118:121], v[166:169], v[190:193], v[118:121]
	v_mfma_f32_16x16x32_bf16 v[114:117], v[182:185], v[190:193], v[114:117]
	v_mfma_f32_16x16x32_bf16 v[102:105], v[166:169], v[204:207], v[102:105]
	v_mfma_f32_16x16x32_bf16 v[98:101], v[182:185], v[204:207], v[98:101]
	v_mfma_f32_16x16x32_bf16 v[86:89], v[166:169], v[212:215], v[86:89]
	v_mfma_f32_16x16x32_bf16 v[82:85], v[182:185], v[212:215], v[82:85]
	v_mfma_f32_16x16x32_bf16 v[70:73], v[166:169], v[220:223], v[70:73]
	v_mfma_f32_16x16x32_bf16 v[66:69], v[182:185], v[220:223], v[66:69]
	s_barrier
	s_setprio 0
	s_add_i32 s54, s82, s2
	v_lshl_add_u64 v[156:157], v[156:157], 0, s[92:93]
	s_mov_b32 m0, s54
	ds_read_b128 v[186:189], v160 offset:49152
	ds_read_b128 v[190:193], v160 offset:50176
	ds_read_b128 v[194:197], v160 offset:51200
	ds_read_b128 v[204:207], v160 offset:52224
	ds_read_b128 v[208:211], v160 offset:53248
	ds_read_b128 v[212:215], v160 offset:54272
	ds_read_b128 v[216:219], v160 offset:55296
	ds_read_b128 v[220:223], v160 offset:56320
	global_load_lds_dwordx4 v[156:157], off
	v_lshl_add_u64 v[156:157], v[176:177], 0, s[92:93]
	s_add_i32 m0, s54, 0x2000
	s_add_i32 s54, s83, s2
	global_load_lds_dwordx4 v[156:157], off
	v_lshl_add_u64 v[156:157], v[224:225], 0, s[92:93]
	s_mov_b32 m0, s54
	s_nop 0
	global_load_lds_dwordx4 v[156:157], off
	v_lshl_add_u64 v[156:157], v[226:227], 0, s[92:93]
	s_add_i32 m0, s54, 0x2000
	s_nop 0
	global_load_lds_dwordx4 v[156:157], off
	v_lshl_add_u64 v[156:157], v[228:229], 0, s[92:93]
	s_mov_b32 m0, s33
	s_nop 0
	global_load_lds_dwordx4 v[156:157], off
	v_lshl_add_u64 v[156:157], v[230:231], 0, s[92:93]
	s_mov_b32 m0, s35
	s_nop 0
	global_load_lds_dwordx4 v[156:157], off
	s_waitcnt vmcnt(8)
	s_waitcnt lgkmcnt(0)
	s_setprio 1
	s_barrier
	v_mfma_f32_16x16x32_bf16 v[62:65], v[130:133], v[186:189], v[62:65]
	v_mfma_f32_16x16x32_bf16 v[58:61], v[148:151], v[186:189], v[58:61]
	v_mfma_f32_16x16x32_bf16 v[46:49], v[130:133], v[194:197], v[46:49]
	v_mfma_f32_16x16x32_bf16 v[42:45], v[148:151], v[194:197], v[42:45]
	v_mfma_f32_16x16x32_bf16 v[30:33], v[130:133], v[208:211], v[30:33]
	v_mfma_f32_16x16x32_bf16 v[26:29], v[148:151], v[208:211], v[26:29]
	v_mfma_f32_16x16x32_bf16 v[14:17], v[130:133], v[216:219], v[14:17]
	v_mfma_f32_16x16x32_bf16 v[10:13], v[148:151], v[216:219], v[10:13]
	v_mfma_f32_16x16x32_bf16 v[62:65], v[134:137], v[190:193], v[62:65]
	v_mfma_f32_16x16x32_bf16 v[58:61], v[152:155], v[190:193], v[58:61]
	v_mfma_f32_16x16x32_bf16 v[46:49], v[134:137], v[204:207], v[46:49]
	v_mfma_f32_16x16x32_bf16 v[42:45], v[152:155], v[204:207], v[42:45]
	v_mfma_f32_16x16x32_bf16 v[30:33], v[134:137], v[212:215], v[30:33]
	v_mfma_f32_16x16x32_bf16 v[26:29], v[152:155], v[212:215], v[26:29]
	v_mfma_f32_16x16x32_bf16 v[14:17], v[134:137], v[220:223], v[14:17]
	v_mfma_f32_16x16x32_bf16 v[10:13], v[152:155], v[220:223], v[10:13]
	v_mfma_f32_16x16x32_bf16 v[54:57], v[162:165], v[186:189], v[54:57]
	v_mfma_f32_16x16x32_bf16 v[50:53], v[170:173], v[186:189], v[50:53]
	v_mfma_f32_16x16x32_bf16 v[38:41], v[162:165], v[194:197], v[38:41]
	v_mfma_f32_16x16x32_bf16 v[34:37], v[170:173], v[194:197], v[34:37]
	v_mfma_f32_16x16x32_bf16 v[22:25], v[162:165], v[208:211], v[22:25]
	v_mfma_f32_16x16x32_bf16 v[18:21], v[170:173], v[208:211], v[18:21]
	v_mfma_f32_16x16x32_bf16 v[6:9], v[162:165], v[216:219], v[6:9]
	v_mfma_f32_16x16x32_bf16 v[2:5], v[170:173], v[216:219], v[2:5]
	v_mfma_f32_16x16x32_bf16 v[54:57], v[166:169], v[190:193], v[54:57]
	v_mfma_f32_16x16x32_bf16 v[50:53], v[182:185], v[190:193], v[50:53]
	v_mfma_f32_16x16x32_bf16 v[38:41], v[166:169], v[204:207], v[38:41]
	v_mfma_f32_16x16x32_bf16 v[34:37], v[182:185], v[204:207], v[34:37]
	v_mfma_f32_16x16x32_bf16 v[22:25], v[166:169], v[212:215], v[22:25]
	v_mfma_f32_16x16x32_bf16 v[18:21], v[182:185], v[212:215], v[18:21]
	v_mfma_f32_16x16x32_bf16 v[6:9], v[166:169], v[220:223], v[6:9]
	v_mfma_f32_16x16x32_bf16 v[2:5], v[182:185], v[220:223], v[2:5]
	s_barrier
	s_setprio 0
	s_add_u32 s52, s52, 0x100
	s_addc_u32 s53, s53, 0
	s_add_u32 s79, s79, 0x100
	s_addc_u32 s80, s80, 0
	s_cmp_ge_u32 s81, s65
	s_mov_b32 s54, s81
	s_cbranch_scc1 .LBB0_346
; #define PG8_STAGE(bufoff, gbase, voff) do { _Pragma("unroll") for (int _i = 0; _i < 2; ++_i) \
;         __builtin_amdgcn_global_load_lds((const unsigned*)((const char*)(gbase) + (voff)[_i]), (PG8_LAS unsigned*)(lds + (bufoff) + ldsw + _i * 8192), 16, 0, 0); } while (0)
; #define PG8_LDA(dst, b, h) do { _Pragma("unroll") for (int m = 0; m < 4; ++m) _Pragma("unroll") for (int k = 0; k < 2; ++k) dst[m][k] = *(const PG8_LAS bf16x8*)(lds + PG8_SA(b, h) + aoff + m * 2048 + k * 1024); } while (0)
; #define PG8_LDB(dst, b, h) do { _Pragma("unroll") for (int n = 0; n < 2; ++n) _Pragma("unroll") for (int k = 0; k < 2; ++k) dst[n][k] = *(const PG8_LAS bf16x8*)(lds + PG8_SB(b, h) + boff + n * 2048 + k * 1024); } while (0)
; #define PG8_WAIT_V(n) asm volatile("s_waitcnt vmcnt(" #n ")" ::: "memory")
; #define PG8_WAIT_L(n) asm volatile("s_waitcnt lgkmcnt(" #n ")" ::: "memory")
; #define PG8_BAR __builtin_amdgcn_s_barrier()
; #define PG8_SCHED __builtin_amdgcn_sched_barrier(0)
; template <class Epi, class Sched, bool ALIGN_EPI = false, bool SP2 = false, bool F16 = false>
; __device__ __forceinline__ void gemm_phase(PG8_LAS unsigned char* lds, const Gemm g, const Sched& S, const Epi& E) {
;     ...
;             const bool last = (t == nt - 2);
;             const char* a1 = cA + (size_t)(t + 1) * kstep;
;             const char* a2 = last ? nA : cA + (size_t)(t + 2) * kstep; const char* b2 = last ? nB : cB + (size_t)(t + 2) * kstep;
;             const char* a3 = a2 + kstep; const char* b3 = b2 + kstep;
;             if (last && has_next) S.a_ready(nxt);
;             if constexpr (SP2) {
;             PG8_LDB(B0, 0, 0); PG8_LDB(B1, 0, 1); PG8_SCHED; PG8_LDA(At, 0, 0); PG8_STAGE(PG8_SA(1, 1), a1 + hstepA, voffA);
;             PG8_WAIT_V(8); PG8_WAIT_L(0); PG8_BAR; PG8_MMA(0, 0, At, B0); PG8_MMA(0, 1, At, B1); PG8_BAR; PG8_SCHED;
;             PG8_LDA(At, 0, 1); PG8_STAGE(PG8_SB(0, 0), b2, voffB); PG8_STAGE(PG8_SB(0, 1), b2 + hstepB, voffB); PG8_STAGE(PG8_SA(0, 0), a2, voffA);
.LBB0_345:
	s_add_i32 s81, s54, 2
	s_add_u32 s82, s52, 0x80
	s_addc_u32 s55, s53, 0
	s_add_i32 s94, 0, 0x10000
	s_cmp_eq_u32 s74, s54
	s_cselect_b32 s55, s41, s55
	s_cselect_b32 s54, s40, s82
	s_cselect_b32 s83, s47, s80
	s_cselect_b32 s82, s46, s79
	s_add_i32 s95, 0, 0x14000
	v_add_u32_e32 v152, s94, v158
	v_add_u32_e32 v156, s95, v158
	ds_read_b128 v[130:133], v152
	ds_read_b128 v[134:137], v152 offset:1024
	ds_read_b128 v[148:151], v152 offset:2048
	ds_read_b128 v[152:155], v152 offset:3072
	ds_read_b128 v[162:165], v156
	ds_read_b128 v[166:169], v156 offset:1024
	ds_read_b128 v[170:173], v156 offset:2048
	ds_read_b128 v[182:185], v156 offset:3072
	s_add_i32 m0, s3, 0xc000
	ds_read_b128 v[186:189], v160
	ds_read_b128 v[190:193], v160 offset:1024
	ds_read_b128 v[194:197], v160 offset:2048
	ds_read_b128 v[204:207], v160 offset:3072
	ds_read_b128 v[208:211], v160 offset:4096
	ds_read_b128 v[212:215], v160 offset:5120
	ds_read_b128 v[216:219], v160 offset:6144
	ds_read_b128 v[220:223], v160 offset:7168
	global_load_lds_dwordx4 v144, s[52:53]
	s_add_i32 m0, s3, 0xe000
	s_nop 0
	global_load_lds_dwordx4 v146, s[52:53]
	s_waitcnt vmcnt(8)
	s_waitcnt lgkmcnt(0)
	s_setprio 1
	s_barrier
	v_mfma_f32_16x16x32_bf16 v[122:125], v[130:133], v[186:189], v[122:125]
	v_mfma_f32_16x16x32_bf16 v[126:129], v[148:151], v[186:189], v[126:129]
	v_mfma_f32_16x16x32_bf16 v[110:113], v[130:133], v[194:197], v[110:113]
	v_mfma_f32_16x16x32_bf16 v[106:109], v[148:151], v[194:197], v[106:109]
	v_mfma_f32_16x16x32_bf16 v[94:97], v[130:133], v[208:211], v[94:97]
	v_mfma_f32_16x16x32_bf16 v[90:93], v[148:151], v[208:211], v[90:93]
	v_mfma_f32_16x16x32_bf16 v[78:81], v[130:133], v[216:219], v[78:81]
	v_mfma_f32_16x16x32_bf16 v[74:77], v[148:151], v[216:219], v[74:77]
	v_mfma_f32_16x16x32_bf16 v[122:125], v[134:137], v[190:193], v[122:125]
	v_mfma_f32_16x16x32_bf16 v[126:129], v[152:155], v[190:193], v[126:129]
	v_mfma_f32_16x16x32_bf16 v[110:113], v[134:137], v[204:207], v[110:113]
	v_mfma_f32_16x16x32_bf16 v[106:109], v[152:155], v[204:207], v[106:109]
	v_mfma_f32_16x16x32_bf16 v[94:97], v[134:137], v[212:215], v[94:97]
	v_mfma_f32_16x16x32_bf16 v[90:93], v[152:155], v[212:215], v[90:93]
	v_mfma_f32_16x16x32_bf16 v[78:81], v[134:137], v[220:223], v[78:81]
	v_mfma_f32_16x16x32_bf16 v[74:77], v[152:155], v[220:223], v[74:77]
	v_mfma_f32_16x16x32_bf16 v[118:121], v[162:165], v[186:189], v[118:121]
	v_mfma_f32_16x16x32_bf16 v[114:117], v[170:173], v[186:189], v[114:117]
	v_mfma_f32_16x16x32_bf16 v[102:105], v[162:165], v[194:197], v[102:105]
	v_mfma_f32_16x16x32_bf16 v[98:101], v[170:173], v[194:197], v[98:101]
	v_mfma_f32_16x16x32_bf16 v[86:89], v[162:165], v[208:211], v[86:89]
	v_mfma_f32_16x16x32_bf16 v[82:85], v[170:173], v[208:211], v[82:85]
	v_mfma_f32_16x16x32_bf16 v[70:73], v[162:165], v[216:219], v[70:73]
	v_mfma_f32_16x16x32_bf16 v[66:69], v[170:173], v[216:219], v[66:69]
	v_mfma_f32_16x16x32_bf16 v[118:121], v[166:169], v[190:193], v[118:121]
	v_mfma_f32_16x16x32_bf16 v[114:117], v[182:185], v[190:193], v[114:117]
	v_mfma_f32_16x16x32_bf16 v[102:105], v[166:169], v[204:207], v[102:105]
	v_mfma_f32_16x16x32_bf16 v[98:101], v[182:185], v[204:207], v[98:101]
	v_mfma_f32_16x16x32_bf16 v[86:89], v[166:169], v[212:215], v[86:89]
	v_mfma_f32_16x16x32_bf16 v[82:85], v[182:185], v[212:215], v[82:85]
	v_mfma_f32_16x16x32_bf16 v[70:73], v[166:169], v[220:223], v[70:73]
	v_mfma_f32_16x16x32_bf16 v[66:69], v[182:185], v[220:223], v[66:69]
	s_barrier
	s_setprio 0
	s_add_i32 s94, s94, s2
	v_lshl_add_u64 v[156:157], s[82:83], 0, v[174:175]
	s_mov_b32 m0, s94
	ds_read_b128 v[186:189], v160 offset:16384
	ds_read_b128 v[190:193], v160 offset:17408
	ds_read_b128 v[194:197], v160 offset:18432
	ds_read_b128 v[204:207], v160 offset:19456
	ds_read_b128 v[208:211], v160 offset:20480
	ds_read_b128 v[212:215], v160 offset:21504
	ds_read_b128 v[216:219], v160 offset:22528
	ds_read_b128 v[220:223], v160 offset:23552
	global_load_lds_dwordx4 v[156:157], off
	s_add_i32 m0, s94, 0x2000
	v_lshl_add_u64 v[176:177], s[82:83], 0, v[142:143]
	s_add_u32 s82, s82, s48
	s_addc_u32 s83, s83, 0
	s_add_i32 s94, s95, s2
	global_load_lds_dwordx4 v[176:177], off
	v_lshl_add_u64 v[224:225], s[82:83], 0, v[174:175]
	s_mov_b32 m0, s94
	v_lshl_add_u64 v[226:227], s[82:83], 0, v[142:143]
	global_load_lds_dwordx4 v[224:225], off
	s_add_i32 m0, s94, 0x2000
	v_lshl_add_u64 v[228:229], s[54:55], 0, v[138:139]
	global_load_lds_dwordx4 v[226:227], off
	s_mov_b32 m0, s3
	v_lshl_add_u64 v[230:231], s[54:55], 0, v[140:141]
	global_load_lds_dwordx4 v[228:229], off
	s_mov_b32 m0, s12
	s_nop 0
	global_load_lds_dwordx4 v[230:231], off
	s_waitcnt vmcnt(8)
	s_waitcnt lgkmcnt(0)
	s_setprio 1
	s_barrier
; #define PG8_STAGE(bufoff, gbase, voff) do { _Pragma("unroll") for (int _i = 0; _i < 2; ++_i) \
;         __builtin_amdgcn_global_load_lds((const unsigned*)((const char*)(gbase) + (voff)[_i]), (PG8_LAS unsigned*)(lds + (bufoff) + ldsw + _i * 8192), 16, 0, 0); } while (0)
; #define PG8_LDA(dst, b, h) do { _Pragma("unroll") for (int m = 0; m < 4; ++m) _Pragma("unroll") for (int k = 0; k < 2; ++k) dst[m][k] = *(const PG8_LAS bf16x8*)(lds + PG8_SA(b, h) + aoff + m * 2048 + k * 1024); } while (0)
; #define PG8_LDB(dst, b, h) do { _Pragma("unroll") for (int n = 0; n < 2; ++n) _Pragma("unroll") for (int k = 0; k < 2; ++k) dst[n][k] = *(const PG8_LAS bf16x8*)(lds + PG8_SB(b, h) + boff + n * 2048 + k * 1024); } while (0)
; #define PG8_WAIT_V(n) asm volatile("s_waitcnt vmcnt(" #n ")" ::: "memory")
; #define PG8_WAIT_L(n) asm volatile("s_waitcnt lgkmcnt(" #n ")" ::: "memory")
; #define PG8_BAR __builtin_amdgcn_s_barrier()
; #define PG8_SCHED __builtin_amdgcn_sched_barrier(0)
; template <class Epi, class Sched, bool ALIGN_EPI = false, bool SP2 = false, bool F16 = false>
; __device__ __forceinline__ void gemm_phase(PG8_LAS unsigned char* lds, const Gemm g, const Sched& S, const Epi& E) {
;     ...
;             PG8_WAIT_V(8); PG8_WAIT_L(0); PG8_BAR; PG8_MMA(1, 0, At, B0); PG8_MMA(1, 1, At, B1); PG8_BAR; PG8_SCHED;
;             PG8_LDB(B0, 1, 0); PG8_LDB(B1, 1, 1); PG8_SCHED; PG8_LDA(At, 1, 0); PG8_STAGE(PG8_SA(0, 1), a2 + hstepA, voffA);
;             PG8_WAIT_V(8); PG8_WAIT_L(0); PG8_BAR; PG8_MMA(0, 0, At, B0); PG8_MMA(0, 1, At, B1); PG8_BAR; PG8_SCHED;
	v_mfma_f32_16x16x32_bf16 v[62:65], v[130:133], v[186:189], v[62:65]
	v_mfma_f32_16x16x32_bf16 v[58:61], v[148:151], v[186:189], v[58:61]
	v_mfma_f32_16x16x32_bf16 v[46:49], v[130:133], v[194:197], v[46:49]
	v_mfma_f32_16x16x32_bf16 v[42:45], v[148:151], v[194:197], v[42:45]
	v_mfma_f32_16x16x32_bf16 v[30:33], v[130:133], v[208:211], v[30:33]
	v_mfma_f32_16x16x32_bf16 v[26:29], v[148:151], v[208:211], v[26:29]
	v_mfma_f32_16x16x32_bf16 v[14:17], v[130:133], v[216:219], v[14:17]
	v_mfma_f32_16x16x32_bf16 v[10:13], v[148:151], v[216:219], v[10:13]
	v_mfma_f32_16x16x32_bf16 v[62:65], v[134:137], v[190:193], v[62:65]
	v_mfma_f32_16x16x32_bf16 v[58:61], v[152:155], v[190:193], v[58:61]
	v_mfma_f32_16x16x32_bf16 v[46:49], v[134:137], v[204:207], v[46:49]
	v_mfma_f32_16x16x32_bf16 v[42:45], v[152:155], v[204:207], v[42:45]
	v_mfma_f32_16x16x32_bf16 v[30:33], v[134:137], v[212:215], v[30:33]
	v_mfma_f32_16x16x32_bf16 v[26:29], v[152:155], v[212:215], v[26:29]
	v_mfma_f32_16x16x32_bf16 v[14:17], v[134:137], v[220:223], v[14:17]
	v_mfma_f32_16x16x32_bf16 v[10:13], v[152:155], v[220:223], v[10:13]
	v_mfma_f32_16x16x32_bf16 v[54:57], v[162:165], v[186:189], v[54:57]
	v_mfma_f32_16x16x32_bf16 v[50:53], v[170:173], v[186:189], v[50:53]
	v_mfma_f32_16x16x32_bf16 v[38:41], v[162:165], v[194:197], v[38:41]
	v_mfma_f32_16x16x32_bf16 v[34:37], v[170:173], v[194:197], v[34:37]
	v_mfma_f32_16x16x32_bf16 v[22:25], v[162:165], v[208:211], v[22:25]
	v_mfma_f32_16x16x32_bf16 v[18:21], v[170:173], v[208:211], v[18:21]
	v_mfma_f32_16x16x32_bf16 v[6:9], v[162:165], v[216:219], v[6:9]
	v_mfma_f32_16x16x32_bf16 v[2:5], v[170:173], v[216:219], v[2:5]
	v_mfma_f32_16x16x32_bf16 v[54:57], v[166:169], v[190:193], v[54:57]
	v_mfma_f32_16x16x32_bf16 v[50:53], v[182:185], v[190:193], v[50:53]
	v_mfma_f32_16x16x32_bf16 v[38:41], v[166:169], v[204:207], v[38:41]
	v_mfma_f32_16x16x32_bf16 v[34:37], v[182:185], v[204:207], v[34:37]
	v_mfma_f32_16x16x32_bf16 v[22:25], v[166:169], v[212:215], v[22:25]
	v_mfma_f32_16x16x32_bf16 v[18:21], v[182:185], v[212:215], v[18:21]
	v_mfma_f32_16x16x32_bf16 v[6:9], v[166:169], v[220:223], v[6:9]
	v_mfma_f32_16x16x32_bf16 v[2:5], v[182:185], v[220:223], v[2:5]
	s_barrier
	s_setprio 0
	s_add_i32 s82, 0, 0x18000
	s_add_i32 s83, 0, 0x1c000
	v_add_u32_e32 v152, s82, v158
	v_add_u32_e32 v161, s83, v158
	ds_read_b128 v[130:133], v152
	ds_read_b128 v[134:137], v152 offset:1024
	ds_read_b128 v[148:151], v152 offset:2048
	ds_read_b128 v[152:155], v152 offset:3072
	ds_read_b128 v[162:165], v161
	ds_read_b128 v[166:169], v161 offset:1024
	ds_read_b128 v[170:173], v161 offset:2048
	ds_read_b128 v[182:185], v161 offset:3072
	s_add_u32 s54, s54, s8
	s_addc_u32 s55, s55, 0
	s_mov_b32 m0, s13
	ds_read_b128 v[186:189], v160 offset:32768
	ds_read_b128 v[190:193], v160 offset:33792
	ds_read_b128 v[194:197], v160 offset:34816
	ds_read_b128 v[204:207], v160 offset:35840
	ds_read_b128 v[208:211], v160 offset:36864
	ds_read_b128 v[212:215], v160 offset:37888
	ds_read_b128 v[216:219], v160 offset:38912
	ds_read_b128 v[220:223], v160 offset:39936
	global_load_lds_dwordx4 v138, s[54:55]
	s_mov_b32 m0, s22
	s_nop 0
	global_load_lds_dwordx4 v140, s[54:55]
	s_waitcnt vmcnt(8)
	s_waitcnt lgkmcnt(0)
	s_setprio 1
	s_barrier
	v_mfma_f32_16x16x32_bf16 v[122:125], v[130:133], v[186:189], v[122:125]
	v_mfma_f32_16x16x32_bf16 v[126:129], v[148:151], v[186:189], v[126:129]
	v_mfma_f32_16x16x32_bf16 v[110:113], v[130:133], v[194:197], v[110:113]
	v_mfma_f32_16x16x32_bf16 v[106:109], v[148:151], v[194:197], v[106:109]
	v_mfma_f32_16x16x32_bf16 v[94:97], v[130:133], v[208:211], v[94:97]
	v_mfma_f32_16x16x32_bf16 v[90:93], v[148:151], v[208:211], v[90:93]
	v_mfma_f32_16x16x32_bf16 v[78:81], v[130:133], v[216:219], v[78:81]
	v_mfma_f32_16x16x32_bf16 v[74:77], v[148:151], v[216:219], v[74:77]
	v_mfma_f32_16x16x32_bf16 v[122:125], v[134:137], v[190:193], v[122:125]
	v_mfma_f32_16x16x32_bf16 v[126:129], v[152:155], v[190:193], v[126:129]
	v_mfma_f32_16x16x32_bf16 v[110:113], v[134:137], v[204:207], v[110:113]
	v_mfma_f32_16x16x32_bf16 v[106:109], v[152:155], v[204:207], v[106:109]
	v_mfma_f32_16x16x32_bf16 v[94:97], v[134:137], v[212:215], v[94:97]
	v_mfma_f32_16x16x32_bf16 v[90:93], v[152:155], v[212:215], v[90:93]
	v_mfma_f32_16x16x32_bf16 v[78:81], v[134:137], v[220:223], v[78:81]
	v_mfma_f32_16x16x32_bf16 v[74:77], v[152:155], v[220:223], v[74:77]
	v_mfma_f32_16x16x32_bf16 v[118:121], v[162:165], v[186:189], v[118:121]
	v_mfma_f32_16x16x32_bf16 v[114:117], v[170:173], v[186:189], v[114:117]
	v_mfma_f32_16x16x32_bf16 v[102:105], v[162:165], v[194:197], v[102:105]
	v_mfma_f32_16x16x32_bf16 v[98:101], v[170:173], v[194:197], v[98:101]
	v_mfma_f32_16x16x32_bf16 v[86:89], v[162:165], v[208:211], v[86:89]
	v_mfma_f32_16x16x32_bf16 v[82:85], v[170:173], v[208:211], v[82:85]
	v_mfma_f32_16x16x32_bf16 v[70:73], v[162:165], v[216:219], v[70:73]
	v_mfma_f32_16x16x32_bf16 v[66:69], v[170:173], v[216:219], v[66:69]
	v_mfma_f32_16x16x32_bf16 v[118:121], v[166:169], v[190:193], v[118:121]
	v_mfma_f32_16x16x32_bf16 v[114:117], v[182:185], v[190:193], v[114:117]
	v_mfma_f32_16x16x32_bf16 v[102:105], v[166:169], v[204:207], v[102:105]
	v_mfma_f32_16x16x32_bf16 v[98:101], v[182:185], v[204:207], v[98:101]
	v_mfma_f32_16x16x32_bf16 v[86:89], v[166:169], v[212:215], v[86:89]
	v_mfma_f32_16x16x32_bf16 v[82:85], v[182:185], v[212:215], v[82:85]
	v_mfma_f32_16x16x32_bf16 v[70:73], v[166:169], v[220:223], v[70:73]
	v_mfma_f32_16x16x32_bf16 v[66:69], v[182:185], v[220:223], v[66:69]
	s_barrier
; #define PG8_STAGE(bufoff, gbase, voff) do { _Pragma("unroll") for (int _i = 0; _i < 2; ++_i) \
;         __builtin_amdgcn_global_load_lds((const unsigned*)((const char*)(gbase) + (voff)[_i]), (PG8_LAS unsigned*)(lds + (bufoff) + ldsw + _i * 8192), 16, 0, 0); } while (0)
; #define PG8_LDA(dst, b, h) do { _Pragma("unroll") for (int m = 0; m < 4; ++m) _Pragma("unroll") for (int k = 0; k < 2; ++k) dst[m][k] = *(const PG8_LAS bf16x8*)(lds + PG8_SA(b, h) + aoff + m * 2048 + k * 1024); } while (0)
; #define PG8_WAIT_V(n) asm volatile("s_waitcnt vmcnt(" #n ")" ::: "memory")
; #define PG8_WAIT_L(n) asm volatile("s_waitcnt lgkmcnt(" #n ")" ::: "memory")
; #define PG8_BAR __builtin_amdgcn_s_barrier()
; #define PG8_SCHED __builtin_amdgcn_sched_barrier(0)
; template <class Epi, class Sched, bool ALIGN_EPI = false, bool SP2 = false, bool F16 = false>
; __device__ __forceinline__ void gemm_phase(PG8_LAS unsigned char* lds, const Gemm g, const Sched& S, const Epi& E) {
;     ...
;         for (int t = 0; t < nt; t += 2) {
;     ...
;             PG8_LDA(At, 1, 1); PG8_STAGE(PG8_SB(1, 0), b3, voffB); PG8_STAGE(PG8_SB(1, 1), b3 + hstepB, voffB); PG8_STAGE(PG8_SA(1, 0), a3, voffA);
;             PG8_WAIT_V(8); PG8_WAIT_L(0); PG8_BAR; PG8_MMA(1, 0, At, B0); PG8_MMA(1, 1, At, B1); PG8_BAR; PG8_SCHED;
	s_setprio 0
	s_add_i32 s54, s82, s2
	v_lshl_add_u64 v[156:157], v[156:157], 0, s[92:93]
	s_mov_b32 m0, s54
	ds_read_b128 v[186:189], v160 offset:49152
	ds_read_b128 v[190:193], v160 offset:50176
	ds_read_b128 v[194:197], v160 offset:51200
	ds_read_b128 v[204:207], v160 offset:52224
	ds_read_b128 v[208:211], v160 offset:53248
	ds_read_b128 v[212:215], v160 offset:54272
	ds_read_b128 v[216:219], v160 offset:55296
	ds_read_b128 v[220:223], v160 offset:56320
	global_load_lds_dwordx4 v[156:157], off
	v_lshl_add_u64 v[156:157], v[176:177], 0, s[92:93]
	s_add_i32 m0, s54, 0x2000
	s_add_i32 s54, s83, s2
	global_load_lds_dwordx4 v[156:157], off
	v_lshl_add_u64 v[156:157], v[224:225], 0, s[92:93]
	s_mov_b32 m0, s54
	s_nop 0
	global_load_lds_dwordx4 v[156:157], off
	v_lshl_add_u64 v[156:157], v[226:227], 0, s[92:93]
	s_add_i32 m0, s54, 0x2000
	s_nop 0
	global_load_lds_dwordx4 v[156:157], off
	v_lshl_add_u64 v[156:157], v[228:229], 0, s[92:93]
	s_mov_b32 m0, s33
	s_nop 0
	global_load_lds_dwordx4 v[156:157], off
	v_lshl_add_u64 v[156:157], v[230:231], 0, s[92:93]
	s_mov_b32 m0, s35
	s_nop 0
	global_load_lds_dwordx4 v[156:157], off
	s_waitcnt vmcnt(8)
	s_waitcnt lgkmcnt(0)
	s_setprio 1
	s_barrier
	v_mfma_f32_16x16x32_bf16 v[62:65], v[130:133], v[186:189], v[62:65]
	v_mfma_f32_16x16x32_bf16 v[58:61], v[148:151], v[186:189], v[58:61]
	v_mfma_f32_16x16x32_bf16 v[46:49], v[130:133], v[194:197], v[46:49]
	v_mfma_f32_16x16x32_bf16 v[42:45], v[148:151], v[194:197], v[42:45]
	v_mfma_f32_16x16x32_bf16 v[30:33], v[130:133], v[208:211], v[30:33]
	v_mfma_f32_16x16x32_bf16 v[26:29], v[148:151], v[208:211], v[26:29]
	v_mfma_f32_16x16x32_bf16 v[14:17], v[130:133], v[216:219], v[14:17]
	v_mfma_f32_16x16x32_bf16 v[10:13], v[148:151], v[216:219], v[10:13]
	v_mfma_f32_16x16x32_bf16 v[62:65], v[134:137], v[190:193], v[62:65]
	v_mfma_f32_16x16x32_bf16 v[58:61], v[152:155], v[190:193], v[58:61]
	v_mfma_f32_16x16x32_bf16 v[46:49], v[134:137], v[204:207], v[46:49]
	v_mfma_f32_16x16x32_bf16 v[42:45], v[152:155], v[204:207], v[42:45]
	v_mfma_f32_16x16x32_bf16 v[30:33], v[134:137], v[212:215], v[30:33]
	v_mfma_f32_16x16x32_bf16 v[26:29], v[152:155], v[212:215], v[26:29]
	v_mfma_f32_16x16x32_bf16 v[14:17], v[134:137], v[220:223], v[14:17]
	v_mfma_f32_16x16x32_bf16 v[10:13], v[152:155], v[220:223], v[10:13]
	v_mfma_f32_16x16x32_bf16 v[54:57], v[162:165], v[186:189], v[54:57]
	v_mfma_f32_16x16x32_bf16 v[50:53], v[170:173], v[186:189], v[50:53]
	v_mfma_f32_16x16x32_bf16 v[38:41], v[162:165], v[194:197], v[38:41]
	v_mfma_f32_16x16x32_bf16 v[34:37], v[170:173], v[194:197], v[34:37]
	v_mfma_f32_16x16x32_bf16 v[22:25], v[162:165], v[208:211], v[22:25]
	v_mfma_f32_16x16x32_bf16 v[18:21], v[170:173], v[208:211], v[18:21]
	v_mfma_f32_16x16x32_bf16 v[6:9], v[162:165], v[216:219], v[6:9]
	v_mfma_f32_16x16x32_bf16 v[2:5], v[170:173], v[216:219], v[2:5]
	v_mfma_f32_16x16x32_bf16 v[54:57], v[166:169], v[190:193], v[54:57]
	v_mfma_f32_16x16x32_bf16 v[50:53], v[182:185], v[190:193], v[50:53]
	v_mfma_f32_16x16x32_bf16 v[38:41], v[166:169], v[204:207], v[38:41]
	v_mfma_f32_16x16x32_bf16 v[34:37], v[182:185], v[204:207], v[34:37]
	v_mfma_f32_16x16x32_bf16 v[22:25], v[166:169], v[212:215], v[22:25]
	v_mfma_f32_16x16x32_bf16 v[18:21], v[182:185], v[212:215], v[18:21]
	v_mfma_f32_16x16x32_bf16 v[6:9], v[166:169], v[220:223], v[6:9]
	v_mfma_f32_16x16x32_bf16 v[2:5], v[182:185], v[220:223], v[2:5]
	s_barrier
	s_setprio 0
	s_add_u32 s52, s52, 0x100
	s_addc_u32 s53, s53, 0
	s_add_u32 s79, s79, 0x100
	s_addc_u32 s80, s80, 0
	s_cmp_ge_u32 s81, s65
	s_mov_b32 s54, s81
	s_cbranch_scc0 .LBB0_345

; #define PG8_STAGE(bufoff, gbase, voff) do { _Pragma("unroll") for (int _i = 0; _i < 2; ++_i) \
;         __builtin_amdgcn_global_load_lds((const unsigned*)((const char*)(gbase) + (voff)[_i]), (PG8_LAS unsigned*)(lds + (bufoff) + ldsw + _i * 8192), 16, 0, 0); } while (0)
; #define PG8_LDA(dst, b, h) do { _Pragma("unroll") for (int m = 0; m < 4; ++m) _Pragma("unroll") for (int k = 0; k < 2; ++k) dst[m][k] = *(const PG8_LAS bf16x8*)(lds + PG8_SA(b, h) + aoff + m * 2048 + k * 1024); } while (0)
; #define PG8_LDB(dst, b, h) do { _Pragma("unroll") for (int n = 0; n < 2; ++n) _Pragma("unroll") for (int k = 0; k < 2; ++k) dst[n][k] = *(const PG8_LAS bf16x8*)(lds + PG8_SB(b, h) + boff + n * 2048 + k * 1024); } while (0)
; #define PG8_WAIT_V(n) asm volatile("s_waitcnt vmcnt(" #n ")" ::: "memory")
; #define PG8_WAIT_L(n) asm volatile("s_waitcnt lgkmcnt(" #n ")" ::: "memory")
; #define PG8_BAR __builtin_amdgcn_s_barrier()
; #define PG8_SCHED __builtin_amdgcn_sched_barrier(0)
; template <class Epi, class Sched, bool ALIGN_EPI = false, bool SP2 = false, bool F16 = false>
; __device__ __forceinline__ void gemm_phase(PG8_LAS unsigned char* lds, const Gemm g, const Sched& S, const Epi& E) {
;     ...
;             const bool last = (t == nt - 2);
;             const char* a1 = cA + (size_t)(t + 1) * kstep;
;             const char* a2 = last ? nA : cA + (size_t)(t + 2) * kstep; const char* b2 = last ? nB : cB + (size_t)(t + 2) * kstep;
;             const char* a3 = a2 + kstep; const char* b3 = b2 + kstep;
;             if (last && has_next) S.a_ready(nxt);
;             if constexpr (SP2) {
;             PG8_LDB(B0, 0, 0); PG8_LDB(B1, 0, 1); PG8_SCHED; PG8_LDA(At, 0, 0); PG8_STAGE(PG8_SA(1, 1), a1 + hstepA, voffA);
;             PG8_WAIT_V(8); PG8_WAIT_L(0); PG8_BAR; PG8_MMA(0, 0, At, B0); PG8_MMA(0, 1, At, B1); PG8_BAR; PG8_SCHED;
;             PG8_LDA(At, 0, 1); PG8_STAGE(PG8_SB(0, 0), b2, voffB); PG8_STAGE(PG8_SB(0, 1), b2 + hstepB, voffB); PG8_STAGE(PG8_SA(0, 0), a2, voffA);
.Lpk_bf:
	s_add_i32 s78, s72, 2
	s_add_u32 s79, s46, 0x80
	s_addc_u32 s73, s47, 0
	s_add_i32 vcc_lo, 0, 0x10000
	s_cmp_eq_u32 s74, s72
	s_cselect_b32 s73, s55, s73
	s_cselect_b32 s72, s54, s79
	s_cselect_b32 s95, s53, s24
	s_cselect_b32 s94, s52, s13
	s_add_i32 s79, 0, 0x14000
	v_add_u32_e32 v142, vcc_lo, v163
	v_add_u32_e32 v172, s79, v163
	ds_read_b128 v[130:133], v142
	ds_read_b128 v[134:137], v142 offset:1024
	ds_read_b128 v[138:141], v142 offset:2048
	ds_read_b128 v[142:145], v142 offset:3072
	ds_read_b128 v[146:149], v172
	ds_read_b128 v[150:153], v172 offset:1024
	ds_read_b128 v[182:185], v172 offset:2048
	ds_read_b128 v[186:189], v172 offset:3072
	s_add_i32 m0, s36, 0xc000
	ds_read_b128 v[190:193], v204
	ds_read_b128 v[194:197], v204 offset:1024
	ds_read_b128 v[206:209], v204 offset:2048
	ds_read_b128 v[210:213], v204 offset:3072
	ds_read_b128 v[214:217], v204 offset:4096
	ds_read_b128 v[218:221], v204 offset:5120
	ds_read_b128 v[222:225], v204 offset:6144
	ds_read_b128 v[226:229], v204 offset:7168
	global_load_lds_dwordx4 v168, s[46:47]
	s_add_i32 m0, s36, 0xe000
	s_nop 0
	global_load_lds_dwordx4 v170, s[46:47]
	s_waitcnt vmcnt(8)
	s_waitcnt lgkmcnt(0)
	s_setprio 1
	s_barrier
	v_mfma_f32_16x16x32_bf16 v[122:125], v[130:133], v[190:193], 0
	v_mfma_f32_16x16x32_bf16 v[126:129], v[138:141], v[190:193], 0
	v_mfma_f32_16x16x32_bf16 v[110:113], v[130:133], v[206:209], 0
	v_mfma_f32_16x16x32_bf16 v[106:109], v[138:141], v[206:209], 0
	v_mfma_f32_16x16x32_bf16 v[94:97], v[130:133], v[214:217], 0
	v_mfma_f32_16x16x32_bf16 v[90:93], v[138:141], v[214:217], 0
	v_mfma_f32_16x16x32_bf16 v[78:81], v[130:133], v[222:225], 0
	v_mfma_f32_16x16x32_bf16 v[74:77], v[138:141], v[222:225], 0
	v_mfma_f32_16x16x32_bf16 v[122:125], v[134:137], v[194:197], v[122:125]
	v_mfma_f32_16x16x32_bf16 v[126:129], v[142:145], v[194:197], v[126:129]
	v_mfma_f32_16x16x32_bf16 v[110:113], v[134:137], v[210:213], v[110:113]
	v_mfma_f32_16x16x32_bf16 v[106:109], v[142:145], v[210:213], v[106:109]
	v_mfma_f32_16x16x32_bf16 v[94:97], v[134:137], v[218:221], v[94:97]
	v_mfma_f32_16x16x32_bf16 v[90:93], v[142:145], v[218:221], v[90:93]
	v_mfma_f32_16x16x32_bf16 v[78:81], v[134:137], v[226:229], v[78:81]
	v_mfma_f32_16x16x32_bf16 v[74:77], v[142:145], v[226:229], v[74:77]
	v_mfma_f32_16x16x32_bf16 v[118:121], v[146:149], v[190:193], 0
	v_mfma_f32_16x16x32_bf16 v[114:117], v[182:185], v[190:193], 0
	v_mfma_f32_16x16x32_bf16 v[102:105], v[146:149], v[206:209], 0
	v_mfma_f32_16x16x32_bf16 v[98:101], v[182:185], v[206:209], 0
	v_mfma_f32_16x16x32_bf16 v[86:89], v[146:149], v[214:217], 0
	v_mfma_f32_16x16x32_bf16 v[82:85], v[182:185], v[214:217], 0
	v_mfma_f32_16x16x32_bf16 v[70:73], v[146:149], v[222:225], 0
	v_mfma_f32_16x16x32_bf16 v[66:69], v[182:185], v[222:225], 0
	v_mfma_f32_16x16x32_bf16 v[118:121], v[150:153], v[194:197], v[118:121]
	v_mfma_f32_16x16x32_bf16 v[114:117], v[186:189], v[194:197], v[114:117]
	v_mfma_f32_16x16x32_bf16 v[102:105], v[150:153], v[210:213], v[102:105]
	v_mfma_f32_16x16x32_bf16 v[98:101], v[186:189], v[210:213], v[98:101]
	v_mfma_f32_16x16x32_bf16 v[86:89], v[150:153], v[218:221], v[86:89]
	v_mfma_f32_16x16x32_bf16 v[82:85], v[186:189], v[218:221], v[82:85]
	v_mfma_f32_16x16x32_bf16 v[70:73], v[150:153], v[226:229], v[70:73]
	v_mfma_f32_16x16x32_bf16 v[66:69], v[186:189], v[226:229], v[66:69]
	s_barrier
	s_setprio 0
	s_add_i32 vcc_lo, vcc_lo, s75
	v_lshl_add_u64 v[172:173], s[94:95], 0, v[156:157]
	s_mov_b32 m0, vcc_lo
	ds_read_b128 v[190:193], v204 offset:16384
	ds_read_b128 v[194:197], v204 offset:17408
	ds_read_b128 v[206:209], v204 offset:18432
	ds_read_b128 v[210:213], v204 offset:19456
	ds_read_b128 v[214:217], v204 offset:20480
	ds_read_b128 v[218:221], v204 offset:21504
	ds_read_b128 v[222:225], v204 offset:22528
	ds_read_b128 v[226:229], v204 offset:23552
	global_load_lds_dwordx4 v[172:173], off
	s_add_i32 m0, vcc_lo, 0x2000
	v_lshl_add_u64 v[176:177], s[94:95], 0, v[160:161]
	s_add_u32 s94, s94, s48
	s_addc_u32 s95, s95, 0
	s_add_i32 s79, s79, s75
	global_load_lds_dwordx4 v[176:177], off
	v_lshl_add_u64 v[230:231], s[94:95], 0, v[156:157]
	s_mov_b32 m0, s79
	v_lshl_add_u64 v[232:233], s[94:95], 0, v[160:161]
	global_load_lds_dwordx4 v[230:231], off
	s_add_i32 m0, s79, 0x2000
	v_lshl_add_u64 v[234:235], s[72:73], 0, v[154:155]
	global_load_lds_dwordx4 v[232:233], off
	s_mov_b32 m0, s36
	v_lshl_add_u64 v[236:237], s[72:73], 0, v[158:159]
	global_load_lds_dwordx4 v[234:235], off
	s_mov_b32 m0, s37
	s_nop 0
	global_load_lds_dwordx4 v[236:237], off
	s_waitcnt vmcnt(8)
	s_waitcnt lgkmcnt(0)
	s_setprio 1
	s_barrier
; #define PG8_STAGE(bufoff, gbase, voff) do { _Pragma("unroll") for (int _i = 0; _i < 2; ++_i) \
;         __builtin_amdgcn_global_load_lds((const unsigned*)((const char*)(gbase) + (voff)[_i]), (PG8_LAS unsigned*)(lds + (bufoff) + ldsw + _i * 8192), 16, 0, 0); } while (0)
; #define PG8_LDA(dst, b, h) do { _Pragma("unroll") for (int m = 0; m < 4; ++m) _Pragma("unroll") for (int k = 0; k < 2; ++k) dst[m][k] = *(const PG8_LAS bf16x8*)(lds + PG8_SA(b, h) + aoff + m * 2048 + k * 1024); } while (0)
; #define PG8_LDB(dst, b, h) do { _Pragma("unroll") for (int n = 0; n < 2; ++n) _Pragma("unroll") for (int k = 0; k < 2; ++k) dst[n][k] = *(const PG8_LAS bf16x8*)(lds + PG8_SB(b, h) + boff + n * 2048 + k * 1024); } while (0)
; #define PG8_WAIT_V(n) asm volatile("s_waitcnt vmcnt(" #n ")" ::: "memory")
; #define PG8_WAIT_L(n) asm volatile("s_waitcnt lgkmcnt(" #n ")" ::: "memory")
; #define PG8_BAR __builtin_amdgcn_s_barrier()
; #define PG8_SCHED __builtin_amdgcn_sched_barrier(0)
; template <class Epi, class Sched, bool ALIGN_EPI = false, bool SP2 = false, bool F16 = false>
; __device__ __forceinline__ void gemm_phase(PG8_LAS unsigned char* lds, const Gemm g, const Sched& S, const Epi& E) {
;     ...
;             PG8_WAIT_V(8); PG8_WAIT_L(0); PG8_BAR; PG8_MMA(1, 0, At, B0); PG8_MMA(1, 1, At, B1); PG8_BAR; PG8_SCHED;
;             PG8_LDB(B0, 1, 0); PG8_LDB(B1, 1, 1); PG8_SCHED; PG8_LDA(At, 1, 0); PG8_STAGE(PG8_SA(0, 1), a2 + hstepA, voffA);
;             PG8_WAIT_V(8); PG8_WAIT_L(0); PG8_BAR; PG8_MMA(0, 0, At, B0); PG8_MMA(0, 1, At, B1); PG8_BAR; PG8_SCHED;
	v_mfma_f32_16x16x32_bf16 v[62:65], v[130:133], v[190:193], 0
	v_mfma_f32_16x16x32_bf16 v[58:61], v[138:141], v[190:193], 0
	v_mfma_f32_16x16x32_bf16 v[46:49], v[130:133], v[206:209], 0
	v_mfma_f32_16x16x32_bf16 v[42:45], v[138:141], v[206:209], 0
	v_mfma_f32_16x16x32_bf16 v[30:33], v[130:133], v[214:217], 0
	v_mfma_f32_16x16x32_bf16 v[26:29], v[138:141], v[214:217], 0
	v_mfma_f32_16x16x32_bf16 v[14:17], v[130:133], v[222:225], 0
	v_mfma_f32_16x16x32_bf16 v[10:13], v[138:141], v[222:225], 0
	v_mfma_f32_16x16x32_bf16 v[62:65], v[134:137], v[194:197], v[62:65]
	v_mfma_f32_16x16x32_bf16 v[58:61], v[142:145], v[194:197], v[58:61]
	v_mfma_f32_16x16x32_bf16 v[46:49], v[134:137], v[210:213], v[46:49]
	v_mfma_f32_16x16x32_bf16 v[42:45], v[142:145], v[210:213], v[42:45]
	v_mfma_f32_16x16x32_bf16 v[30:33], v[134:137], v[218:221], v[30:33]
	v_mfma_f32_16x16x32_bf16 v[26:29], v[142:145], v[218:221], v[26:29]
	v_mfma_f32_16x16x32_bf16 v[14:17], v[134:137], v[226:229], v[14:17]
	v_mfma_f32_16x16x32_bf16 v[10:13], v[142:145], v[226:229], v[10:13]
	v_mfma_f32_16x16x32_bf16 v[54:57], v[146:149], v[190:193], 0
	v_mfma_f32_16x16x32_bf16 v[50:53], v[182:185], v[190:193], 0
	v_mfma_f32_16x16x32_bf16 v[38:41], v[146:149], v[206:209], 0
	v_mfma_f32_16x16x32_bf16 v[34:37], v[182:185], v[206:209], 0
	v_mfma_f32_16x16x32_bf16 v[22:25], v[146:149], v[214:217], 0
	v_mfma_f32_16x16x32_bf16 v[18:21], v[182:185], v[214:217], 0
	v_mfma_f32_16x16x32_bf16 v[6:9], v[146:149], v[222:225], 0
	v_mfma_f32_16x16x32_bf16 v[2:5], v[182:185], v[222:225], 0
	v_mfma_f32_16x16x32_bf16 v[54:57], v[150:153], v[194:197], v[54:57]
	v_mfma_f32_16x16x32_bf16 v[50:53], v[186:189], v[194:197], v[50:53]
	v_mfma_f32_16x16x32_bf16 v[38:41], v[150:153], v[210:213], v[38:41]
	v_mfma_f32_16x16x32_bf16 v[34:37], v[186:189], v[210:213], v[34:37]
	v_mfma_f32_16x16x32_bf16 v[22:25], v[150:153], v[218:221], v[22:25]
	v_mfma_f32_16x16x32_bf16 v[18:21], v[186:189], v[218:221], v[18:21]
	v_mfma_f32_16x16x32_bf16 v[6:9], v[150:153], v[226:229], v[6:9]
	v_mfma_f32_16x16x32_bf16 v[2:5], v[186:189], v[226:229], v[2:5]
	s_barrier
	s_setprio 0
	s_add_i32 s79, 0, 0x18000
	s_add_i32 s94, 0, 0x1c000
	v_add_u32_e32 v142, s79, v163
	v_add_u32_e32 v174, s94, v163
	ds_read_b128 v[130:133], v142
	ds_read_b128 v[134:137], v142 offset:1024
	ds_read_b128 v[138:141], v142 offset:2048
	ds_read_b128 v[142:145], v142 offset:3072
	ds_read_b128 v[146:149], v174
	ds_read_b128 v[150:153], v174 offset:1024
	ds_read_b128 v[182:185], v174 offset:2048
	ds_read_b128 v[186:189], v174 offset:3072
	s_add_u32 s72, s72, s8
	s_addc_u32 s73, s73, 0
	s_mov_b32 m0, s35
	ds_read_b128 v[190:193], v204 offset:32768
	ds_read_b128 v[194:197], v204 offset:33792
	ds_read_b128 v[206:209], v204 offset:34816
	ds_read_b128 v[210:213], v204 offset:35840
	ds_read_b128 v[214:217], v204 offset:36864
	ds_read_b128 v[218:221], v204 offset:37888
	ds_read_b128 v[222:225], v204 offset:38912
	ds_read_b128 v[226:229], v204 offset:39936
	global_load_lds_dwordx4 v154, s[72:73]
	s_mov_b32 m0, s2
	s_nop 0
	global_load_lds_dwordx4 v158, s[72:73]
	s_waitcnt vmcnt(8)
	s_waitcnt lgkmcnt(0)
	s_setprio 1
	s_barrier
	v_mfma_f32_16x16x32_bf16 v[122:125], v[130:133], v[190:193], v[122:125]
	v_mfma_f32_16x16x32_bf16 v[126:129], v[138:141], v[190:193], v[126:129]
	v_mfma_f32_16x16x32_bf16 v[110:113], v[130:133], v[206:209], v[110:113]
	v_mfma_f32_16x16x32_bf16 v[106:109], v[138:141], v[206:209], v[106:109]
	v_mfma_f32_16x16x32_bf16 v[94:97], v[130:133], v[214:217], v[94:97]
	v_mfma_f32_16x16x32_bf16 v[90:93], v[138:141], v[214:217], v[90:93]
	v_mfma_f32_16x16x32_bf16 v[78:81], v[130:133], v[222:225], v[78:81]
	v_mfma_f32_16x16x32_bf16 v[74:77], v[138:141], v[222:225], v[74:77]
	v_mfma_f32_16x16x32_bf16 v[122:125], v[134:137], v[194:197], v[122:125]
	v_mfma_f32_16x16x32_bf16 v[126:129], v[142:145], v[194:197], v[126:129]
	v_mfma_f32_16x16x32_bf16 v[110:113], v[134:137], v[210:213], v[110:113]
	v_mfma_f32_16x16x32_bf16 v[106:109], v[142:145], v[210:213], v[106:109]
	v_mfma_f32_16x16x32_bf16 v[94:97], v[134:137], v[218:221], v[94:97]
	v_mfma_f32_16x16x32_bf16 v[90:93], v[142:145], v[218:221], v[90:93]
	v_mfma_f32_16x16x32_bf16 v[78:81], v[134:137], v[226:229], v[78:81]
	v_mfma_f32_16x16x32_bf16 v[74:77], v[142:145], v[226:229], v[74:77]
	v_mfma_f32_16x16x32_bf16 v[118:121], v[146:149], v[190:193], v[118:121]
	v_mfma_f32_16x16x32_bf16 v[114:117], v[182:185], v[190:193], v[114:117]
	v_mfma_f32_16x16x32_bf16 v[102:105], v[146:149], v[206:209], v[102:105]
	v_mfma_f32_16x16x32_bf16 v[98:101], v[182:185], v[206:209], v[98:101]
	v_mfma_f32_16x16x32_bf16 v[86:89], v[146:149], v[214:217], v[86:89]
	v_mfma_f32_16x16x32_bf16 v[82:85], v[182:185], v[214:217], v[82:85]
	v_mfma_f32_16x16x32_bf16 v[70:73], v[146:149], v[222:225], v[70:73]
	v_mfma_f32_16x16x32_bf16 v[66:69], v[182:185], v[222:225], v[66:69]
	v_mfma_f32_16x16x32_bf16 v[118:121], v[150:153], v[194:197], v[118:121]
	v_mfma_f32_16x16x32_bf16 v[114:117], v[186:189], v[194:197], v[114:117]
	v_mfma_f32_16x16x32_bf16 v[102:105], v[150:153], v[210:213], v[102:105]
	v_mfma_f32_16x16x32_bf16 v[98:101], v[186:189], v[210:213], v[98:101]
	v_mfma_f32_16x16x32_bf16 v[86:89], v[150:153], v[218:221], v[86:89]
	v_mfma_f32_16x16x32_bf16 v[82:85], v[186:189], v[218:221], v[82:85]
	v_mfma_f32_16x16x32_bf16 v[70:73], v[150:153], v[226:229], v[70:73]
	v_mfma_f32_16x16x32_bf16 v[66:69], v[186:189], v[226:229], v[66:69]
	s_barrier
; #define PG8_STAGE(bufoff, gbase, voff) do { _Pragma("unroll") for (int _i = 0; _i < 2; ++_i) \
;         __builtin_amdgcn_global_load_lds((const unsigned*)((const char*)(gbase) + (voff)[_i]), (PG8_LAS unsigned*)(lds + (bufoff) + ldsw + _i * 8192), 16, 0, 0); } while (0)
; #define PG8_LDA(dst, b, h) do { _Pragma("unroll") for (int m = 0; m < 4; ++m) _Pragma("unroll") for (int k = 0; k < 2; ++k) dst[m][k] = *(const PG8_LAS bf16x8*)(lds + PG8_SA(b, h) + aoff + m * 2048 + k * 1024); } while (0)
; #define PG8_LDB(dst, b, h) do { _Pragma("unroll") for (int n = 0; n < 2; ++n) _Pragma("unroll") for (int k = 0; k < 2; ++k) dst[n][k] = *(const PG8_LAS bf16x8*)(lds + PG8_SB(b, h) + boff + n * 2048 + k * 1024); } while (0)
; #define PG8_WAIT_V(n) asm volatile("s_waitcnt vmcnt(" #n ")" ::: "memory")
; #define PG8_WAIT_L(n) asm volatile("s_waitcnt lgkmcnt(" #n ")" ::: "memory")
; #define PG8_BAR __builtin_amdgcn_s_barrier()
; #define PG8_SCHED __builtin_amdgcn_sched_barrier(0)
; template <class Epi, class Sched, bool ALIGN_EPI = false, bool SP2 = false, bool F16 = false>
; __device__ __forceinline__ void gemm_phase(PG8_LAS unsigned char* lds, const Gemm g, const Sched& S, const Epi& E) {
;     ...
;         for (int t = 0; t < nt; t += 2) {
;             const bool last = (t == nt - 2);
;             const char* a1 = cA + (size_t)(t + 1) * kstep;
;             const char* a2 = last ? nA : cA + (size_t)(t + 2) * kstep; const char* b2 = last ? nB : cB + (size_t)(t + 2) * kstep;
;             const char* a3 = a2 + kstep; const char* b3 = b2 + kstep;
;             if (last && has_next) S.a_ready(nxt);
;             if constexpr (SP2) {
;             PG8_LDB(B0, 0, 0); PG8_LDB(B1, 0, 1); PG8_SCHED; PG8_LDA(At, 0, 0); PG8_STAGE(PG8_SA(1, 1), a1 + hstepA, voffA);
;             PG8_WAIT_V(8); PG8_WAIT_L(0); PG8_BAR; PG8_MMA(0, 0, At, B0); PG8_MMA(0, 1, At, B1); PG8_BAR; PG8_SCHED;
;     ...
;             PG8_LDA(At, 1, 1); PG8_STAGE(PG8_SB(1, 0), b3, voffB); PG8_STAGE(PG8_SB(1, 1), b3 + hstepB, voffB); PG8_STAGE(PG8_SA(1, 0), a3, voffA);
;             PG8_WAIT_V(8); PG8_WAIT_L(0); PG8_BAR; PG8_MMA(1, 0, At, B0); PG8_MMA(1, 1, At, B1); PG8_BAR; PG8_SCHED;
	s_setprio 0
	s_add_i32 s72, s79, s75
	v_lshl_add_u64 v[172:173], v[172:173], 0, s[92:93]
	s_mov_b32 m0, s72
	ds_read_b128 v[190:193], v204 offset:49152
	ds_read_b128 v[194:197], v204 offset:50176
	ds_read_b128 v[206:209], v204 offset:51200
	ds_read_b128 v[210:213], v204 offset:52224
	ds_read_b128 v[214:217], v204 offset:53248
	ds_read_b128 v[218:221], v204 offset:54272
	ds_read_b128 v[222:225], v204 offset:55296
	ds_read_b128 v[226:229], v204 offset:56320
	global_load_lds_dwordx4 v[172:173], off
	v_lshl_add_u64 v[172:173], v[176:177], 0, s[92:93]
	s_add_i32 m0, s72, 0x2000
	s_add_i32 s72, s94, s75
	global_load_lds_dwordx4 v[172:173], off
	v_lshl_add_u64 v[172:173], v[230:231], 0, s[92:93]
	s_mov_b32 m0, s72
	s_nop 0
	global_load_lds_dwordx4 v[172:173], off
	v_lshl_add_u64 v[172:173], v[232:233], 0, s[92:93]
	s_add_i32 m0, s72, 0x2000
	s_nop 0
	global_load_lds_dwordx4 v[172:173], off
	v_lshl_add_u64 v[172:173], v[234:235], 0, s[92:93]
	s_mov_b32 m0, s22
	s_nop 0
	global_load_lds_dwordx4 v[172:173], off
	v_lshl_add_u64 v[172:173], v[236:237], 0, s[92:93]
	s_mov_b32 m0, s23
	s_nop 0
	global_load_lds_dwordx4 v[172:173], off
	s_waitcnt vmcnt(8)
	s_waitcnt lgkmcnt(0)
	s_setprio 1
	s_barrier
	v_mfma_f32_16x16x32_bf16 v[62:65], v[130:133], v[190:193], v[62:65]
	v_mfma_f32_16x16x32_bf16 v[58:61], v[138:141], v[190:193], v[58:61]
	v_mfma_f32_16x16x32_bf16 v[46:49], v[130:133], v[206:209], v[46:49]
	v_mfma_f32_16x16x32_bf16 v[42:45], v[138:141], v[206:209], v[42:45]
	v_mfma_f32_16x16x32_bf16 v[30:33], v[130:133], v[214:217], v[30:33]
	v_mfma_f32_16x16x32_bf16 v[26:29], v[138:141], v[214:217], v[26:29]
	v_mfma_f32_16x16x32_bf16 v[14:17], v[130:133], v[222:225], v[14:17]
	v_mfma_f32_16x16x32_bf16 v[10:13], v[138:141], v[222:225], v[10:13]
	v_mfma_f32_16x16x32_bf16 v[62:65], v[134:137], v[194:197], v[62:65]
	v_mfma_f32_16x16x32_bf16 v[58:61], v[142:145], v[194:197], v[58:61]
	v_mfma_f32_16x16x32_bf16 v[46:49], v[134:137], v[210:213], v[46:49]
	v_mfma_f32_16x16x32_bf16 v[42:45], v[142:145], v[210:213], v[42:45]
	v_mfma_f32_16x16x32_bf16 v[30:33], v[134:137], v[218:221], v[30:33]
	v_mfma_f32_16x16x32_bf16 v[26:29], v[142:145], v[218:221], v[26:29]
	v_mfma_f32_16x16x32_bf16 v[14:17], v[134:137], v[226:229], v[14:17]
	v_mfma_f32_16x16x32_bf16 v[10:13], v[142:145], v[226:229], v[10:13]
	v_mfma_f32_16x16x32_bf16 v[54:57], v[146:149], v[190:193], v[54:57]
	v_mfma_f32_16x16x32_bf16 v[50:53], v[182:185], v[190:193], v[50:53]
	v_mfma_f32_16x16x32_bf16 v[38:41], v[146:149], v[206:209], v[38:41]
	v_mfma_f32_16x16x32_bf16 v[34:37], v[182:185], v[206:209], v[34:37]
	v_mfma_f32_16x16x32_bf16 v[22:25], v[146:149], v[214:217], v[22:25]
	v_mfma_f32_16x16x32_bf16 v[18:21], v[182:185], v[214:217], v[18:21]
	v_mfma_f32_16x16x32_bf16 v[6:9], v[146:149], v[222:225], v[6:9]
	v_mfma_f32_16x16x32_bf16 v[2:5], v[182:185], v[222:225], v[2:5]
	v_mfma_f32_16x16x32_bf16 v[54:57], v[150:153], v[194:197], v[54:57]
	v_mfma_f32_16x16x32_bf16 v[50:53], v[186:189], v[194:197], v[50:53]
	v_mfma_f32_16x16x32_bf16 v[38:41], v[150:153], v[210:213], v[38:41]
	v_mfma_f32_16x16x32_bf16 v[34:37], v[186:189], v[210:213], v[34:37]
	v_mfma_f32_16x16x32_bf16 v[22:25], v[150:153], v[218:221], v[22:25]
	v_mfma_f32_16x16x32_bf16 v[18:21], v[186:189], v[218:221], v[18:21]
	v_mfma_f32_16x16x32_bf16 v[6:9], v[150:153], v[226:229], v[6:9]
	v_mfma_f32_16x16x32_bf16 v[2:5], v[186:189], v[226:229], v[2:5]
	s_barrier
	s_setprio 0
	s_add_u32 s46, s46, 0x100
	s_addc_u32 s47, s47, 0
	s_add_u32 s13, s13, 0x100
	s_addc_u32 s24, s24, 0
	s_cmp_ge_u32 s78, s65
	s_mov_b32 s72, s78
	s_cbranch_scc1 .LBB0_399
.LBB0_398:
	s_add_i32 s78, s72, 2
	s_add_u32 s79, s46, 0x80
	s_addc_u32 s73, s47, 0
	s_add_i32 vcc_lo, 0, 0x10000
	s_cmp_eq_u32 s74, s72
	s_cselect_b32 s73, s55, s73
	s_cselect_b32 s72, s54, s79
	s_cselect_b32 s95, s53, s24
	s_cselect_b32 s94, s52, s13
	s_add_i32 s79, 0, 0x14000
	v_add_u32_e32 v142, vcc_lo, v163
	v_add_u32_e32 v172, s79, v163
	ds_read_b128 v[130:133], v142
	ds_read_b128 v[134:137], v142 offset:1024
	ds_read_b128 v[138:141], v142 offset:2048
	ds_read_b128 v[142:145], v142 offset:3072
	ds_read_b128 v[146:149], v172
	ds_read_b128 v[150:153], v172 offset:1024
	ds_read_b128 v[182:185], v172 offset:2048
	ds_read_b128 v[186:189], v172 offset:3072
	s_add_i32 m0, s36, 0xc000
	ds_read_b128 v[190:193], v204
	ds_read_b128 v[194:197], v204 offset:1024
	ds_read_b128 v[206:209], v204 offset:2048
	ds_read_b128 v[210:213], v204 offset:3072
	ds_read_b128 v[214:217], v204 offset:4096
	ds_read_b128 v[218:221], v204 offset:5120
	ds_read_b128 v[222:225], v204 offset:6144
	ds_read_b128 v[226:229], v204 offset:7168
	global_load_lds_dwordx4 v168, s[46:47]
	s_add_i32 m0, s36, 0xe000
	s_nop 0
	global_load_lds_dwordx4 v170, s[46:47]
	s_waitcnt vmcnt(8)
	s_waitcnt lgkmcnt(0)
	s_setprio 1
	s_barrier
; #define PG8_STAGE(bufoff, gbase, voff) do { _Pragma("unroll") for (int _i = 0; _i < 2; ++_i) \
;         __builtin_amdgcn_global_load_lds((const unsigned*)((const char*)(gbase) + (voff)[_i]), (PG8_LAS unsigned*)(lds + (bufoff) + ldsw + _i * 8192), 16, 0, 0); } while (0)
; #define PG8_LDA(dst, b, h) do { _Pragma("unroll") for (int m = 0; m < 4; ++m) _Pragma("unroll") for (int k = 0; k < 2; ++k) dst[m][k] = *(const PG8_LAS bf16x8*)(lds + PG8_SA(b, h) + aoff + m * 2048 + k * 1024); } while (0)
; #define PG8_WAIT_V(n) asm volatile("s_waitcnt vmcnt(" #n ")" ::: "memory")
; #define PG8_WAIT_L(n) asm volatile("s_waitcnt lgkmcnt(" #n ")" ::: "memory")
; #define PG8_BAR __builtin_amdgcn_s_barrier()
; #define PG8_SCHED __builtin_amdgcn_sched_barrier(0)
; template <class Epi, class Sched, bool ALIGN_EPI = false, bool SP2 = false, bool F16 = false>
; __device__ __forceinline__ void gemm_phase(PG8_LAS unsigned char* lds, const Gemm g, const Sched& S, const Epi& E) {
;     ...
;             PG8_WAIT_V(8); PG8_WAIT_L(0); PG8_BAR; PG8_MMA(0, 0, At, B0); PG8_MMA(0, 1, At, B1); PG8_BAR; PG8_SCHED;
;             PG8_LDA(At, 0, 1); PG8_STAGE(PG8_SB(0, 0), b2, voffB); PG8_STAGE(PG8_SB(0, 1), b2 + hstepB, voffB); PG8_STAGE(PG8_SA(0, 0), a2, voffA);
;             PG8_WAIT_V(8); PG8_WAIT_L(0); PG8_BAR; PG8_MMA(1, 0, At, B0); PG8_MMA(1, 1, At, B1); PG8_BAR; PG8_SCHED;
	v_mfma_f32_16x16x32_bf16 v[122:125], v[130:133], v[190:193], v[122:125]
	v_mfma_f32_16x16x32_bf16 v[126:129], v[138:141], v[190:193], v[126:129]
	v_mfma_f32_16x16x32_bf16 v[110:113], v[130:133], v[206:209], v[110:113]
	v_mfma_f32_16x16x32_bf16 v[106:109], v[138:141], v[206:209], v[106:109]
	v_mfma_f32_16x16x32_bf16 v[94:97], v[130:133], v[214:217], v[94:97]
	v_mfma_f32_16x16x32_bf16 v[90:93], v[138:141], v[214:217], v[90:93]
	v_mfma_f32_16x16x32_bf16 v[78:81], v[130:133], v[222:225], v[78:81]
	v_mfma_f32_16x16x32_bf16 v[74:77], v[138:141], v[222:225], v[74:77]
	v_mfma_f32_16x16x32_bf16 v[122:125], v[134:137], v[194:197], v[122:125]
	v_mfma_f32_16x16x32_bf16 v[126:129], v[142:145], v[194:197], v[126:129]
	v_mfma_f32_16x16x32_bf16 v[110:113], v[134:137], v[210:213], v[110:113]
	v_mfma_f32_16x16x32_bf16 v[106:109], v[142:145], v[210:213], v[106:109]
	v_mfma_f32_16x16x32_bf16 v[94:97], v[134:137], v[218:221], v[94:97]
	v_mfma_f32_16x16x32_bf16 v[90:93], v[142:145], v[218:221], v[90:93]
	v_mfma_f32_16x16x32_bf16 v[78:81], v[134:137], v[226:229], v[78:81]
	v_mfma_f32_16x16x32_bf16 v[74:77], v[142:145], v[226:229], v[74:77]
	v_mfma_f32_16x16x32_bf16 v[118:121], v[146:149], v[190:193], v[118:121]
	v_mfma_f32_16x16x32_bf16 v[114:117], v[182:185], v[190:193], v[114:117]
	v_mfma_f32_16x16x32_bf16 v[102:105], v[146:149], v[206:209], v[102:105]
	v_mfma_f32_16x16x32_bf16 v[98:101], v[182:185], v[206:209], v[98:101]
	v_mfma_f32_16x16x32_bf16 v[86:89], v[146:149], v[214:217], v[86:89]
	v_mfma_f32_16x16x32_bf16 v[82:85], v[182:185], v[214:217], v[82:85]
	v_mfma_f32_16x16x32_bf16 v[70:73], v[146:149], v[222:225], v[70:73]
	v_mfma_f32_16x16x32_bf16 v[66:69], v[182:185], v[222:225], v[66:69]
	v_mfma_f32_16x16x32_bf16 v[118:121], v[150:153], v[194:197], v[118:121]
	v_mfma_f32_16x16x32_bf16 v[114:117], v[186:189], v[194:197], v[114:117]
	v_mfma_f32_16x16x32_bf16 v[102:105], v[150:153], v[210:213], v[102:105]
	v_mfma_f32_16x16x32_bf16 v[98:101], v[186:189], v[210:213], v[98:101]
	v_mfma_f32_16x16x32_bf16 v[86:89], v[150:153], v[218:221], v[86:89]
	v_mfma_f32_16x16x32_bf16 v[82:85], v[186:189], v[218:221], v[82:85]
	v_mfma_f32_16x16x32_bf16 v[70:73], v[150:153], v[226:229], v[70:73]
	v_mfma_f32_16x16x32_bf16 v[66:69], v[186:189], v[226:229], v[66:69]
	s_barrier
	s_setprio 0
	s_add_i32 vcc_lo, vcc_lo, s75
	v_lshl_add_u64 v[172:173], s[94:95], 0, v[156:157]
	s_mov_b32 m0, vcc_lo
	ds_read_b128 v[190:193], v204 offset:16384
	ds_read_b128 v[194:197], v204 offset:17408
	ds_read_b128 v[206:209], v204 offset:18432
	ds_read_b128 v[210:213], v204 offset:19456
	ds_read_b128 v[214:217], v204 offset:20480
	ds_read_b128 v[218:221], v204 offset:21504
	ds_read_b128 v[222:225], v204 offset:22528
	ds_read_b128 v[226:229], v204 offset:23552
	global_load_lds_dwordx4 v[172:173], off
	s_add_i32 m0, vcc_lo, 0x2000
	v_lshl_add_u64 v[176:177], s[94:95], 0, v[160:161]
	s_add_u32 s94, s94, s48
	s_addc_u32 s95, s95, 0
	s_add_i32 s79, s79, s75
	global_load_lds_dwordx4 v[176:177], off
	v_lshl_add_u64 v[230:231], s[94:95], 0, v[156:157]
	s_mov_b32 m0, s79
	v_lshl_add_u64 v[232:233], s[94:95], 0, v[160:161]
	global_load_lds_dwordx4 v[230:231], off
	s_add_i32 m0, s79, 0x2000
	v_lshl_add_u64 v[234:235], s[72:73], 0, v[154:155]
	global_load_lds_dwordx4 v[232:233], off
	s_mov_b32 m0, s36
	v_lshl_add_u64 v[236:237], s[72:73], 0, v[158:159]
	global_load_lds_dwordx4 v[234:235], off
	s_mov_b32 m0, s37
	s_nop 0
	global_load_lds_dwordx4 v[236:237], off
	s_waitcnt vmcnt(8)
	s_waitcnt lgkmcnt(0)
	s_setprio 1
	s_barrier
	v_mfma_f32_16x16x32_bf16 v[62:65], v[130:133], v[190:193], v[62:65]
	v_mfma_f32_16x16x32_bf16 v[58:61], v[138:141], v[190:193], v[58:61]
	v_mfma_f32_16x16x32_bf16 v[46:49], v[130:133], v[206:209], v[46:49]
	v_mfma_f32_16x16x32_bf16 v[42:45], v[138:141], v[206:209], v[42:45]
	v_mfma_f32_16x16x32_bf16 v[30:33], v[130:133], v[214:217], v[30:33]
	v_mfma_f32_16x16x32_bf16 v[26:29], v[138:141], v[214:217], v[26:29]
	v_mfma_f32_16x16x32_bf16 v[14:17], v[130:133], v[222:225], v[14:17]
	v_mfma_f32_16x16x32_bf16 v[10:13], v[138:141], v[222:225], v[10:13]
	v_mfma_f32_16x16x32_bf16 v[62:65], v[134:137], v[194:197], v[62:65]
	v_mfma_f32_16x16x32_bf16 v[58:61], v[142:145], v[194:197], v[58:61]
	v_mfma_f32_16x16x32_bf16 v[46:49], v[134:137], v[210:213], v[46:49]
	v_mfma_f32_16x16x32_bf16 v[42:45], v[142:145], v[210:213], v[42:45]
	v_mfma_f32_16x16x32_bf16 v[30:33], v[134:137], v[218:221], v[30:33]
	v_mfma_f32_16x16x32_bf16 v[26:29], v[142:145], v[218:221], v[26:29]
	v_mfma_f32_16x16x32_bf16 v[14:17], v[134:137], v[226:229], v[14:17]
	v_mfma_f32_16x16x32_bf16 v[10:13], v[142:145], v[226:229], v[10:13]
	v_mfma_f32_16x16x32_bf16 v[54:57], v[146:149], v[190:193], v[54:57]
	v_mfma_f32_16x16x32_bf16 v[50:53], v[182:185], v[190:193], v[50:53]
	v_mfma_f32_16x16x32_bf16 v[38:41], v[146:149], v[206:209], v[38:41]
	v_mfma_f32_16x16x32_bf16 v[34:37], v[182:185], v[206:209], v[34:37]
	v_mfma_f32_16x16x32_bf16 v[22:25], v[146:149], v[214:217], v[22:25]
	v_mfma_f32_16x16x32_bf16 v[18:21], v[182:185], v[214:217], v[18:21]
	v_mfma_f32_16x16x32_bf16 v[6:9], v[146:149], v[222:225], v[6:9]
	v_mfma_f32_16x16x32_bf16 v[2:5], v[182:185], v[222:225], v[2:5]
	v_mfma_f32_16x16x32_bf16 v[54:57], v[150:153], v[194:197], v[54:57]
	v_mfma_f32_16x16x32_bf16 v[50:53], v[186:189], v[194:197], v[50:53]
	v_mfma_f32_16x16x32_bf16 v[38:41], v[150:153], v[210:213], v[38:41]
	v_mfma_f32_16x16x32_bf16 v[34:37], v[186:189], v[210:213], v[34:37]
	v_mfma_f32_16x16x32_bf16 v[22:25], v[150:153], v[218:221], v[22:25]
	v_mfma_f32_16x16x32_bf16 v[18:21], v[186:189], v[218:221], v[18:21]
	v_mfma_f32_16x16x32_bf16 v[6:9], v[150:153], v[226:229], v[6:9]
	v_mfma_f32_16x16x32_bf16 v[2:5], v[186:189], v[226:229], v[2:5]
	s_barrier
; #define PG8_STAGE(bufoff, gbase, voff) do { _Pragma("unroll") for (int _i = 0; _i < 2; ++_i) \
;         __builtin_amdgcn_global_load_lds((const unsigned*)((const char*)(gbase) + (voff)[_i]), (PG8_LAS unsigned*)(lds + (bufoff) + ldsw + _i * 8192), 16, 0, 0); } while (0)
; #define PG8_LDA(dst, b, h) do { _Pragma("unroll") for (int m = 0; m < 4; ++m) _Pragma("unroll") for (int k = 0; k < 2; ++k) dst[m][k] = *(const PG8_LAS bf16x8*)(lds + PG8_SA(b, h) + aoff + m * 2048 + k * 1024); } while (0)
; #define PG8_LDB(dst, b, h) do { _Pragma("unroll") for (int n = 0; n < 2; ++n) _Pragma("unroll") for (int k = 0; k < 2; ++k) dst[n][k] = *(const PG8_LAS bf16x8*)(lds + PG8_SB(b, h) + boff + n * 2048 + k * 1024); } while (0)
; #define PG8_WAIT_V(n) asm volatile("s_waitcnt vmcnt(" #n ")" ::: "memory")
; #define PG8_WAIT_L(n) asm volatile("s_waitcnt lgkmcnt(" #n ")" ::: "memory")
; #define PG8_BAR __builtin_amdgcn_s_barrier()
; #define PG8_SCHED __builtin_amdgcn_sched_barrier(0)
; template <class Epi, class Sched, bool ALIGN_EPI = false, bool SP2 = false, bool F16 = false>
; __device__ __forceinline__ void gemm_phase(PG8_LAS unsigned char* lds, const Gemm g, const Sched& S, const Epi& E) {
;     ...
;             PG8_LDB(B0, 1, 0); PG8_LDB(B1, 1, 1); PG8_SCHED; PG8_LDA(At, 1, 0); PG8_STAGE(PG8_SA(0, 1), a2 + hstepA, voffA);
;             PG8_WAIT_V(8); PG8_WAIT_L(0); PG8_BAR; PG8_MMA(0, 0, At, B0); PG8_MMA(0, 1, At, B1); PG8_BAR; PG8_SCHED;
;             PG8_LDA(At, 1, 1); PG8_STAGE(PG8_SB(1, 0), b3, voffB); PG8_STAGE(PG8_SB(1, 1), b3 + hstepB, voffB); PG8_STAGE(PG8_SA(1, 0), a3, voffA);
;             PG8_WAIT_V(8); PG8_WAIT_L(0); PG8_BAR; PG8_MMA(1, 0, At, B0); PG8_MMA(1, 1, At, B1); PG8_BAR; PG8_SCHED;
	s_setprio 0
	s_add_i32 s79, 0, 0x18000
	s_add_i32 s94, 0, 0x1c000
	v_add_u32_e32 v142, s79, v163
	v_add_u32_e32 v174, s94, v163
	ds_read_b128 v[130:133], v142
	ds_read_b128 v[134:137], v142 offset:1024
	ds_read_b128 v[138:141], v142 offset:2048
	ds_read_b128 v[142:145], v142 offset:3072
	ds_read_b128 v[146:149], v174
	ds_read_b128 v[150:153], v174 offset:1024
	ds_read_b128 v[182:185], v174 offset:2048
	ds_read_b128 v[186:189], v174 offset:3072
	s_add_u32 s72, s72, s8
	s_addc_u32 s73, s73, 0
	s_mov_b32 m0, s35
	ds_read_b128 v[190:193], v204 offset:32768
	ds_read_b128 v[194:197], v204 offset:33792
	ds_read_b128 v[206:209], v204 offset:34816
	ds_read_b128 v[210:213], v204 offset:35840
	ds_read_b128 v[214:217], v204 offset:36864
	ds_read_b128 v[218:221], v204 offset:37888
	ds_read_b128 v[222:225], v204 offset:38912
	ds_read_b128 v[226:229], v204 offset:39936
	global_load_lds_dwordx4 v154, s[72:73]
	s_mov_b32 m0, s2
	s_nop 0
	global_load_lds_dwordx4 v158, s[72:73]
	s_waitcnt vmcnt(8)
	s_waitcnt lgkmcnt(0)
	s_setprio 1
	s_barrier
	v_mfma_f32_16x16x32_bf16 v[122:125], v[130:133], v[190:193], v[122:125]
	v_mfma_f32_16x16x32_bf16 v[126:129], v[138:141], v[190:193], v[126:129]
	v_mfma_f32_16x16x32_bf16 v[110:113], v[130:133], v[206:209], v[110:113]
	v_mfma_f32_16x16x32_bf16 v[106:109], v[138:141], v[206:209], v[106:109]
	v_mfma_f32_16x16x32_bf16 v[94:97], v[130:133], v[214:217], v[94:97]
	v_mfma_f32_16x16x32_bf16 v[90:93], v[138:141], v[214:217], v[90:93]
	v_mfma_f32_16x16x32_bf16 v[78:81], v[130:133], v[222:225], v[78:81]
	v_mfma_f32_16x16x32_bf16 v[74:77], v[138:141], v[222:225], v[74:77]
	v_mfma_f32_16x16x32_bf16 v[122:125], v[134:137], v[194:197], v[122:125]
	v_mfma_f32_16x16x32_bf16 v[126:129], v[142:145], v[194:197], v[126:129]
	v_mfma_f32_16x16x32_bf16 v[110:113], v[134:137], v[210:213], v[110:113]
	v_mfma_f32_16x16x32_bf16 v[106:109], v[142:145], v[210:213], v[106:109]
	v_mfma_f32_16x16x32_bf16 v[94:97], v[134:137], v[218:221], v[94:97]
	v_mfma_f32_16x16x32_bf16 v[90:93], v[142:145], v[218:221], v[90:93]
	v_mfma_f32_16x16x32_bf16 v[78:81], v[134:137], v[226:229], v[78:81]
	v_mfma_f32_16x16x32_bf16 v[74:77], v[142:145], v[226:229], v[74:77]
	v_mfma_f32_16x16x32_bf16 v[118:121], v[146:149], v[190:193], v[118:121]
	v_mfma_f32_16x16x32_bf16 v[114:117], v[182:185], v[190:193], v[114:117]
	v_mfma_f32_16x16x32_bf16 v[102:105], v[146:149], v[206:209], v[102:105]
	v_mfma_f32_16x16x32_bf16 v[98:101], v[182:185], v[206:209], v[98:101]
	v_mfma_f32_16x16x32_bf16 v[86:89], v[146:149], v[214:217], v[86:89]
	v_mfma_f32_16x16x32_bf16 v[82:85], v[182:185], v[214:217], v[82:85]
	v_mfma_f32_16x16x32_bf16 v[70:73], v[146:149], v[222:225], v[70:73]
	v_mfma_f32_16x16x32_bf16 v[66:69], v[182:185], v[222:225], v[66:69]
	v_mfma_f32_16x16x32_bf16 v[118:121], v[150:153], v[194:197], v[118:121]
	v_mfma_f32_16x16x32_bf16 v[114:117], v[186:189], v[194:197], v[114:117]
	v_mfma_f32_16x16x32_bf16 v[102:105], v[150:153], v[210:213], v[102:105]
	v_mfma_f32_16x16x32_bf16 v[98:101], v[186:189], v[210:213], v[98:101]
	v_mfma_f32_16x16x32_bf16 v[86:89], v[150:153], v[218:221], v[86:89]
	v_mfma_f32_16x16x32_bf16 v[82:85], v[186:189], v[218:221], v[82:85]
	v_mfma_f32_16x16x32_bf16 v[70:73], v[150:153], v[226:229], v[70:73]
	v_mfma_f32_16x16x32_bf16 v[66:69], v[186:189], v[226:229], v[66:69]
	s_barrier
	s_setprio 0
	s_add_i32 s72, s79, s75
	v_lshl_add_u64 v[172:173], v[172:173], 0, s[92:93]
	s_mov_b32 m0, s72
	ds_read_b128 v[190:193], v204 offset:49152
	ds_read_b128 v[194:197], v204 offset:50176
	ds_read_b128 v[206:209], v204 offset:51200
	ds_read_b128 v[210:213], v204 offset:52224
	ds_read_b128 v[214:217], v204 offset:53248
	ds_read_b128 v[218:221], v204 offset:54272
	ds_read_b128 v[222:225], v204 offset:55296
	ds_read_b128 v[226:229], v204 offset:56320
	global_load_lds_dwordx4 v[172:173], off
	v_lshl_add_u64 v[172:173], v[176:177], 0, s[92:93]
	s_add_i32 m0, s72, 0x2000
	s_add_i32 s72, s94, s75
	global_load_lds_dwordx4 v[172:173], off
	v_lshl_add_u64 v[172:173], v[230:231], 0, s[92:93]
	s_mov_b32 m0, s72
	s_nop 0
	global_load_lds_dwordx4 v[172:173], off
	v_lshl_add_u64 v[172:173], v[232:233], 0, s[92:93]
	s_add_i32 m0, s72, 0x2000
	s_nop 0
	global_load_lds_dwordx4 v[172:173], off
	v_lshl_add_u64 v[172:173], v[234:235], 0, s[92:93]
	s_mov_b32 m0, s22
	s_nop 0
	global_load_lds_dwordx4 v[172:173], off
	v_lshl_add_u64 v[172:173], v[236:237], 0, s[92:93]
	s_mov_b32 m0, s23
	s_nop 0
	global_load_lds_dwordx4 v[172:173], off
	s_waitcnt vmcnt(8)
	s_waitcnt lgkmcnt(0)
	s_setprio 1
	s_barrier
	v_mfma_f32_16x16x32_bf16 v[62:65], v[130:133], v[190:193], v[62:65]
	v_mfma_f32_16x16x32_bf16 v[58:61], v[138:141], v[190:193], v[58:61]
	v_mfma_f32_16x16x32_bf16 v[46:49], v[130:133], v[206:209], v[46:49]
	v_mfma_f32_16x16x32_bf16 v[42:45], v[138:141], v[206:209], v[42:45]
	v_mfma_f32_16x16x32_bf16 v[30:33], v[130:133], v[214:217], v[30:33]
	v_mfma_f32_16x16x32_bf16 v[26:29], v[138:141], v[214:217], v[26:29]
	v_mfma_f32_16x16x32_bf16 v[14:17], v[130:133], v[222:225], v[14:17]
	v_mfma_f32_16x16x32_bf16 v[10:13], v[138:141], v[222:225], v[10:13]
	v_mfma_f32_16x16x32_bf16 v[62:65], v[134:137], v[194:197], v[62:65]
	v_mfma_f32_16x16x32_bf16 v[58:61], v[142:145], v[194:197], v[58:61]
	v_mfma_f32_16x16x32_bf16 v[46:49], v[134:137], v[210:213], v[46:49]
	v_mfma_f32_16x16x32_bf16 v[42:45], v[142:145], v[210:213], v[42:45]
	v_mfma_f32_16x16x32_bf16 v[30:33], v[134:137], v[218:221], v[30:33]
	v_mfma_f32_16x16x32_bf16 v[26:29], v[142:145], v[218:221], v[26:29]
	v_mfma_f32_16x16x32_bf16 v[14:17], v[134:137], v[226:229], v[14:17]
	v_mfma_f32_16x16x32_bf16 v[10:13], v[142:145], v[226:229], v[10:13]
	v_mfma_f32_16x16x32_bf16 v[54:57], v[146:149], v[190:193], v[54:57]
	v_mfma_f32_16x16x32_bf16 v[50:53], v[182:185], v[190:193], v[50:53]
	v_mfma_f32_16x16x32_bf16 v[38:41], v[146:149], v[206:209], v[38:41]
	v_mfma_f32_16x16x32_bf16 v[34:37], v[182:185], v[206:209], v[34:37]
	v_mfma_f32_16x16x32_bf16 v[22:25], v[146:149], v[214:217], v[22:25]
	v_mfma_f32_16x16x32_bf16 v[18:21], v[182:185], v[214:217], v[18:21]
	v_mfma_f32_16x16x32_bf16 v[6:9], v[146:149], v[222:225], v[6:9]
	v_mfma_f32_16x16x32_bf16 v[2:5], v[182:185], v[222:225], v[2:5]
	v_mfma_f32_16x16x32_bf16 v[54:57], v[150:153], v[194:197], v[54:57]
	v_mfma_f32_16x16x32_bf16 v[50:53], v[186:189], v[194:197], v[50:53]
	v_mfma_f32_16x16x32_bf16 v[38:41], v[150:153], v[210:213], v[38:41]
	v_mfma_f32_16x16x32_bf16 v[34:37], v[186:189], v[210:213], v[34:37]
	v_mfma_f32_16x16x32_bf16 v[22:25], v[150:153], v[218:221], v[22:25]
	v_mfma_f32_16x16x32_bf16 v[18:21], v[186:189], v[218:221], v[18:21]
	v_mfma_f32_16x16x32_bf16 v[6:9], v[150:153], v[226:229], v[6:9]
	v_mfma_f32_16x16x32_bf16 v[2:5], v[186:189], v[226:229], v[2:5]
	s_barrier
	s_setprio 0
	s_add_u32 s46, s46, 0x100
	s_addc_u32 s47, s47, 0
	s_add_u32 s13, s13, 0x100
	s_addc_u32 s24, s24, 0
	s_cmp_ge_u32 s78, s65
	s_mov_b32 s72, s78
	s_cbranch_scc0 .LBB0_398

; #define PG8_STAGE(bufoff, gbase, voff) do { _Pragma("unroll") for (int _i = 0; _i < 2; ++_i) \
;         __builtin_amdgcn_global_load_lds((const unsigned*)((const char*)(gbase) + (voff)[_i]), (PG8_LAS unsigned*)(lds + (bufoff) + ldsw + _i * 8192), 16, 0, 0); } while (0)
; #define PG8_LDA(dst, b, h) do { _Pragma("unroll") for (int m = 0; m < 4; ++m) _Pragma("unroll") for (int k = 0; k < 2; ++k) dst[m][k] = *(const PG8_LAS bf16x8*)(lds + PG8_SA(b, h) + aoff + m * 2048 + k * 1024); } while (0)
; #define PG8_LDB(dst, b, h) do { _Pragma("unroll") for (int n = 0; n < 2; ++n) _Pragma("unroll") for (int k = 0; k < 2; ++k) dst[n][k] = *(const PG8_LAS bf16x8*)(lds + PG8_SB(b, h) + boff + n * 2048 + k * 1024); } while (0)
; #define PG8_WAIT_V(n) asm volatile("s_waitcnt vmcnt(" #n ")" ::: "memory")
; #define PG8_WAIT_L(n) asm volatile("s_waitcnt lgkmcnt(" #n ")" ::: "memory")
; #define PG8_BAR __builtin_amdgcn_s_barrier()
; #define PG8_SCHED __builtin_amdgcn_sched_barrier(0)
; template <class Epi, class Sched, bool ALIGN_EPI = false, bool SP2 = false, bool F16 = false>
; __device__ __forceinline__ void gemm_phase(PG8_LAS unsigned char* lds, const Gemm g, const Sched& S, const Epi& E) {
;     ...
;             const bool last = (t == nt - 2);
;             const char* a1 = cA + (size_t)(t + 1) * kstep;
;             const char* a2 = last ? nA : cA + (size_t)(t + 2) * kstep; const char* b2 = last ? nB : cB + (size_t)(t + 2) * kstep;
;             const char* a3 = a2 + kstep; const char* b3 = b2 + kstep;
;             if (last && has_next) S.a_ready(nxt);
;             if constexpr (SP2) {
;             PG8_LDB(B0, 0, 0); PG8_LDB(B1, 0, 1); PG8_SCHED; PG8_LDA(At, 0, 0); PG8_STAGE(PG8_SA(1, 1), a1 + hstepA, voffA);
;             PG8_WAIT_V(8); PG8_WAIT_L(0); PG8_BAR; PG8_MMA(0, 0, At, B0); PG8_MMA(0, 1, At, B1); PG8_BAR; PG8_SCHED;
;             PG8_LDA(At, 0, 1); PG8_STAGE(PG8_SB(0, 0), b2, voffB); PG8_STAGE(PG8_SB(0, 1), b2 + hstepB, voffB); PG8_STAGE(PG8_SA(0, 0), a2, voffA);
;             PG8_WAIT_V(8); PG8_WAIT_L(0); PG8_BAR; PG8_MMA(1, 0, At, B0); PG8_MMA(1, 1, At, B1); PG8_BAR; PG8_SCHED;
.Lpk_bh:
	s_add_i32 s73, s52, 2
	s_add_u32 s82, s44, 0x80
	s_addc_u32 s53, s45, 0
	s_add_i32 s94, 0, 0x10000
	s_cmp_eq_u32 s74, s52
	s_cselect_b32 s53, s79, s53
	s_cselect_b32 s52, s78, s82
	s_cselect_b32 s83, s55, s72
	s_cselect_b32 s82, s54, s24
	s_add_i32 s95, 0, 0x14000
	v_add_u32_e32 v142, s94, v163
	v_add_u32_e32 v172, s95, v163
	ds_read_b128 v[130:133], v142
	ds_read_b128 v[134:137], v142 offset:1024
	ds_read_b128 v[138:141], v142 offset:2048
	ds_read_b128 v[142:145], v142 offset:3072
	ds_read_b128 v[146:149], v172
	ds_read_b128 v[150:153], v172 offset:1024
	ds_read_b128 v[182:185], v172 offset:2048
	ds_read_b128 v[186:189], v172 offset:3072
	s_add_i32 m0, s35, 0xc000
	ds_read_b128 v[190:193], v204
	ds_read_b128 v[194:197], v204 offset:1024
	ds_read_b128 v[206:209], v204 offset:2048
	ds_read_b128 v[210:213], v204 offset:3072
	ds_read_b128 v[214:217], v204 offset:4096
	ds_read_b128 v[218:221], v204 offset:5120
	ds_read_b128 v[222:225], v204 offset:6144
	ds_read_b128 v[226:229], v204 offset:7168
	global_load_lds_dwordx4 v168, s[44:45]
	s_add_i32 m0, s35, 0xe000
	s_nop 0
	global_load_lds_dwordx4 v170, s[44:45]
	s_waitcnt vmcnt(8)
	s_waitcnt lgkmcnt(0)
	s_setprio 1
	s_barrier
	v_mfma_f32_16x16x32_f16 v[122:125], v[130:133], v[190:193], 0
	v_mfma_f32_16x16x32_f16 v[126:129], v[138:141], v[190:193], 0
	v_mfma_f32_16x16x32_f16 v[110:113], v[130:133], v[206:209], 0
	v_mfma_f32_16x16x32_f16 v[106:109], v[138:141], v[206:209], 0
	v_mfma_f32_16x16x32_f16 v[94:97], v[130:133], v[214:217], 0
	v_mfma_f32_16x16x32_f16 v[90:93], v[138:141], v[214:217], 0
	v_mfma_f32_16x16x32_f16 v[78:81], v[130:133], v[222:225], 0
	v_mfma_f32_16x16x32_f16 v[74:77], v[138:141], v[222:225], 0
	v_mfma_f32_16x16x32_f16 v[122:125], v[134:137], v[194:197], v[122:125]
	v_mfma_f32_16x16x32_f16 v[126:129], v[142:145], v[194:197], v[126:129]
	v_mfma_f32_16x16x32_f16 v[110:113], v[134:137], v[210:213], v[110:113]
	v_mfma_f32_16x16x32_f16 v[106:109], v[142:145], v[210:213], v[106:109]
	v_mfma_f32_16x16x32_f16 v[94:97], v[134:137], v[218:221], v[94:97]
	v_mfma_f32_16x16x32_f16 v[90:93], v[142:145], v[218:221], v[90:93]
	v_mfma_f32_16x16x32_f16 v[78:81], v[134:137], v[226:229], v[78:81]
	v_mfma_f32_16x16x32_f16 v[74:77], v[142:145], v[226:229], v[74:77]
	v_mfma_f32_16x16x32_f16 v[118:121], v[146:149], v[190:193], 0
	v_mfma_f32_16x16x32_f16 v[114:117], v[182:185], v[190:193], 0
	v_mfma_f32_16x16x32_f16 v[102:105], v[146:149], v[206:209], 0
	v_mfma_f32_16x16x32_f16 v[98:101], v[182:185], v[206:209], 0
	v_mfma_f32_16x16x32_f16 v[86:89], v[146:149], v[214:217], 0
	v_mfma_f32_16x16x32_f16 v[82:85], v[182:185], v[214:217], 0
	v_mfma_f32_16x16x32_f16 v[70:73], v[146:149], v[222:225], 0
	v_mfma_f32_16x16x32_f16 v[66:69], v[182:185], v[222:225], 0
	v_mfma_f32_16x16x32_f16 v[118:121], v[150:153], v[194:197], v[118:121]
	v_mfma_f32_16x16x32_f16 v[114:117], v[186:189], v[194:197], v[114:117]
	v_mfma_f32_16x16x32_f16 v[102:105], v[150:153], v[210:213], v[102:105]
	v_mfma_f32_16x16x32_f16 v[98:101], v[186:189], v[210:213], v[98:101]
	v_mfma_f32_16x16x32_f16 v[86:89], v[150:153], v[218:221], v[86:89]
	v_mfma_f32_16x16x32_f16 v[82:85], v[186:189], v[218:221], v[82:85]
	v_mfma_f32_16x16x32_f16 v[70:73], v[150:153], v[226:229], v[70:73]
	v_mfma_f32_16x16x32_f16 v[66:69], v[186:189], v[226:229], v[66:69]
	s_barrier
	s_setprio 0
	s_add_i32 s94, s94, s75
	v_lshl_add_u64 v[172:173], s[82:83], 0, v[156:157]
	s_mov_b32 m0, s94
	ds_read_b128 v[190:193], v204 offset:16384
	ds_read_b128 v[194:197], v204 offset:17408
	ds_read_b128 v[206:209], v204 offset:18432
	ds_read_b128 v[210:213], v204 offset:19456
	ds_read_b128 v[214:217], v204 offset:20480
	ds_read_b128 v[218:221], v204 offset:21504
	ds_read_b128 v[222:225], v204 offset:22528
	ds_read_b128 v[226:229], v204 offset:23552
	global_load_lds_dwordx4 v[172:173], off
	s_add_i32 m0, s94, 0x2000
	v_lshl_add_u64 v[176:177], s[82:83], 0, v[160:161]
	s_add_u32 s82, s82, s48
	s_addc_u32 s83, s83, 0
	s_add_i32 s94, s95, s75
	global_load_lds_dwordx4 v[176:177], off
	v_lshl_add_u64 v[230:231], s[82:83], 0, v[156:157]
	s_mov_b32 m0, s94
	v_lshl_add_u64 v[232:233], s[82:83], 0, v[160:161]
	global_load_lds_dwordx4 v[230:231], off
	s_add_i32 m0, s94, 0x2000
	v_lshl_add_u64 v[234:235], s[52:53], 0, v[154:155]
	global_load_lds_dwordx4 v[232:233], off
	s_mov_b32 m0, s35
	v_lshl_add_u64 v[236:237], s[52:53], 0, v[158:159]
	global_load_lds_dwordx4 v[234:235], off
	s_mov_b32 m0, s2
	s_nop 0
	global_load_lds_dwordx4 v[236:237], off
	s_waitcnt vmcnt(8)
	s_waitcnt lgkmcnt(0)
	s_setprio 1
	s_barrier
	v_mfma_f32_16x16x32_f16 v[62:65], v[130:133], v[190:193], 0
	v_mfma_f32_16x16x32_f16 v[58:61], v[138:141], v[190:193], 0
	v_mfma_f32_16x16x32_f16 v[46:49], v[130:133], v[206:209], 0
	v_mfma_f32_16x16x32_f16 v[42:45], v[138:141], v[206:209], 0
	v_mfma_f32_16x16x32_f16 v[30:33], v[130:133], v[214:217], 0
	v_mfma_f32_16x16x32_f16 v[26:29], v[138:141], v[214:217], 0
	v_mfma_f32_16x16x32_f16 v[14:17], v[130:133], v[222:225], 0
	v_mfma_f32_16x16x32_f16 v[10:13], v[138:141], v[222:225], 0
	v_mfma_f32_16x16x32_f16 v[62:65], v[134:137], v[194:197], v[62:65]
	v_mfma_f32_16x16x32_f16 v[58:61], v[142:145], v[194:197], v[58:61]
	v_mfma_f32_16x16x32_f16 v[46:49], v[134:137], v[210:213], v[46:49]
	v_mfma_f32_16x16x32_f16 v[42:45], v[142:145], v[210:213], v[42:45]
	v_mfma_f32_16x16x32_f16 v[30:33], v[134:137], v[218:221], v[30:33]
	v_mfma_f32_16x16x32_f16 v[26:29], v[142:145], v[218:221], v[26:29]
	v_mfma_f32_16x16x32_f16 v[14:17], v[134:137], v[226:229], v[14:17]
	v_mfma_f32_16x16x32_f16 v[10:13], v[142:145], v[226:229], v[10:13]
	v_mfma_f32_16x16x32_f16 v[54:57], v[146:149], v[190:193], 0
	v_mfma_f32_16x16x32_f16 v[50:53], v[182:185], v[190:193], 0
	v_mfma_f32_16x16x32_f16 v[38:41], v[146:149], v[206:209], 0
	v_mfma_f32_16x16x32_f16 v[34:37], v[182:185], v[206:209], 0
	v_mfma_f32_16x16x32_f16 v[22:25], v[146:149], v[214:217], 0
	v_mfma_f32_16x16x32_f16 v[18:21], v[182:185], v[214:217], 0
	v_mfma_f32_16x16x32_f16 v[6:9], v[146:149], v[222:225], 0
	v_mfma_f32_16x16x32_f16 v[2:5], v[182:185], v[222:225], 0
	v_mfma_f32_16x16x32_f16 v[54:57], v[150:153], v[194:197], v[54:57]
	v_mfma_f32_16x16x32_f16 v[50:53], v[186:189], v[194:197], v[50:53]
	v_mfma_f32_16x16x32_f16 v[38:41], v[150:153], v[210:213], v[38:41]
	v_mfma_f32_16x16x32_f16 v[34:37], v[186:189], v[210:213], v[34:37]
	v_mfma_f32_16x16x32_f16 v[22:25], v[150:153], v[218:221], v[22:25]
	v_mfma_f32_16x16x32_f16 v[18:21], v[186:189], v[218:221], v[18:21]
	v_mfma_f32_16x16x32_f16 v[6:9], v[150:153], v[226:229], v[6:9]
	v_mfma_f32_16x16x32_f16 v[2:5], v[186:189], v[226:229], v[2:5]
	s_barrier
; #define PG8_STAGE(bufoff, gbase, voff) do { _Pragma("unroll") for (int _i = 0; _i < 2; ++_i) \
;         __builtin_amdgcn_global_load_lds((const unsigned*)((const char*)(gbase) + (voff)[_i]), (PG8_LAS unsigned*)(lds + (bufoff) + ldsw + _i * 8192), 16, 0, 0); } while (0)
; #define PG8_LDA(dst, b, h) do { _Pragma("unroll") for (int m = 0; m < 4; ++m) _Pragma("unroll") for (int k = 0; k < 2; ++k) dst[m][k] = *(const PG8_LAS bf16x8*)(lds + PG8_SA(b, h) + aoff + m * 2048 + k * 1024); } while (0)
; #define PG8_LDB(dst, b, h) do { _Pragma("unroll") for (int n = 0; n < 2; ++n) _Pragma("unroll") for (int k = 0; k < 2; ++k) dst[n][k] = *(const PG8_LAS bf16x8*)(lds + PG8_SB(b, h) + boff + n * 2048 + k * 1024); } while (0)
; #define PG8_WAIT_V(n) asm volatile("s_waitcnt vmcnt(" #n ")" ::: "memory")
; #define PG8_WAIT_L(n) asm volatile("s_waitcnt lgkmcnt(" #n ")" ::: "memory")
; #define PG8_BAR __builtin_amdgcn_s_barrier()
; #define PG8_SCHED __builtin_amdgcn_sched_barrier(0)
; template <class Epi, class Sched, bool ALIGN_EPI = false, bool SP2 = false, bool F16 = false>
; __device__ __forceinline__ void gemm_phase(PG8_LAS unsigned char* lds, const Gemm g, const Sched& S, const Epi& E) {
;     ...
;             PG8_LDB(B0, 1, 0); PG8_LDB(B1, 1, 1); PG8_SCHED; PG8_LDA(At, 1, 0); PG8_STAGE(PG8_SA(0, 1), a2 + hstepA, voffA);
;             PG8_WAIT_V(8); PG8_WAIT_L(0); PG8_BAR; PG8_MMA(0, 0, At, B0); PG8_MMA(0, 1, At, B1); PG8_BAR; PG8_SCHED;
;             PG8_LDA(At, 1, 1); PG8_STAGE(PG8_SB(1, 0), b3, voffB); PG8_STAGE(PG8_SB(1, 1), b3 + hstepB, voffB); PG8_STAGE(PG8_SA(1, 0), a3, voffA);
;             PG8_WAIT_V(8); PG8_WAIT_L(0); PG8_BAR; PG8_MMA(1, 0, At, B0); PG8_MMA(1, 1, At, B1); PG8_BAR; PG8_SCHED;
	s_setprio 0
	s_add_i32 s82, 0, 0x18000
	s_add_i32 s83, 0, 0x1c000
	v_add_u32_e32 v142, s82, v163
	v_add_u32_e32 v174, s83, v163
	ds_read_b128 v[130:133], v142
	ds_read_b128 v[134:137], v142 offset:1024
	ds_read_b128 v[138:141], v142 offset:2048
	ds_read_b128 v[142:145], v142 offset:3072
	ds_read_b128 v[146:149], v174
	ds_read_b128 v[150:153], v174 offset:1024
	ds_read_b128 v[182:185], v174 offset:2048
	ds_read_b128 v[186:189], v174 offset:3072
	s_add_u32 s52, s52, s8
	s_addc_u32 s53, s53, 0
	s_mov_b32 m0, s22
	ds_read_b128 v[190:193], v204 offset:32768
	ds_read_b128 v[194:197], v204 offset:33792
	ds_read_b128 v[206:209], v204 offset:34816
	ds_read_b128 v[210:213], v204 offset:35840
	ds_read_b128 v[214:217], v204 offset:36864
	ds_read_b128 v[218:221], v204 offset:37888
	ds_read_b128 v[222:225], v204 offset:38912
	ds_read_b128 v[226:229], v204 offset:39936
	global_load_lds_dwordx4 v154, s[52:53]
	s_mov_b32 m0, s23
	s_nop 0
	global_load_lds_dwordx4 v158, s[52:53]
	s_waitcnt vmcnt(8)
	s_waitcnt lgkmcnt(0)
	s_setprio 1
	s_barrier
	v_mfma_f32_16x16x32_f16 v[122:125], v[130:133], v[190:193], v[122:125]
	v_mfma_f32_16x16x32_f16 v[126:129], v[138:141], v[190:193], v[126:129]
	v_mfma_f32_16x16x32_f16 v[110:113], v[130:133], v[206:209], v[110:113]
	v_mfma_f32_16x16x32_f16 v[106:109], v[138:141], v[206:209], v[106:109]
	v_mfma_f32_16x16x32_f16 v[94:97], v[130:133], v[214:217], v[94:97]
	v_mfma_f32_16x16x32_f16 v[90:93], v[138:141], v[214:217], v[90:93]
	v_mfma_f32_16x16x32_f16 v[78:81], v[130:133], v[222:225], v[78:81]
	v_mfma_f32_16x16x32_f16 v[74:77], v[138:141], v[222:225], v[74:77]
	v_mfma_f32_16x16x32_f16 v[122:125], v[134:137], v[194:197], v[122:125]
	v_mfma_f32_16x16x32_f16 v[126:129], v[142:145], v[194:197], v[126:129]
	v_mfma_f32_16x16x32_f16 v[110:113], v[134:137], v[210:213], v[110:113]
	v_mfma_f32_16x16x32_f16 v[106:109], v[142:145], v[210:213], v[106:109]
	v_mfma_f32_16x16x32_f16 v[94:97], v[134:137], v[218:221], v[94:97]
	v_mfma_f32_16x16x32_f16 v[90:93], v[142:145], v[218:221], v[90:93]
	v_mfma_f32_16x16x32_f16 v[78:81], v[134:137], v[226:229], v[78:81]
	v_mfma_f32_16x16x32_f16 v[74:77], v[142:145], v[226:229], v[74:77]
	v_mfma_f32_16x16x32_f16 v[118:121], v[146:149], v[190:193], v[118:121]
	v_mfma_f32_16x16x32_f16 v[114:117], v[182:185], v[190:193], v[114:117]
	v_mfma_f32_16x16x32_f16 v[102:105], v[146:149], v[206:209], v[102:105]
	v_mfma_f32_16x16x32_f16 v[98:101], v[182:185], v[206:209], v[98:101]
	v_mfma_f32_16x16x32_f16 v[86:89], v[146:149], v[214:217], v[86:89]
	v_mfma_f32_16x16x32_f16 v[82:85], v[182:185], v[214:217], v[82:85]
	v_mfma_f32_16x16x32_f16 v[70:73], v[146:149], v[222:225], v[70:73]
	v_mfma_f32_16x16x32_f16 v[66:69], v[182:185], v[222:225], v[66:69]
	v_mfma_f32_16x16x32_f16 v[118:121], v[150:153], v[194:197], v[118:121]
	v_mfma_f32_16x16x32_f16 v[114:117], v[186:189], v[194:197], v[114:117]
	v_mfma_f32_16x16x32_f16 v[102:105], v[150:153], v[210:213], v[102:105]
	v_mfma_f32_16x16x32_f16 v[98:101], v[186:189], v[210:213], v[98:101]
	v_mfma_f32_16x16x32_f16 v[86:89], v[150:153], v[218:221], v[86:89]
	v_mfma_f32_16x16x32_f16 v[82:85], v[186:189], v[218:221], v[82:85]
	v_mfma_f32_16x16x32_f16 v[70:73], v[150:153], v[226:229], v[70:73]
	v_mfma_f32_16x16x32_f16 v[66:69], v[186:189], v[226:229], v[66:69]
	s_barrier
	s_setprio 0
	s_add_i32 s52, s82, s75
	v_lshl_add_u64 v[172:173], v[172:173], 0, s[92:93]
	s_mov_b32 m0, s52
	ds_read_b128 v[190:193], v204 offset:49152
	ds_read_b128 v[194:197], v204 offset:50176
	ds_read_b128 v[206:209], v204 offset:51200
	ds_read_b128 v[210:213], v204 offset:52224
	ds_read_b128 v[214:217], v204 offset:53248
	ds_read_b128 v[218:221], v204 offset:54272
	ds_read_b128 v[222:225], v204 offset:55296
	ds_read_b128 v[226:229], v204 offset:56320
	global_load_lds_dwordx4 v[172:173], off
	v_lshl_add_u64 v[172:173], v[176:177], 0, s[92:93]
	s_add_i32 m0, s52, 0x2000
	s_add_i32 s52, s83, s75
	global_load_lds_dwordx4 v[172:173], off
	v_lshl_add_u64 v[172:173], v[230:231], 0, s[92:93]
	s_mov_b32 m0, s52
	s_nop 0
	global_load_lds_dwordx4 v[172:173], off
	v_lshl_add_u64 v[172:173], v[232:233], 0, s[92:93]
	s_add_i32 m0, s52, 0x2000
	s_nop 0
	global_load_lds_dwordx4 v[172:173], off
	v_lshl_add_u64 v[172:173], v[234:235], 0, s[92:93]
	s_mov_b32 m0, s61
	s_nop 0
	global_load_lds_dwordx4 v[172:173], off
	v_lshl_add_u64 v[172:173], v[236:237], 0, s[92:93]
	s_mov_b32 m0, s18
	s_nop 0
	global_load_lds_dwordx4 v[172:173], off
	s_waitcnt vmcnt(8)
	s_waitcnt lgkmcnt(0)
	s_setprio 1
	s_barrier
	v_mfma_f32_16x16x32_f16 v[62:65], v[130:133], v[190:193], v[62:65]
	v_mfma_f32_16x16x32_f16 v[58:61], v[138:141], v[190:193], v[58:61]
	v_mfma_f32_16x16x32_f16 v[46:49], v[130:133], v[206:209], v[46:49]
	v_mfma_f32_16x16x32_f16 v[42:45], v[138:141], v[206:209], v[42:45]
	v_mfma_f32_16x16x32_f16 v[30:33], v[130:133], v[214:217], v[30:33]
	v_mfma_f32_16x16x32_f16 v[26:29], v[138:141], v[214:217], v[26:29]
	v_mfma_f32_16x16x32_f16 v[14:17], v[130:133], v[222:225], v[14:17]
	v_mfma_f32_16x16x32_f16 v[10:13], v[138:141], v[222:225], v[10:13]
	v_mfma_f32_16x16x32_f16 v[62:65], v[134:137], v[194:197], v[62:65]
	v_mfma_f32_16x16x32_f16 v[58:61], v[142:145], v[194:197], v[58:61]
	v_mfma_f32_16x16x32_f16 v[46:49], v[134:137], v[210:213], v[46:49]
	v_mfma_f32_16x16x32_f16 v[42:45], v[142:145], v[210:213], v[42:45]
	v_mfma_f32_16x16x32_f16 v[30:33], v[134:137], v[218:221], v[30:33]
	v_mfma_f32_16x16x32_f16 v[26:29], v[142:145], v[218:221], v[26:29]
	v_mfma_f32_16x16x32_f16 v[14:17], v[134:137], v[226:229], v[14:17]
	v_mfma_f32_16x16x32_f16 v[10:13], v[142:145], v[226:229], v[10:13]
	v_mfma_f32_16x16x32_f16 v[54:57], v[146:149], v[190:193], v[54:57]
	v_mfma_f32_16x16x32_f16 v[50:53], v[182:185], v[190:193], v[50:53]
	v_mfma_f32_16x16x32_f16 v[38:41], v[146:149], v[206:209], v[38:41]
	v_mfma_f32_16x16x32_f16 v[34:37], v[182:185], v[206:209], v[34:37]
	v_mfma_f32_16x16x32_f16 v[22:25], v[146:149], v[214:217], v[22:25]
	v_mfma_f32_16x16x32_f16 v[18:21], v[182:185], v[214:217], v[18:21]
	v_mfma_f32_16x16x32_f16 v[6:9], v[146:149], v[222:225], v[6:9]
	v_mfma_f32_16x16x32_f16 v[2:5], v[182:185], v[222:225], v[2:5]
	v_mfma_f32_16x16x32_f16 v[54:57], v[150:153], v[194:197], v[54:57]
	v_mfma_f32_16x16x32_f16 v[50:53], v[186:189], v[194:197], v[50:53]
	v_mfma_f32_16x16x32_f16 v[38:41], v[150:153], v[210:213], v[38:41]
	v_mfma_f32_16x16x32_f16 v[34:37], v[186:189], v[210:213], v[34:37]
	v_mfma_f32_16x16x32_f16 v[22:25], v[150:153], v[218:221], v[22:25]
	v_mfma_f32_16x16x32_f16 v[18:21], v[186:189], v[218:221], v[18:21]
	v_mfma_f32_16x16x32_f16 v[6:9], v[150:153], v[226:229], v[6:9]
	v_mfma_f32_16x16x32_f16 v[2:5], v[186:189], v[226:229], v[2:5]
	s_barrier
	s_setprio 0
	s_add_u32 s44, s44, 0x100
	s_addc_u32 s45, s45, 0
	s_add_u32 s24, s24, 0x100
	s_addc_u32 s72, s72, 0
	s_cmp_ge_u32 s73, s65
	s_mov_b32 s52, s73
	s_cbranch_scc1 .LBB0_565
; #define PG8_STAGE(bufoff, gbase, voff) do { _Pragma("unroll") for (int _i = 0; _i < 2; ++_i) \
;         __builtin_amdgcn_global_load_lds((const unsigned*)((const char*)(gbase) + (voff)[_i]), (PG8_LAS unsigned*)(lds + (bufoff) + ldsw + _i * 8192), 16, 0, 0); } while (0)
; #define PG8_LDA(dst, b, h) do { _Pragma("unroll") for (int m = 0; m < 4; ++m) _Pragma("unroll") for (int k = 0; k < 2; ++k) dst[m][k] = *(const PG8_LAS bf16x8*)(lds + PG8_SA(b, h) + aoff + m * 2048 + k * 1024); } while (0)
; #define PG8_LDB(dst, b, h) do { _Pragma("unroll") for (int n = 0; n < 2; ++n) _Pragma("unroll") for (int k = 0; k < 2; ++k) dst[n][k] = *(const PG8_LAS bf16x8*)(lds + PG8_SB(b, h) + boff + n * 2048 + k * 1024); } while (0)
; #define PG8_WAIT_V(n) asm volatile("s_waitcnt vmcnt(" #n ")" ::: "memory")
; #define PG8_WAIT_L(n) asm volatile("s_waitcnt lgkmcnt(" #n ")" ::: "memory")
; #define PG8_BAR __builtin_amdgcn_s_barrier()
; #define PG8_SCHED __builtin_amdgcn_sched_barrier(0)
; template <class Epi, class Sched, bool ALIGN_EPI = false, bool SP2 = false, bool F16 = false>
; __device__ __forceinline__ void gemm_phase(PG8_LAS unsigned char* lds, const Gemm g, const Sched& S, const Epi& E) {
;     ...
;             const bool last = (t == nt - 2);
;             const char* a1 = cA + (size_t)(t + 1) * kstep;
;             const char* a2 = last ? nA : cA + (size_t)(t + 2) * kstep; const char* b2 = last ? nB : cB + (size_t)(t + 2) * kstep;
;             const char* a3 = a2 + kstep; const char* b3 = b2 + kstep;
;             if (last && has_next) S.a_ready(nxt);
;             if constexpr (SP2) {
;             PG8_LDB(B0, 0, 0); PG8_LDB(B1, 0, 1); PG8_SCHED; PG8_LDA(At, 0, 0); PG8_STAGE(PG8_SA(1, 1), a1 + hstepA, voffA);
;             PG8_WAIT_V(8); PG8_WAIT_L(0); PG8_BAR; PG8_MMA(0, 0, At, B0); PG8_MMA(0, 1, At, B1); PG8_BAR; PG8_SCHED;
;             PG8_LDA(At, 0, 1); PG8_STAGE(PG8_SB(0, 0), b2, voffB); PG8_STAGE(PG8_SB(0, 1), b2 + hstepB, voffB); PG8_STAGE(PG8_SA(0, 0), a2, voffA);
.LBB0_564:
	s_add_i32 s73, s52, 2
	s_add_u32 s82, s44, 0x80
	s_addc_u32 s53, s45, 0
	s_add_i32 s94, 0, 0x10000
	s_cmp_eq_u32 s74, s52
	s_cselect_b32 s53, s79, s53
	s_cselect_b32 s52, s78, s82
	s_cselect_b32 s83, s55, s72
	s_cselect_b32 s82, s54, s24
	s_add_i32 s95, 0, 0x14000
	v_add_u32_e32 v142, s94, v163
	v_add_u32_e32 v172, s95, v163
	ds_read_b128 v[130:133], v142
	ds_read_b128 v[134:137], v142 offset:1024
	ds_read_b128 v[138:141], v142 offset:2048
	ds_read_b128 v[142:145], v142 offset:3072
	ds_read_b128 v[146:149], v172
	ds_read_b128 v[150:153], v172 offset:1024
	ds_read_b128 v[182:185], v172 offset:2048
	ds_read_b128 v[186:189], v172 offset:3072
	s_add_i32 m0, s35, 0xc000
	ds_read_b128 v[190:193], v204
	ds_read_b128 v[194:197], v204 offset:1024
	ds_read_b128 v[206:209], v204 offset:2048
	ds_read_b128 v[210:213], v204 offset:3072
	ds_read_b128 v[214:217], v204 offset:4096
	ds_read_b128 v[218:221], v204 offset:5120
	ds_read_b128 v[222:225], v204 offset:6144
	ds_read_b128 v[226:229], v204 offset:7168
	global_load_lds_dwordx4 v168, s[44:45]
	s_add_i32 m0, s35, 0xe000
	s_nop 0
	global_load_lds_dwordx4 v170, s[44:45]
	s_waitcnt vmcnt(8)
	s_waitcnt lgkmcnt(0)
	s_setprio 1
	s_barrier
	v_mfma_f32_16x16x32_f16 v[122:125], v[130:133], v[190:193], v[122:125]
	v_mfma_f32_16x16x32_f16 v[126:129], v[138:141], v[190:193], v[126:129]
	v_mfma_f32_16x16x32_f16 v[110:113], v[130:133], v[206:209], v[110:113]
	v_mfma_f32_16x16x32_f16 v[106:109], v[138:141], v[206:209], v[106:109]
	v_mfma_f32_16x16x32_f16 v[94:97], v[130:133], v[214:217], v[94:97]
	v_mfma_f32_16x16x32_f16 v[90:93], v[138:141], v[214:217], v[90:93]
	v_mfma_f32_16x16x32_f16 v[78:81], v[130:133], v[222:225], v[78:81]
	v_mfma_f32_16x16x32_f16 v[74:77], v[138:141], v[222:225], v[74:77]
	v_mfma_f32_16x16x32_f16 v[122:125], v[134:137], v[194:197], v[122:125]
	v_mfma_f32_16x16x32_f16 v[126:129], v[142:145], v[194:197], v[126:129]
	v_mfma_f32_16x16x32_f16 v[110:113], v[134:137], v[210:213], v[110:113]
	v_mfma_f32_16x16x32_f16 v[106:109], v[142:145], v[210:213], v[106:109]
	v_mfma_f32_16x16x32_f16 v[94:97], v[134:137], v[218:221], v[94:97]
	v_mfma_f32_16x16x32_f16 v[90:93], v[142:145], v[218:221], v[90:93]
	v_mfma_f32_16x16x32_f16 v[78:81], v[134:137], v[226:229], v[78:81]
	v_mfma_f32_16x16x32_f16 v[74:77], v[142:145], v[226:229], v[74:77]
	v_mfma_f32_16x16x32_f16 v[118:121], v[146:149], v[190:193], v[118:121]
	v_mfma_f32_16x16x32_f16 v[114:117], v[182:185], v[190:193], v[114:117]
	v_mfma_f32_16x16x32_f16 v[102:105], v[146:149], v[206:209], v[102:105]
	v_mfma_f32_16x16x32_f16 v[98:101], v[182:185], v[206:209], v[98:101]
	v_mfma_f32_16x16x32_f16 v[86:89], v[146:149], v[214:217], v[86:89]
	v_mfma_f32_16x16x32_f16 v[82:85], v[182:185], v[214:217], v[82:85]
	v_mfma_f32_16x16x32_f16 v[70:73], v[146:149], v[222:225], v[70:73]
	v_mfma_f32_16x16x32_f16 v[66:69], v[182:185], v[222:225], v[66:69]
	v_mfma_f32_16x16x32_f16 v[118:121], v[150:153], v[194:197], v[118:121]
	v_mfma_f32_16x16x32_f16 v[114:117], v[186:189], v[194:197], v[114:117]
	v_mfma_f32_16x16x32_f16 v[102:105], v[150:153], v[210:213], v[102:105]
	v_mfma_f32_16x16x32_f16 v[98:101], v[186:189], v[210:213], v[98:101]
	v_mfma_f32_16x16x32_f16 v[86:89], v[150:153], v[218:221], v[86:89]
	v_mfma_f32_16x16x32_f16 v[82:85], v[186:189], v[218:221], v[82:85]
	v_mfma_f32_16x16x32_f16 v[70:73], v[150:153], v[226:229], v[70:73]
	v_mfma_f32_16x16x32_f16 v[66:69], v[186:189], v[226:229], v[66:69]
	s_barrier
	s_setprio 0
	s_add_i32 s94, s94, s75
	v_lshl_add_u64 v[172:173], s[82:83], 0, v[156:157]
	s_mov_b32 m0, s94
	ds_read_b128 v[190:193], v204 offset:16384
	ds_read_b128 v[194:197], v204 offset:17408
	ds_read_b128 v[206:209], v204 offset:18432
	ds_read_b128 v[210:213], v204 offset:19456
	ds_read_b128 v[214:217], v204 offset:20480
	ds_read_b128 v[218:221], v204 offset:21504
	ds_read_b128 v[222:225], v204 offset:22528
	ds_read_b128 v[226:229], v204 offset:23552
	global_load_lds_dwordx4 v[172:173], off
	s_add_i32 m0, s94, 0x2000
	v_lshl_add_u64 v[176:177], s[82:83], 0, v[160:161]
	s_add_u32 s82, s82, s48
	s_addc_u32 s83, s83, 0
	s_add_i32 s94, s95, s75
	global_load_lds_dwordx4 v[176:177], off
	v_lshl_add_u64 v[230:231], s[82:83], 0, v[156:157]
	s_mov_b32 m0, s94
	v_lshl_add_u64 v[232:233], s[82:83], 0, v[160:161]
	global_load_lds_dwordx4 v[230:231], off
	s_add_i32 m0, s94, 0x2000
	v_lshl_add_u64 v[234:235], s[52:53], 0, v[154:155]
	global_load_lds_dwordx4 v[232:233], off
	s_mov_b32 m0, s35
	v_lshl_add_u64 v[236:237], s[52:53], 0, v[158:159]
	global_load_lds_dwordx4 v[234:235], off
	s_mov_b32 m0, s2
	s_nop 0
	global_load_lds_dwordx4 v[236:237], off
	s_waitcnt vmcnt(8)
	s_waitcnt lgkmcnt(0)
	s_setprio 1
	s_barrier
; #define PG8_STAGE(bufoff, gbase, voff) do { _Pragma("unroll") for (int _i = 0; _i < 2; ++_i) \
;         __builtin_amdgcn_global_load_lds((const unsigned*)((const char*)(gbase) + (voff)[_i]), (PG8_LAS unsigned*)(lds + (bufoff) + ldsw + _i * 8192), 16, 0, 0); } while (0)
; #define PG8_LDA(dst, b, h) do { _Pragma("unroll") for (int m = 0; m < 4; ++m) _Pragma("unroll") for (int k = 0; k < 2; ++k) dst[m][k] = *(const PG8_LAS bf16x8*)(lds + PG8_SA(b, h) + aoff + m * 2048 + k * 1024); } while (0)
; #define PG8_LDB(dst, b, h) do { _Pragma("unroll") for (int n = 0; n < 2; ++n) _Pragma("unroll") for (int k = 0; k < 2; ++k) dst[n][k] = *(const PG8_LAS bf16x8*)(lds + PG8_SB(b, h) + boff + n * 2048 + k * 1024); } while (0)
; #define PG8_WAIT_V(n) asm volatile("s_waitcnt vmcnt(" #n ")" ::: "memory")
; #define PG8_WAIT_L(n) asm volatile("s_waitcnt lgkmcnt(" #n ")" ::: "memory")
; #define PG8_BAR __builtin_amdgcn_s_barrier()
; #define PG8_SCHED __builtin_amdgcn_sched_barrier(0)
; template <class Epi, class Sched, bool ALIGN_EPI = false, bool SP2 = false, bool F16 = false>
; __device__ __forceinline__ void gemm_phase(PG8_LAS unsigned char* lds, const Gemm g, const Sched& S, const Epi& E) {
;     ...
;             PG8_WAIT_V(8); PG8_WAIT_L(0); PG8_BAR; PG8_MMA(1, 0, At, B0); PG8_MMA(1, 1, At, B1); PG8_BAR; PG8_SCHED;
;             PG8_LDB(B0, 1, 0); PG8_LDB(B1, 1, 1); PG8_SCHED; PG8_LDA(At, 1, 0); PG8_STAGE(PG8_SA(0, 1), a2 + hstepA, voffA);
;             PG8_WAIT_V(8); PG8_WAIT_L(0); PG8_BAR; PG8_MMA(0, 0, At, B0); PG8_MMA(0, 1, At, B1); PG8_BAR; PG8_SCHED;
	v_mfma_f32_16x16x32_f16 v[62:65], v[130:133], v[190:193], v[62:65]
	v_mfma_f32_16x16x32_f16 v[58:61], v[138:141], v[190:193], v[58:61]
	v_mfma_f32_16x16x32_f16 v[46:49], v[130:133], v[206:209], v[46:49]
	v_mfma_f32_16x16x32_f16 v[42:45], v[138:141], v[206:209], v[42:45]
	v_mfma_f32_16x16x32_f16 v[30:33], v[130:133], v[214:217], v[30:33]
	v_mfma_f32_16x16x32_f16 v[26:29], v[138:141], v[214:217], v[26:29]
	v_mfma_f32_16x16x32_f16 v[14:17], v[130:133], v[222:225], v[14:17]
	v_mfma_f32_16x16x32_f16 v[10:13], v[138:141], v[222:225], v[10:13]
	v_mfma_f32_16x16x32_f16 v[62:65], v[134:137], v[194:197], v[62:65]
	v_mfma_f32_16x16x32_f16 v[58:61], v[142:145], v[194:197], v[58:61]
	v_mfma_f32_16x16x32_f16 v[46:49], v[134:137], v[210:213], v[46:49]
	v_mfma_f32_16x16x32_f16 v[42:45], v[142:145], v[210:213], v[42:45]
	v_mfma_f32_16x16x32_f16 v[30:33], v[134:137], v[218:221], v[30:33]
	v_mfma_f32_16x16x32_f16 v[26:29], v[142:145], v[218:221], v[26:29]
	v_mfma_f32_16x16x32_f16 v[14:17], v[134:137], v[226:229], v[14:17]
	v_mfma_f32_16x16x32_f16 v[10:13], v[142:145], v[226:229], v[10:13]
	v_mfma_f32_16x16x32_f16 v[54:57], v[146:149], v[190:193], v[54:57]
	v_mfma_f32_16x16x32_f16 v[50:53], v[182:185], v[190:193], v[50:53]
	v_mfma_f32_16x16x32_f16 v[38:41], v[146:149], v[206:209], v[38:41]
	v_mfma_f32_16x16x32_f16 v[34:37], v[182:185], v[206:209], v[34:37]
	v_mfma_f32_16x16x32_f16 v[22:25], v[146:149], v[214:217], v[22:25]
	v_mfma_f32_16x16x32_f16 v[18:21], v[182:185], v[214:217], v[18:21]
	v_mfma_f32_16x16x32_f16 v[6:9], v[146:149], v[222:225], v[6:9]
	v_mfma_f32_16x16x32_f16 v[2:5], v[182:185], v[222:225], v[2:5]
	v_mfma_f32_16x16x32_f16 v[54:57], v[150:153], v[194:197], v[54:57]
	v_mfma_f32_16x16x32_f16 v[50:53], v[186:189], v[194:197], v[50:53]
	v_mfma_f32_16x16x32_f16 v[38:41], v[150:153], v[210:213], v[38:41]
	v_mfma_f32_16x16x32_f16 v[34:37], v[186:189], v[210:213], v[34:37]
	v_mfma_f32_16x16x32_f16 v[22:25], v[150:153], v[218:221], v[22:25]
	v_mfma_f32_16x16x32_f16 v[18:21], v[186:189], v[218:221], v[18:21]
	v_mfma_f32_16x16x32_f16 v[6:9], v[150:153], v[226:229], v[6:9]
	v_mfma_f32_16x16x32_f16 v[2:5], v[186:189], v[226:229], v[2:5]
	s_barrier
	s_setprio 0
	s_add_i32 s82, 0, 0x18000
	s_add_i32 s83, 0, 0x1c000
	v_add_u32_e32 v142, s82, v163
	v_add_u32_e32 v174, s83, v163
	ds_read_b128 v[130:133], v142
	ds_read_b128 v[134:137], v142 offset:1024
	ds_read_b128 v[138:141], v142 offset:2048
	ds_read_b128 v[142:145], v142 offset:3072
	ds_read_b128 v[146:149], v174
	ds_read_b128 v[150:153], v174 offset:1024
	ds_read_b128 v[182:185], v174 offset:2048
	ds_read_b128 v[186:189], v174 offset:3072
	s_add_u32 s52, s52, s8
	s_addc_u32 s53, s53, 0
	s_mov_b32 m0, s22
	ds_read_b128 v[190:193], v204 offset:32768
	ds_read_b128 v[194:197], v204 offset:33792
	ds_read_b128 v[206:209], v204 offset:34816
	ds_read_b128 v[210:213], v204 offset:35840
	ds_read_b128 v[214:217], v204 offset:36864
	ds_read_b128 v[218:221], v204 offset:37888
	ds_read_b128 v[222:225], v204 offset:38912
	ds_read_b128 v[226:229], v204 offset:39936
	global_load_lds_dwordx4 v154, s[52:53]
	s_mov_b32 m0, s23
	s_nop 0
	global_load_lds_dwordx4 v158, s[52:53]
	s_waitcnt vmcnt(8)
	s_waitcnt lgkmcnt(0)
	s_setprio 1
	s_barrier
	v_mfma_f32_16x16x32_f16 v[122:125], v[130:133], v[190:193], v[122:125]
	v_mfma_f32_16x16x32_f16 v[126:129], v[138:141], v[190:193], v[126:129]
	v_mfma_f32_16x16x32_f16 v[110:113], v[130:133], v[206:209], v[110:113]
	v_mfma_f32_16x16x32_f16 v[106:109], v[138:141], v[206:209], v[106:109]
	v_mfma_f32_16x16x32_f16 v[94:97], v[130:133], v[214:217], v[94:97]
	v_mfma_f32_16x16x32_f16 v[90:93], v[138:141], v[214:217], v[90:93]
	v_mfma_f32_16x16x32_f16 v[78:81], v[130:133], v[222:225], v[78:81]
	v_mfma_f32_16x16x32_f16 v[74:77], v[138:141], v[222:225], v[74:77]
	v_mfma_f32_16x16x32_f16 v[122:125], v[134:137], v[194:197], v[122:125]
	v_mfma_f32_16x16x32_f16 v[126:129], v[142:145], v[194:197], v[126:129]
	v_mfma_f32_16x16x32_f16 v[110:113], v[134:137], v[210:213], v[110:113]
	v_mfma_f32_16x16x32_f16 v[106:109], v[142:145], v[210:213], v[106:109]
	v_mfma_f32_16x16x32_f16 v[94:97], v[134:137], v[218:221], v[94:97]
	v_mfma_f32_16x16x32_f16 v[90:93], v[142:145], v[218:221], v[90:93]
	v_mfma_f32_16x16x32_f16 v[78:81], v[134:137], v[226:229], v[78:81]
	v_mfma_f32_16x16x32_f16 v[74:77], v[142:145], v[226:229], v[74:77]
	v_mfma_f32_16x16x32_f16 v[118:121], v[146:149], v[190:193], v[118:121]
	v_mfma_f32_16x16x32_f16 v[114:117], v[182:185], v[190:193], v[114:117]
	v_mfma_f32_16x16x32_f16 v[102:105], v[146:149], v[206:209], v[102:105]
	v_mfma_f32_16x16x32_f16 v[98:101], v[182:185], v[206:209], v[98:101]
	v_mfma_f32_16x16x32_f16 v[86:89], v[146:149], v[214:217], v[86:89]
	v_mfma_f32_16x16x32_f16 v[82:85], v[182:185], v[214:217], v[82:85]
	v_mfma_f32_16x16x32_f16 v[70:73], v[146:149], v[222:225], v[70:73]
	v_mfma_f32_16x16x32_f16 v[66:69], v[182:185], v[222:225], v[66:69]
	v_mfma_f32_16x16x32_f16 v[118:121], v[150:153], v[194:197], v[118:121]
	v_mfma_f32_16x16x32_f16 v[114:117], v[186:189], v[194:197], v[114:117]
	v_mfma_f32_16x16x32_f16 v[102:105], v[150:153], v[210:213], v[102:105]
	v_mfma_f32_16x16x32_f16 v[98:101], v[186:189], v[210:213], v[98:101]
	v_mfma_f32_16x16x32_f16 v[86:89], v[150:153], v[218:221], v[86:89]
	v_mfma_f32_16x16x32_f16 v[82:85], v[186:189], v[218:221], v[82:85]
	v_mfma_f32_16x16x32_f16 v[70:73], v[150:153], v[226:229], v[70:73]
	v_mfma_f32_16x16x32_f16 v[66:69], v[186:189], v[226:229], v[66:69]
	s_barrier
; #define PG8_STAGE(bufoff, gbase, voff) do { _Pragma("unroll") for (int _i = 0; _i < 2; ++_i) \
;         __builtin_amdgcn_global_load_lds((const unsigned*)((const char*)(gbase) + (voff)[_i]), (PG8_LAS unsigned*)(lds + (bufoff) + ldsw + _i * 8192), 16, 0, 0); } while (0)
; #define PG8_LDA(dst, b, h) do { _Pragma("unroll") for (int m = 0; m < 4; ++m) _Pragma("unroll") for (int k = 0; k < 2; ++k) dst[m][k] = *(const PG8_LAS bf16x8*)(lds + PG8_SA(b, h) + aoff + m * 2048 + k * 1024); } while (0)
; #define PG8_WAIT_V(n) asm volatile("s_waitcnt vmcnt(" #n ")" ::: "memory")
; #define PG8_WAIT_L(n) asm volatile("s_waitcnt lgkmcnt(" #n ")" ::: "memory")
; #define PG8_BAR __builtin_amdgcn_s_barrier()
; #define PG8_SCHED __builtin_amdgcn_sched_barrier(0)
; template <class Epi, class Sched, bool ALIGN_EPI = false, bool SP2 = false, bool F16 = false>
; __device__ __forceinline__ void gemm_phase(PG8_LAS unsigned char* lds, const Gemm g, const Sched& S, const Epi& E) {
;     ...
;         for (int t = 0; t < nt; t += 2) {
;     ...
;             PG8_LDA(At, 1, 1); PG8_STAGE(PG8_SB(1, 0), b3, voffB); PG8_STAGE(PG8_SB(1, 1), b3 + hstepB, voffB); PG8_STAGE(PG8_SA(1, 0), a3, voffA);
;             PG8_WAIT_V(8); PG8_WAIT_L(0); PG8_BAR; PG8_MMA(1, 0, At, B0); PG8_MMA(1, 1, At, B1); PG8_BAR; PG8_SCHED;
	s_setprio 0
	s_add_i32 s52, s82, s75
	v_lshl_add_u64 v[172:173], v[172:173], 0, s[92:93]
	s_mov_b32 m0, s52
	ds_read_b128 v[190:193], v204 offset:49152
	ds_read_b128 v[194:197], v204 offset:50176
	ds_read_b128 v[206:209], v204 offset:51200
	ds_read_b128 v[210:213], v204 offset:52224
	ds_read_b128 v[214:217], v204 offset:53248
	ds_read_b128 v[218:221], v204 offset:54272
	ds_read_b128 v[222:225], v204 offset:55296
	ds_read_b128 v[226:229], v204 offset:56320
	global_load_lds_dwordx4 v[172:173], off
	v_lshl_add_u64 v[172:173], v[176:177], 0, s[92:93]
	s_add_i32 m0, s52, 0x2000
	s_add_i32 s52, s83, s75
	global_load_lds_dwordx4 v[172:173], off
	v_lshl_add_u64 v[172:173], v[230:231], 0, s[92:93]
	s_mov_b32 m0, s52
	s_nop 0
	global_load_lds_dwordx4 v[172:173], off
	v_lshl_add_u64 v[172:173], v[232:233], 0, s[92:93]
	s_add_i32 m0, s52, 0x2000
	s_nop 0
	global_load_lds_dwordx4 v[172:173], off
	v_lshl_add_u64 v[172:173], v[234:235], 0, s[92:93]
	s_mov_b32 m0, s61
	s_nop 0
	global_load_lds_dwordx4 v[172:173], off
	v_lshl_add_u64 v[172:173], v[236:237], 0, s[92:93]
	s_mov_b32 m0, s18
	s_nop 0
	global_load_lds_dwordx4 v[172:173], off
	s_waitcnt vmcnt(8)
	s_waitcnt lgkmcnt(0)
	s_setprio 1
	s_barrier
	v_mfma_f32_16x16x32_f16 v[62:65], v[130:133], v[190:193], v[62:65]
	v_mfma_f32_16x16x32_f16 v[58:61], v[138:141], v[190:193], v[58:61]
	v_mfma_f32_16x16x32_f16 v[46:49], v[130:133], v[206:209], v[46:49]
	v_mfma_f32_16x16x32_f16 v[42:45], v[138:141], v[206:209], v[42:45]
	v_mfma_f32_16x16x32_f16 v[30:33], v[130:133], v[214:217], v[30:33]
	v_mfma_f32_16x16x32_f16 v[26:29], v[138:141], v[214:217], v[26:29]
	v_mfma_f32_16x16x32_f16 v[14:17], v[130:133], v[222:225], v[14:17]
	v_mfma_f32_16x16x32_f16 v[10:13], v[138:141], v[222:225], v[10:13]
	v_mfma_f32_16x16x32_f16 v[62:65], v[134:137], v[194:197], v[62:65]
	v_mfma_f32_16x16x32_f16 v[58:61], v[142:145], v[194:197], v[58:61]
	v_mfma_f32_16x16x32_f16 v[46:49], v[134:137], v[210:213], v[46:49]
	v_mfma_f32_16x16x32_f16 v[42:45], v[142:145], v[210:213], v[42:45]
	v_mfma_f32_16x16x32_f16 v[30:33], v[134:137], v[218:221], v[30:33]
	v_mfma_f32_16x16x32_f16 v[26:29], v[142:145], v[218:221], v[26:29]
	v_mfma_f32_16x16x32_f16 v[14:17], v[134:137], v[226:229], v[14:17]
	v_mfma_f32_16x16x32_f16 v[10:13], v[142:145], v[226:229], v[10:13]
	v_mfma_f32_16x16x32_f16 v[54:57], v[146:149], v[190:193], v[54:57]
	v_mfma_f32_16x16x32_f16 v[50:53], v[182:185], v[190:193], v[50:53]
	v_mfma_f32_16x16x32_f16 v[38:41], v[146:149], v[206:209], v[38:41]
	v_mfma_f32_16x16x32_f16 v[34:37], v[182:185], v[206:209], v[34:37]
	v_mfma_f32_16x16x32_f16 v[22:25], v[146:149], v[214:217], v[22:25]
	v_mfma_f32_16x16x32_f16 v[18:21], v[182:185], v[214:217], v[18:21]
	v_mfma_f32_16x16x32_f16 v[6:9], v[146:149], v[222:225], v[6:9]
	v_mfma_f32_16x16x32_f16 v[2:5], v[182:185], v[222:225], v[2:5]
	v_mfma_f32_16x16x32_f16 v[54:57], v[150:153], v[194:197], v[54:57]
	v_mfma_f32_16x16x32_f16 v[50:53], v[186:189], v[194:197], v[50:53]
	v_mfma_f32_16x16x32_f16 v[38:41], v[150:153], v[210:213], v[38:41]
	v_mfma_f32_16x16x32_f16 v[34:37], v[186:189], v[210:213], v[34:37]
	v_mfma_f32_16x16x32_f16 v[22:25], v[150:153], v[218:221], v[22:25]
	v_mfma_f32_16x16x32_f16 v[18:21], v[186:189], v[218:221], v[18:21]
	v_mfma_f32_16x16x32_f16 v[6:9], v[150:153], v[226:229], v[6:9]
	v_mfma_f32_16x16x32_f16 v[2:5], v[186:189], v[226:229], v[2:5]
	s_barrier
	s_setprio 0
	s_add_u32 s44, s44, 0x100
	s_addc_u32 s45, s45, 0
	s_add_u32 s24, s24, 0x100
	s_addc_u32 s72, s72, 0
	s_cmp_ge_u32 s73, s65
	s_mov_b32 s52, s73
	s_cbranch_scc0 .LBB0_564
